# GEMM phases: per-segment s_setprio toggles removed, static priority 1 for waves 4..7
# speedup vs baseline: 1.0032x; 1.0032x over previous
; #define GRID_SYNC() do { if (pc >= ph_lo && pc + 1 < ph_hi) { GAS unsigned char* w_ = (GAS unsigned char*)P.ws; OPQ64(w_); XcdBarrier xb_; xb_.bar = (unsigned*)(w_ + WS_BAR); xb_.x = xb_xcc_id(); xb_.st = (volatile LAS unsigned*)(lds + LDS_BYTES - 16); xcd_barrier(xb_); } ++pc; } while (0)
; __global__ void __launch_bounds__(NTHREADS, 2) hybrid_fwd(Params P) {
;     ...
;     GRID_SYNC();
; #pragma unroll 1
;     for (int l = 0; l < 4; ++l) {
;         const int li = l >> 1;
;         if ((l & 1) == 0) {
.LBB0_180:
	s_or_b64 exec, exec, s[0:1]
	s_waitcnt lgkmcnt(0)
	s_barrier
	v_readfirstlane_b32 vcc_lo, v139
	s_cmpk_lt_u32 vcc_lo, 0x100
	s_cbranch_scc1 .Lprio_0
	s_setprio 1
.Lprio_0:
.LBB0_181:
	s_lshr_b32 s0, s88, 31
	s_add_i32 s0, s88, s0
	s_ashr_i32 s82, s0, 1
	s_sub_i32 s4, s88, s82
	s_ashr_i32 s3, s88, 31
	s_ashr_i32 s5, s4, 31
	s_and_b32 s0, s88, -2
	v_writelane_b32 v254, s94, 0
	s_cmpk_eq_i32 s0, 0x100
	s_cselect_b64 s[0:1], -1, 0
	v_writelane_b32 v254, s95, 1
	v_writelane_b32 v254, s0, 2
	s_cmpk_eq_i32 s88, 0x100
	v_mov_b32_e32 v1, 0
	v_writelane_b32 v254, s1, 3
	s_cselect_b64 s[0:1], -1, 0
	v_writelane_b32 v254, s0, 4
	s_cmpk_lg_i32 s88, 0x100
	s_movk_i32 s58, 0x6000
	v_writelane_b32 v254, s1, 5
	s_cselect_b64 s[0:1], -1, 0
	s_abs_i32 s87, s88
	v_cvt_f32_u32_e32 v0, s87
	v_writelane_b32 v254, s0, 6
	s_lshl_b32 s6, s88, 9
	s_mov_b32 s59, 0x800000
	v_rcp_iflag_f32_e32 v0, v0
	v_writelane_b32 v254, s1, 7
	s_mul_i32 s0, s89, s88
	s_mul_i32 s0, s0, s33
	v_mul_f32_e32 v0, 0x4f7ffffe, v0
	v_cvt_u32_f32_e32 v0, v0
	v_writelane_b32 v254, s0, 8
	s_mov_b32 s0, 1
	v_writelane_b32 v254, s0, 9
	s_add_i32 s0, s88, 0xffffffbe
	v_writelane_b32 v254, s0, 10
	s_sub_i32 s0, 0, s87
	v_readfirstlane_b32 s1, v0
	s_mul_i32 s0, s0, s1
	s_mul_hi_u32 s0, s1, s0
	s_add_i32 s0, s1, s0
	v_writelane_b32 v254, s0, 11
	s_mul_hi_u32 s0, s0, 0x2b5
	s_mul_i32 s0, s0, s87
	s_sub_i32 s0, 0x2b5, s0
	s_sub_i32 s1, s0, s87
	s_cmp_ge_u32 s0, s87
	s_cselect_b32 s0, s1, s0
	s_sub_i32 s1, s0, s87
	s_cmp_ge_u32 s0, s87
	s_cselect_b32 s0, s1, s0
	v_writelane_b32 v254, s0, 12
	s_lshl_b32 s0, s88, 5
	v_writelane_b32 v254, s0, 13
	s_lshl_b32 s0, s88, 14
	v_writelane_b32 v254, s0, 14
	s_lshl_b32 s0, s88, 4
	v_writelane_b32 v254, s0, 15
	s_ashr_i32 s7, s6, 31
	v_writelane_b32 v254, s6, 16
	s_lshl_b32 s0, s88, 12
	s_movk_i32 s33, 0x2000
	v_writelane_b32 v254, s7, 17
	v_writelane_b32 v254, s0, 18
	s_sub_i32 s0, 0, s82
	v_writelane_b32 v254, s0, 19
	s_lshl_b32 s0, s88, 10
	v_writelane_b32 v254, s0, 20
	s_add_i32 s0, 0, 0x23ff0
	v_writelane_b32 v254, s0, 21
	s_add_i32 s0, 0, 0x23ff4
	v_writelane_b32 v254, s0, 22
	s_add_i32 s0, 0, 0x10800
	v_writelane_b32 v254, s0, 23
	s_add_i32 s0, 0, 0x15000
	v_writelane_b32 v254, s0, 24
	s_add_i32 s0, 0, 0x19800
	v_writelane_b32 v254, s0, 25
	v_cmp_eq_u32_e64 s[0:1], 0, v139
	v_mbcnt_lo_u32_b32 v0, -1, 0
	s_movk_i32 s89, 0x4000
	v_writelane_b32 v254, s0, 26
	v_mov_b32_e32 v210, 0x1000
	v_mov_b32_e32 v211, 0x2000
	v_writelane_b32 v254, s1, 27
	v_writelane_b32 v254, s4, 28
	s_lshl_b64 s[0:1], s[4:5], 19
	v_mov_b32_e32 v212, 0x2a2ab000
	v_writelane_b32 v254, s5, 29
	v_writelane_b32 v254, s0, 30
	s_mov_b64 s[4:5], 0
	v_mov_b32_e32 v213, 1
	v_writelane_b32 v254, s1, 31
	s_lshl_b64 s[0:1], s[6:7], 5
	v_writelane_b32 v254, s0, 32
	v_mov_b32_e32 v214, 0x3ecc95a3
	s_movk_i32 s60, 0x1000
	v_writelane_b32 v254, s1, 33
	s_mov_b64 s[0:1], 64
	v_writelane_b32 v254, s0, 34
	s_movk_i32 s61, 0x3000
	s_movk_i32 s64, 0x5000
	v_writelane_b32 v254, s1, 35
	s_mov_b64 s[0:1], 0
	v_writelane_b32 v254, s0, 36
	s_movk_i32 s65, 0x7000
	s_mov_b32 s66, 0x5040100
	v_writelane_b32 v254, s1, 37
	v_writelane_b32 v254, s4, 38
	v_mov_b32_e32 v138, 0x358637bd
	s_movk_i32 s67, 0x2a00
	v_writelane_b32 v254, s5, 39
	s_load_dwordx4 s[4:7], s[96:97], 0xc8
	v_mbcnt_hi_u32_b32 v215, -1, v0
	v_mov_b32_e32 v216, 0x42800000
	v_mov_b32_e32 v217, 0x7fc00000
	v_mov_b32_e32 v218, 0xff800000
	s_waitcnt lgkmcnt(0)
	v_writelane_b32 v254, s4, 40
	v_mov_b32_e32 v219, 0x7f800000
	v_mov_b64_e32 v[140:141], 0x100
	v_writelane_b32 v254, s5, 41
	v_writelane_b32 v254, s6, 42
	v_writelane_b32 v254, s7, 43
	v_writelane_b32 v254, s92, 44
	v_mov_b64_e32 v[142:143], 0xff
	v_mov_b32_e32 v220, 0x80
	v_writelane_b32 v254, s93, 45
	v_writelane_b32 v254, s96, 46
	v_mov_b32_e32 v144, 0x3e000000
	v_mov_b32_e32 v221, 0xf149f2ca
	v_writelane_b32 v254, s97, 47
	v_writelane_b32 v254, s90, 48
	v_mov_b32_e32 v222, 0x70
	v_mov_b32_e32 v223, 0x60
	v_mov_b32_e32 v224, 0x50
	s_mov_b32 s81, 0
	s_mov_b64 s[0:1], 0x80
	s_mov_b32 s2, 0x3a000000
	s_mov_b64 s[94:95], 0x8000
	s_mov_b32 s86, 0x3db504f3
	v_writelane_b32 v254, s82, 49
	s_branch .LBB0_185

; #define GRID_SYNC() do { if (pc >= ph_lo && pc + 1 < ph_hi) { GAS unsigned char* w_ = (GAS unsigned char*)P.ws; OPQ64(w_); XcdBarrier xb_; xb_.bar = (unsigned*)(w_ + WS_BAR); xb_.x = xb_xcc_id(); xb_.st = (volatile LAS unsigned*)(lds + LDS_BYTES - 16); xcd_barrier(xb_); } ++pc; } while (0)
; __global__ void __launch_bounds__(NTHREADS, 2) hybrid_fwd(Params P) {
;     ...
;     for (int l = 0; l < 4; ++l) {
;     ...
;         GRID_SYNC();
;     }
.LBB0_183:
	s_or_b64 exec, exec, s[6:7]
	s_waitcnt lgkmcnt(0)
	s_barrier
	v_readfirstlane_b32 vcc_lo, v139
	s_cmpk_lt_u32 vcc_lo, 0x100
	s_cbranch_scc1 .Lprio_1
	s_setprio 1
.Lprio_1:
.LBB0_184:
	v_readlane_b32 s8, v254, 38
	v_readlane_b32 s9, v254, 39
	s_add_u32 s8, s8, 1
	s_addc_u32 s9, s9, 0
	v_readlane_b32 s6, v254, 34
	v_readlane_b32 s7, v254, 35
	s_add_u32 s6, s6, 0x1000000
	s_addc_u32 s7, s7, 0
	v_writelane_b32 v254, s6, 34
	s_nop 1
	v_writelane_b32 v254, s7, 35
	s_nop 0
	v_readlane_b32 s6, v254, 36
	v_readlane_b32 s7, v254, 37
	s_add_u32 s6, s6, 0x1000000
	s_addc_u32 s7, s7, 0
	v_writelane_b32 v254, s6, 36
	s_nop 1
	v_writelane_b32 v254, s7, 37
	v_writelane_b32 v254, s8, 38
	s_cmp_eq_u32 s8, 4
	s_nop 0
	v_writelane_b32 v254, s9, 39
	s_cbranch_scc0 .LBB0_185
	s_getpc_b64 s[98:99]

; #define PG8_STAGE(bufoff, gbase, voff) do { _Pragma("unroll") for (int _i = 0; _i < 2; ++_i) \
;         __builtin_amdgcn_global_load_lds((const unsigned*)((const char*)(gbase) + (voff)[_i]), (PG8_LAS unsigned*)(lds + (bufoff) + ldsw + _i * 8192), 16, 0, 0); } while (0)
; #define PG8_LDA(dst, b, h) do { _Pragma("unroll") for (int m = 0; m < 4; ++m) _Pragma("unroll") for (int k = 0; k < 2; ++k) dst[m][k] = *(const PG8_LAS bf16x8*)(lds + PG8_SA(b, h) + aoff + m * 2048 + k * 1024); } while (0)
; #define PG8_LDB(dst, b, h) do { _Pragma("unroll") for (int n = 0; n < 2; ++n) _Pragma("unroll") for (int k = 0; k < 2; ++k) dst[n][k] = *(const PG8_LAS bf16x8*)(lds + PG8_SB(b, h) + boff + n * 2048 + k * 1024); } while (0)
; #define PG8_MMA(ai, bj, At, Bt) do { __builtin_amdgcn_s_setprio(1); _Pragma("unroll") for (int m = 0; m < 4; ++m) _Pragma("unroll") for (int n = 0; n < 2; ++n) _Pragma("unroll") for (int k = 0; k < 2; ++k) \
;         acc[ai][bj][m][n] = __builtin_amdgcn_mfma_f32_16x16x32_bf16(Bt[n][k], At[m][k], acc[ai][bj][m][n], 0, 0, 0); __builtin_amdgcn_s_setprio(0); } while (0)
; #define PG8_WAIT_V(n) asm volatile("s_waitcnt vmcnt(" #n ")" ::: "memory")
; #define PG8_WAIT_L(n) asm volatile("s_waitcnt lgkmcnt(" #n ")" ::: "memory")
; #define PG8_BAR __builtin_amdgcn_s_barrier()
; #define PG8_SCHED __builtin_amdgcn_sched_barrier(0)
; template <class Epi, class Sched, bool ALIGN_EPI = false, bool SP2 = false>
; __device__ __forceinline__ void gemm_phase(PG8_LAS unsigned char* lds, const Gemm g, const Sched& S, const Epi& E) {
;     ...
;             PG8_LDB(B0, 0, 0); PG8_LDB(B1, 0, 1); PG8_SCHED; PG8_LDA(At, 0, 0); PG8_STAGE(PG8_SA(1, 1), a1 + hstep, voffA);
;             PG8_WAIT_V(8); PG8_WAIT_L(0); PG8_BAR; PG8_MMA(0, 0, At, B0); PG8_MMA(0, 1, At, B1); PG8_BAR; PG8_SCHED;
;             PG8_LDA(At, 0, 1); PG8_STAGE(PG8_SB(0, 0), b2, voffB); PG8_STAGE(PG8_SB(0, 1), b2 + hstep, voffB); PG8_STAGE(PG8_SA(0, 0), a2, voffA);
;             PG8_WAIT_V(8); PG8_WAIT_L(0); PG8_BAR; PG8_MMA(1, 0, At, B0); PG8_MMA(1, 1, At, B1); PG8_BAR; PG8_SCHED;
.LBB0_198:
	s_add_u32 s34, s10, 0xfff80080
	s_addc_u32 s35, s11, -1
	s_add_i32 s55, 0, 0x10000
	s_cmp_eq_u32 s54, 28
	s_cselect_b32 s37, s9, s35
	s_cselect_b32 s36, s13, s34
	s_cselect_b32 s35, s25, s53
	s_cselect_b32 s34, s27, s52
	s_add_i32 s62, 0, 0x14000
	v_add_u32_e32 v164, s55, v192
	v_add_u32_e32 v180, s62, v192
	ds_read_b128 v[130:133], v164
	ds_read_b128 v[134:137], v164 offset:1024
	ds_read_b128 v[160:163], v164 offset:2048
	ds_read_b128 v[164:167], v164 offset:3072
	ds_read_b128 v[168:171], v180
	ds_read_b128 v[172:175], v180 offset:1024
	ds_read_b128 v[176:179], v180 offset:2048
	ds_read_b128 v[180:183], v180 offset:3072
	v_lshl_add_u64 v[208:209], s[10:11], 0, v[156:157]
	s_add_i32 m0, s44, 0xc000
	ds_read_b128 v[184:187], v194
	ds_read_b128 v[188:191], v194 offset:1024
	ds_read_b128 v[196:199], v194 offset:2048
	ds_read_b128 v[200:203], v194 offset:3072
	ds_read_b128 v[204:207], v194 offset:4096
	ds_read_b128 v[226:229], v194 offset:5120
	ds_read_b128 v[230:233], v194 offset:6144
	ds_read_b128 v[234:237], v194 offset:7168
	global_load_lds_dwordx4 v[208:209], off
	v_lshl_add_u64 v[208:209], s[10:11], 0, v[158:159]
	s_add_i32 m0, s44, 0xe000
	s_nop 0
	global_load_lds_dwordx4 v[208:209], off
	s_waitcnt vmcnt(8)
	s_waitcnt lgkmcnt(0)
	s_barrier
	s_waitcnt lgkmcnt(0)
	v_mfma_f32_16x16x32_bf16 v[126:129], v[130:133], v[184:187], v[126:129]
	v_mfma_f32_16x16x32_bf16 v[122:125], v[160:163], v[184:187], v[122:125]
	v_mfma_f32_16x16x32_bf16 v[110:113], v[130:133], v[196:199], v[110:113]
	v_mfma_f32_16x16x32_bf16 v[106:109], v[160:163], v[196:199], v[106:109]
	v_mfma_f32_16x16x32_bf16 v[94:97], v[130:133], v[204:207], v[94:97]
	v_mfma_f32_16x16x32_bf16 v[90:93], v[160:163], v[204:207], v[90:93]
	v_mfma_f32_16x16x32_bf16 v[78:81], v[130:133], v[230:233], v[78:81]
	v_mfma_f32_16x16x32_bf16 v[74:77], v[160:163], v[230:233], v[74:77]
	v_mfma_f32_16x16x32_bf16 v[126:129], v[134:137], v[188:191], v[126:129]
	v_mfma_f32_16x16x32_bf16 v[122:125], v[164:167], v[188:191], v[122:125]
	v_mfma_f32_16x16x32_bf16 v[110:113], v[134:137], v[200:203], v[110:113]
	v_mfma_f32_16x16x32_bf16 v[106:109], v[164:167], v[200:203], v[106:109]
	v_mfma_f32_16x16x32_bf16 v[94:97], v[134:137], v[226:229], v[94:97]
	v_mfma_f32_16x16x32_bf16 v[90:93], v[164:167], v[226:229], v[90:93]
	v_mfma_f32_16x16x32_bf16 v[78:81], v[134:137], v[234:237], v[78:81]
	v_mfma_f32_16x16x32_bf16 v[74:77], v[164:167], v[234:237], v[74:77]
	v_mfma_f32_16x16x32_bf16 v[118:121], v[168:171], v[184:187], v[118:121]
	v_mfma_f32_16x16x32_bf16 v[114:117], v[176:179], v[184:187], v[114:117]
	v_mfma_f32_16x16x32_bf16 v[102:105], v[168:171], v[196:199], v[102:105]
	v_mfma_f32_16x16x32_bf16 v[98:101], v[176:179], v[196:199], v[98:101]
	v_mfma_f32_16x16x32_bf16 v[86:89], v[168:171], v[204:207], v[86:89]
	v_mfma_f32_16x16x32_bf16 v[82:85], v[176:179], v[204:207], v[82:85]
	v_mfma_f32_16x16x32_bf16 v[70:73], v[168:171], v[230:233], v[70:73]
	v_mfma_f32_16x16x32_bf16 v[66:69], v[176:179], v[230:233], v[66:69]
	v_mfma_f32_16x16x32_bf16 v[118:121], v[172:175], v[188:191], v[118:121]
	v_mfma_f32_16x16x32_bf16 v[114:117], v[180:183], v[188:191], v[114:117]
	v_mfma_f32_16x16x32_bf16 v[102:105], v[172:175], v[200:203], v[102:105]
	v_mfma_f32_16x16x32_bf16 v[98:101], v[180:183], v[200:203], v[98:101]
	v_mfma_f32_16x16x32_bf16 v[86:89], v[172:175], v[226:229], v[86:89]
	v_mfma_f32_16x16x32_bf16 v[82:85], v[180:183], v[226:229], v[82:85]
	v_mfma_f32_16x16x32_bf16 v[70:73], v[172:175], v[234:237], v[70:73]
	v_mfma_f32_16x16x32_bf16 v[66:69], v[180:183], v[234:237], v[66:69]
	s_barrier
	s_add_i32 s55, s55, s43
	v_lshl_add_u64 v[208:209], s[34:35], 0, v[0:1]
	s_mov_b32 m0, s55
	ds_read_b128 v[184:187], v194 offset:16384
	ds_read_b128 v[188:191], v194 offset:17408
	ds_read_b128 v[196:199], v194 offset:18432
	ds_read_b128 v[200:203], v194 offset:19456
	ds_read_b128 v[204:207], v194 offset:20480
	ds_read_b128 v[226:229], v194 offset:21504
	ds_read_b128 v[230:233], v194 offset:22528
	ds_read_b128 v[234:237], v194 offset:23552
	global_load_lds_dwordx4 v[208:209], off
	s_add_i32 m0, s55, 0x2000
	s_add_u32 s56, s34, 0x80000
	v_lshl_add_u64 v[238:239], s[34:35], 0, v[150:151]
	s_addc_u32 s57, s35, 0
	s_add_i32 s55, s62, s43
	global_load_lds_dwordx4 v[238:239], off
	v_lshl_add_u64 v[240:241], s[56:57], 0, v[0:1]
	s_mov_b32 m0, s55
	v_lshl_add_u64 v[242:243], s[36:37], 0, v[148:149]
	global_load_lds_dwordx4 v[240:241], off
	v_lshl_add_u64 v[240:241], s[56:57], 0, v[150:151]
	s_add_i32 m0, s55, 0x2000
	s_nop 0
	global_load_lds_dwordx4 v[240:241], off
	v_lshl_add_u64 v[240:241], s[36:37], 0, v[146:147]
	s_mov_b32 m0, s44
	s_nop 0
	global_load_lds_dwordx4 v[240:241], off
	s_mov_b32 m0, s45
	s_nop 0
	global_load_lds_dwordx4 v[242:243], off
	s_waitcnt vmcnt(8)
	s_waitcnt lgkmcnt(0)
	s_barrier
; #define PG8_STAGE(bufoff, gbase, voff) do { _Pragma("unroll") for (int _i = 0; _i < 2; ++_i) \
;         __builtin_amdgcn_global_load_lds((const unsigned*)((const char*)(gbase) + (voff)[_i]), (PG8_LAS unsigned*)(lds + (bufoff) + ldsw + _i * 8192), 16, 0, 0); } while (0)
; #define PG8_LDA(dst, b, h) do { _Pragma("unroll") for (int m = 0; m < 4; ++m) _Pragma("unroll") for (int k = 0; k < 2; ++k) dst[m][k] = *(const PG8_LAS bf16x8*)(lds + PG8_SA(b, h) + aoff + m * 2048 + k * 1024); } while (0)
; #define PG8_LDB(dst, b, h) do { _Pragma("unroll") for (int n = 0; n < 2; ++n) _Pragma("unroll") for (int k = 0; k < 2; ++k) dst[n][k] = *(const PG8_LAS bf16x8*)(lds + PG8_SB(b, h) + boff + n * 2048 + k * 1024); } while (0)
; #define PG8_MMA(ai, bj, At, Bt) do { __builtin_amdgcn_s_setprio(1); _Pragma("unroll") for (int m = 0; m < 4; ++m) _Pragma("unroll") for (int n = 0; n < 2; ++n) _Pragma("unroll") for (int k = 0; k < 2; ++k) \
;         acc[ai][bj][m][n] = __builtin_amdgcn_mfma_f32_16x16x32_bf16(Bt[n][k], At[m][k], acc[ai][bj][m][n], 0, 0, 0); __builtin_amdgcn_s_setprio(0); } while (0)
; #define PG8_WAIT_V(n) asm volatile("s_waitcnt vmcnt(" #n ")" ::: "memory")
; #define PG8_WAIT_L(n) asm volatile("s_waitcnt lgkmcnt(" #n ")" ::: "memory")
; #define PG8_BAR __builtin_amdgcn_s_barrier()
; #define PG8_SCHED __builtin_amdgcn_sched_barrier(0)
; template <class Epi, class Sched, bool ALIGN_EPI = false, bool SP2 = false>
; __device__ __forceinline__ void gemm_phase(PG8_LAS unsigned char* lds, const Gemm g, const Sched& S, const Epi& E) {
;     ...
;             PG8_WAIT_V(8); PG8_WAIT_L(0); PG8_BAR; PG8_MMA(1, 0, At, B0); PG8_MMA(1, 1, At, B1); PG8_BAR; PG8_SCHED;
;             PG8_LDB(B0, 1, 0); PG8_LDB(B1, 1, 1); PG8_SCHED; PG8_LDA(At, 1, 0); PG8_STAGE(PG8_SA(0, 1), a2 + hstep, voffA);
;             PG8_WAIT_V(8); PG8_WAIT_L(0); PG8_BAR; PG8_MMA(0, 0, At, B0); PG8_MMA(0, 1, At, B1); PG8_BAR; PG8_SCHED;
;             PG8_LDA(At, 1, 1); PG8_STAGE(PG8_SB(1, 0), b3, voffB); PG8_STAGE(PG8_SB(1, 1), b3 + hstep, voffB); PG8_STAGE(PG8_SA(1, 0), a3, voffA);
	s_waitcnt lgkmcnt(0)
	v_mfma_f32_16x16x32_bf16 v[62:65], v[130:133], v[184:187], v[62:65]
	v_mfma_f32_16x16x32_bf16 v[58:61], v[160:163], v[184:187], v[58:61]
	v_mfma_f32_16x16x32_bf16 v[46:49], v[130:133], v[196:199], v[46:49]
	v_mfma_f32_16x16x32_bf16 v[42:45], v[160:163], v[196:199], v[42:45]
	v_mfma_f32_16x16x32_bf16 v[30:33], v[130:133], v[204:207], v[30:33]
	v_mfma_f32_16x16x32_bf16 v[26:29], v[160:163], v[204:207], v[26:29]
	v_mfma_f32_16x16x32_bf16 v[14:17], v[130:133], v[230:233], v[14:17]
	v_mfma_f32_16x16x32_bf16 v[10:13], v[160:163], v[230:233], v[10:13]
	v_mfma_f32_16x16x32_bf16 v[62:65], v[134:137], v[188:191], v[62:65]
	v_mfma_f32_16x16x32_bf16 v[58:61], v[164:167], v[188:191], v[58:61]
	v_mfma_f32_16x16x32_bf16 v[46:49], v[134:137], v[200:203], v[46:49]
	v_mfma_f32_16x16x32_bf16 v[42:45], v[164:167], v[200:203], v[42:45]
	v_mfma_f32_16x16x32_bf16 v[30:33], v[134:137], v[226:229], v[30:33]
	v_mfma_f32_16x16x32_bf16 v[26:29], v[164:167], v[226:229], v[26:29]
	v_mfma_f32_16x16x32_bf16 v[14:17], v[134:137], v[234:237], v[14:17]
	v_mfma_f32_16x16x32_bf16 v[10:13], v[164:167], v[234:237], v[10:13]
	v_mfma_f32_16x16x32_bf16 v[54:57], v[168:171], v[184:187], v[54:57]
	v_mfma_f32_16x16x32_bf16 v[50:53], v[176:179], v[184:187], v[50:53]
	v_mfma_f32_16x16x32_bf16 v[38:41], v[168:171], v[196:199], v[38:41]
	v_mfma_f32_16x16x32_bf16 v[34:37], v[176:179], v[196:199], v[34:37]
	v_mfma_f32_16x16x32_bf16 v[22:25], v[168:171], v[204:207], v[22:25]
	v_mfma_f32_16x16x32_bf16 v[18:21], v[176:179], v[204:207], v[18:21]
	v_mfma_f32_16x16x32_bf16 v[6:9], v[168:171], v[230:233], v[6:9]
	v_mfma_f32_16x16x32_bf16 v[2:5], v[176:179], v[230:233], v[2:5]
	v_mfma_f32_16x16x32_bf16 v[54:57], v[172:175], v[188:191], v[54:57]
	v_mfma_f32_16x16x32_bf16 v[50:53], v[180:183], v[188:191], v[50:53]
	v_mfma_f32_16x16x32_bf16 v[38:41], v[172:175], v[200:203], v[38:41]
	v_mfma_f32_16x16x32_bf16 v[34:37], v[180:183], v[200:203], v[34:37]
	v_mfma_f32_16x16x32_bf16 v[22:25], v[172:175], v[226:229], v[22:25]
	v_mfma_f32_16x16x32_bf16 v[18:21], v[180:183], v[226:229], v[18:21]
	v_mfma_f32_16x16x32_bf16 v[6:9], v[172:175], v[234:237], v[6:9]
	v_mfma_f32_16x16x32_bf16 v[2:5], v[180:183], v[234:237], v[2:5]
	s_barrier
	s_add_i32 s55, 0, 0x18000
	s_add_i32 s56, 0, 0x1c000
	v_add_u32_e32 v164, s55, v192
	v_add_u32_e32 v180, s56, v192
	ds_read_b128 v[130:133], v164
	ds_read_b128 v[134:137], v164 offset:1024
	ds_read_b128 v[160:163], v164 offset:2048
	ds_read_b128 v[164:167], v164 offset:3072
	ds_read_b128 v[168:171], v180
	ds_read_b128 v[172:175], v180 offset:1024
	ds_read_b128 v[176:179], v180 offset:2048
	ds_read_b128 v[180:183], v180 offset:3072
	s_add_u32 s36, s36, 0x80000
	s_addc_u32 s37, s37, 0
	s_mov_b32 m0, s46
	v_lshl_add_u64 v[244:245], s[36:37], 0, v[146:147]
	ds_read_b128 v[184:187], v194 offset:32768
	ds_read_b128 v[188:191], v194 offset:33792
	ds_read_b128 v[196:199], v194 offset:34816
	ds_read_b128 v[200:203], v194 offset:35840
	ds_read_b128 v[204:207], v194 offset:36864
	ds_read_b128 v[226:229], v194 offset:37888
	ds_read_b128 v[230:233], v194 offset:38912
	ds_read_b128 v[234:237], v194 offset:39936
	global_load_lds_dwordx4 v[244:245], off
	v_lshl_add_u64 v[244:245], s[36:37], 0, v[148:149]
	s_mov_b32 m0, s47
	s_nop 0
	global_load_lds_dwordx4 v[244:245], off
	s_waitcnt vmcnt(8)
	s_waitcnt lgkmcnt(0)
	s_barrier
	s_waitcnt lgkmcnt(0)
	v_mfma_f32_16x16x32_bf16 v[126:129], v[130:133], v[184:187], v[126:129]
	v_mfma_f32_16x16x32_bf16 v[122:125], v[160:163], v[184:187], v[122:125]
	v_mfma_f32_16x16x32_bf16 v[110:113], v[130:133], v[196:199], v[110:113]
	v_mfma_f32_16x16x32_bf16 v[106:109], v[160:163], v[196:199], v[106:109]
	v_mfma_f32_16x16x32_bf16 v[94:97], v[130:133], v[204:207], v[94:97]
	v_mfma_f32_16x16x32_bf16 v[90:93], v[160:163], v[204:207], v[90:93]
	v_mfma_f32_16x16x32_bf16 v[78:81], v[130:133], v[230:233], v[78:81]
	v_mfma_f32_16x16x32_bf16 v[74:77], v[160:163], v[230:233], v[74:77]
	v_mfma_f32_16x16x32_bf16 v[126:129], v[134:137], v[188:191], v[126:129]
	v_mfma_f32_16x16x32_bf16 v[122:125], v[164:167], v[188:191], v[122:125]
	v_mfma_f32_16x16x32_bf16 v[110:113], v[134:137], v[200:203], v[110:113]
	v_mfma_f32_16x16x32_bf16 v[106:109], v[164:167], v[200:203], v[106:109]
	v_mfma_f32_16x16x32_bf16 v[94:97], v[134:137], v[226:229], v[94:97]
	v_mfma_f32_16x16x32_bf16 v[90:93], v[164:167], v[226:229], v[90:93]
	v_mfma_f32_16x16x32_bf16 v[78:81], v[134:137], v[234:237], v[78:81]
	v_mfma_f32_16x16x32_bf16 v[74:77], v[164:167], v[234:237], v[74:77]
	v_mfma_f32_16x16x32_bf16 v[118:121], v[168:171], v[184:187], v[118:121]
	v_mfma_f32_16x16x32_bf16 v[114:117], v[176:179], v[184:187], v[114:117]
	v_mfma_f32_16x16x32_bf16 v[102:105], v[168:171], v[196:199], v[102:105]
	v_mfma_f32_16x16x32_bf16 v[98:101], v[176:179], v[196:199], v[98:101]
	v_mfma_f32_16x16x32_bf16 v[86:89], v[168:171], v[204:207], v[86:89]
	v_mfma_f32_16x16x32_bf16 v[82:85], v[176:179], v[204:207], v[82:85]
	v_mfma_f32_16x16x32_bf16 v[70:73], v[168:171], v[230:233], v[70:73]
	v_mfma_f32_16x16x32_bf16 v[66:69], v[176:179], v[230:233], v[66:69]
	v_mfma_f32_16x16x32_bf16 v[118:121], v[172:175], v[188:191], v[118:121]
	v_mfma_f32_16x16x32_bf16 v[114:117], v[180:183], v[188:191], v[114:117]
	v_mfma_f32_16x16x32_bf16 v[102:105], v[172:175], v[200:203], v[102:105]
	v_mfma_f32_16x16x32_bf16 v[98:101], v[180:183], v[200:203], v[98:101]
	v_mfma_f32_16x16x32_bf16 v[86:89], v[172:175], v[226:229], v[86:89]
	v_mfma_f32_16x16x32_bf16 v[82:85], v[180:183], v[226:229], v[82:85]
	v_mfma_f32_16x16x32_bf16 v[70:73], v[172:175], v[234:237], v[70:73]
	v_mfma_f32_16x16x32_bf16 v[66:69], v[180:183], v[234:237], v[66:69]
	s_barrier
; #define PG8_STAGE(bufoff, gbase, voff) do { _Pragma("unroll") for (int _i = 0; _i < 2; ++_i) \
;         __builtin_amdgcn_global_load_lds((const unsigned*)((const char*)(gbase) + (voff)[_i]), (PG8_LAS unsigned*)(lds + (bufoff) + ldsw + _i * 8192), 16, 0, 0); } while (0)
; #define PG8_LDA(dst, b, h) do { _Pragma("unroll") for (int m = 0; m < 4; ++m) _Pragma("unroll") for (int k = 0; k < 2; ++k) dst[m][k] = *(const PG8_LAS bf16x8*)(lds + PG8_SA(b, h) + aoff + m * 2048 + k * 1024); } while (0)
; #define PG8_MMA(ai, bj, At, Bt) do { __builtin_amdgcn_s_setprio(1); _Pragma("unroll") for (int m = 0; m < 4; ++m) _Pragma("unroll") for (int n = 0; n < 2; ++n) _Pragma("unroll") for (int k = 0; k < 2; ++k) \
;         acc[ai][bj][m][n] = __builtin_amdgcn_mfma_f32_16x16x32_bf16(Bt[n][k], At[m][k], acc[ai][bj][m][n], 0, 0, 0); __builtin_amdgcn_s_setprio(0); } while (0)
; #define PG8_WAIT_V(n) asm volatile("s_waitcnt vmcnt(" #n ")" ::: "memory")
; #define PG8_WAIT_L(n) asm volatile("s_waitcnt lgkmcnt(" #n ")" ::: "memory")
; #define PG8_BAR __builtin_amdgcn_s_barrier()
; #define PG8_SCHED __builtin_amdgcn_sched_barrier(0)
; template <class Epi, class Sched, bool ALIGN_EPI = false, bool SP2 = false>
; __device__ __forceinline__ void gemm_phase(PG8_LAS unsigned char* lds, const Gemm g, const Sched& S, const Epi& E) {
;     ...
;         for (int t = 0; t < nt; t += 2) {
;     ...
;             PG8_LDA(At, 1, 1); PG8_STAGE(PG8_SB(1, 0), b3, voffB); PG8_STAGE(PG8_SB(1, 1), b3 + hstep, voffB); PG8_STAGE(PG8_SA(1, 0), a3, voffA);
;             PG8_WAIT_V(8); PG8_WAIT_L(0); PG8_BAR; PG8_MMA(1, 0, At, B0); PG8_MMA(1, 1, At, B1); PG8_BAR; PG8_SCHED;
	s_add_i32 s36, s55, s43
	v_lshl_add_u64 v[208:209], v[208:209], 0, s[0:1]
	s_mov_b32 m0, s36
	ds_read_b128 v[184:187], v194 offset:49152
	ds_read_b128 v[188:191], v194 offset:50176
	ds_read_b128 v[196:199], v194 offset:51200
	ds_read_b128 v[200:203], v194 offset:52224
	ds_read_b128 v[204:207], v194 offset:53248
	ds_read_b128 v[226:229], v194 offset:54272
	ds_read_b128 v[230:233], v194 offset:55296
	ds_read_b128 v[234:237], v194 offset:56320
	global_load_lds_dwordx4 v[208:209], off
	s_add_i32 m0, s36, 0x2000
	s_add_u32 s34, s34, 0x80080
	v_lshl_add_u64 v[208:209], v[238:239], 0, s[0:1]
	s_addc_u32 s35, s35, 0
	s_add_i32 s36, s56, s43
	global_load_lds_dwordx4 v[208:209], off
	v_lshl_add_u64 v[208:209], s[34:35], 0, v[0:1]
	s_mov_b32 m0, s36
	s_nop 0
	global_load_lds_dwordx4 v[208:209], off
	v_lshl_add_u64 v[208:209], s[34:35], 0, v[150:151]
	s_add_i32 m0, s36, 0x2000
	s_nop 0
	global_load_lds_dwordx4 v[208:209], off
	v_lshl_add_u64 v[208:209], v[240:241], 0, s[0:1]
	s_mov_b32 m0, s48
	s_nop 0
	global_load_lds_dwordx4 v[208:209], off
	v_lshl_add_u64 v[208:209], v[242:243], 0, s[0:1]
	s_mov_b32 m0, s49
	s_nop 0
	global_load_lds_dwordx4 v[208:209], off
	s_waitcnt vmcnt(8)
	s_waitcnt lgkmcnt(0)
	s_barrier
	s_waitcnt lgkmcnt(0)
	v_mfma_f32_16x16x32_bf16 v[62:65], v[130:133], v[184:187], v[62:65]
	v_mfma_f32_16x16x32_bf16 v[58:61], v[160:163], v[184:187], v[58:61]
	v_mfma_f32_16x16x32_bf16 v[46:49], v[130:133], v[196:199], v[46:49]
	v_mfma_f32_16x16x32_bf16 v[42:45], v[160:163], v[196:199], v[42:45]
	v_mfma_f32_16x16x32_bf16 v[30:33], v[130:133], v[204:207], v[30:33]
	v_mfma_f32_16x16x32_bf16 v[26:29], v[160:163], v[204:207], v[26:29]
	v_mfma_f32_16x16x32_bf16 v[14:17], v[130:133], v[230:233], v[14:17]
	v_mfma_f32_16x16x32_bf16 v[10:13], v[160:163], v[230:233], v[10:13]
	v_mfma_f32_16x16x32_bf16 v[62:65], v[134:137], v[188:191], v[62:65]
	v_mfma_f32_16x16x32_bf16 v[58:61], v[164:167], v[188:191], v[58:61]
	v_mfma_f32_16x16x32_bf16 v[46:49], v[134:137], v[200:203], v[46:49]
	v_mfma_f32_16x16x32_bf16 v[42:45], v[164:167], v[200:203], v[42:45]
	v_mfma_f32_16x16x32_bf16 v[30:33], v[134:137], v[226:229], v[30:33]
	v_mfma_f32_16x16x32_bf16 v[26:29], v[164:167], v[226:229], v[26:29]
	v_mfma_f32_16x16x32_bf16 v[14:17], v[134:137], v[234:237], v[14:17]
	v_mfma_f32_16x16x32_bf16 v[10:13], v[164:167], v[234:237], v[10:13]
	v_mfma_f32_16x16x32_bf16 v[54:57], v[168:171], v[184:187], v[54:57]
	v_mfma_f32_16x16x32_bf16 v[50:53], v[176:179], v[184:187], v[50:53]
	v_mfma_f32_16x16x32_bf16 v[38:41], v[168:171], v[196:199], v[38:41]
	v_mfma_f32_16x16x32_bf16 v[34:37], v[176:179], v[196:199], v[34:37]
	v_mfma_f32_16x16x32_bf16 v[22:25], v[168:171], v[204:207], v[22:25]
	v_mfma_f32_16x16x32_bf16 v[18:21], v[176:179], v[204:207], v[18:21]
	v_mfma_f32_16x16x32_bf16 v[6:9], v[168:171], v[230:233], v[6:9]
	v_mfma_f32_16x16x32_bf16 v[2:5], v[176:179], v[230:233], v[2:5]
	v_mfma_f32_16x16x32_bf16 v[54:57], v[172:175], v[188:191], v[54:57]
	v_mfma_f32_16x16x32_bf16 v[50:53], v[180:183], v[188:191], v[50:53]
	v_mfma_f32_16x16x32_bf16 v[38:41], v[172:175], v[200:203], v[38:41]
	v_mfma_f32_16x16x32_bf16 v[34:37], v[180:183], v[200:203], v[34:37]
	v_mfma_f32_16x16x32_bf16 v[22:25], v[172:175], v[226:229], v[22:25]
	v_mfma_f32_16x16x32_bf16 v[18:21], v[180:183], v[226:229], v[18:21]
	v_mfma_f32_16x16x32_bf16 v[6:9], v[172:175], v[234:237], v[6:9]
	v_mfma_f32_16x16x32_bf16 v[2:5], v[180:183], v[234:237], v[2:5]
	s_barrier
	s_add_i32 s54, s54, 2
	s_add_u32 s10, s10, 0x100
	s_addc_u32 s11, s11, 0
	s_add_u32 s52, s52, 0x100
	s_addc_u32 s53, s53, 0
	s_cmp_gt_u32 s54, 29
	s_cbranch_scc0 .LBB0_198
	s_and_b64 vcc, exec, s[22:23]
	s_cbranch_vccz .LBB0_201
	s_barrier

; #define GRID_SYNC() do { if (pc >= ph_lo && pc + 1 < ph_hi) { GAS unsigned char* w_ = (GAS unsigned char*)P.ws; OPQ64(w_); XcdBarrier xb_; xb_.bar = (unsigned*)(w_ + WS_BAR); xb_.x = xb_xcc_id(); xb_.st = (volatile LAS unsigned*)(lds + LDS_BYTES - 16); xcd_barrier(xb_); } ++pc; } while (0)
; __global__ void __launch_bounds__(NTHREADS, 2) hybrid_fwd(Params P) {
;     ...
;             GRID_SYNC();
;             for (int rep_ = 0; rep_ < (PH(2) ? REP(2) : 0); ++rep_) {
.LBB0_306:
	s_or_b64 exec, exec, s[8:9]
	s_waitcnt lgkmcnt(0)
	s_barrier
	s_setprio 0

; #define PG8_STAGE(bufoff, gbase, voff) do { _Pragma("unroll") for (int _i = 0; _i < 2; ++_i) \
;         __builtin_amdgcn_global_load_lds((const unsigned*)((const char*)(gbase) + (voff)[_i]), (PG8_LAS unsigned*)(lds + (bufoff) + ldsw + _i * 8192), 16, 0, 0); } while (0)
; #define PG8_LDA(dst, b, h) do { _Pragma("unroll") for (int m = 0; m < 4; ++m) _Pragma("unroll") for (int k = 0; k < 2; ++k) dst[m][k] = *(const PG8_LAS bf16x8*)(lds + PG8_SA(b, h) + aoff + m * 2048 + k * 1024); } while (0)
; #define PG8_LDB(dst, b, h) do { _Pragma("unroll") for (int n = 0; n < 2; ++n) _Pragma("unroll") for (int k = 0; k < 2; ++k) dst[n][k] = *(const PG8_LAS bf16x8*)(lds + PG8_SB(b, h) + boff + n * 2048 + k * 1024); } while (0)
; #define PG8_MMA(ai, bj, At, Bt) do { __builtin_amdgcn_s_setprio(1); _Pragma("unroll") for (int m = 0; m < 4; ++m) _Pragma("unroll") for (int n = 0; n < 2; ++n) _Pragma("unroll") for (int k = 0; k < 2; ++k) \
;         acc[ai][bj][m][n] = __builtin_amdgcn_mfma_f32_16x16x32_bf16(Bt[n][k], At[m][k], acc[ai][bj][m][n], 0, 0, 0); __builtin_amdgcn_s_setprio(0); } while (0)
; #define PG8_WAIT_V(n) asm volatile("s_waitcnt vmcnt(" #n ")" ::: "memory")
; #define PG8_WAIT_L(n) asm volatile("s_waitcnt lgkmcnt(" #n ")" ::: "memory")
; #define PG8_BAR __builtin_amdgcn_s_barrier()
; #define PG8_SCHED __builtin_amdgcn_sched_barrier(0)
; template <class Epi, class Sched, bool ALIGN_EPI = false, bool SP2 = false>
; __device__ __forceinline__ void gemm_phase(PG8_LAS unsigned char* lds, const Gemm g, const Sched& S, const Epi& E) {
;     ...
;             PG8_LDB(B0, 0, 0); PG8_LDB(B1, 0, 1); PG8_SCHED; PG8_LDA(At, 0, 0); PG8_STAGE(PG8_SA(1, 1), a1 + hstep, voffA);
;             PG8_WAIT_V(8); PG8_WAIT_L(0); PG8_BAR; PG8_MMA(0, 0, At, B0); PG8_MMA(0, 1, At, B1); PG8_BAR; PG8_SCHED;
;             PG8_LDA(At, 0, 1); PG8_STAGE(PG8_SB(0, 0), b2, voffB); PG8_STAGE(PG8_SB(0, 1), b2 + hstep, voffB); PG8_STAGE(PG8_SA(0, 0), a2, voffA);
.LBB0_335:
	s_add_u32 s50, s10, 0xfff80080
	s_addc_u32 s51, s11, -1
	s_add_i32 s78, 0, 0x10000
	s_cmp_eq_u32 s77, 28
	s_cselect_b32 s53, s9, s51
	s_cselect_b32 s52, s13, s50
	s_cselect_b32 s51, s41, s76
	s_cselect_b32 s50, s45, s75
	s_add_i32 s80, 0, 0x14000
	v_add_u32_e32 v164, s78, v193
	v_add_u32_e32 v180, s80, v193
	ds_read_b128 v[130:133], v164
	ds_read_b128 v[134:137], v164 offset:1024
	ds_read_b128 v[160:163], v164 offset:2048
	ds_read_b128 v[164:167], v164 offset:3072
	ds_read_b128 v[168:171], v180
	ds_read_b128 v[172:175], v180 offset:1024
	ds_read_b128 v[176:179], v180 offset:2048
	ds_read_b128 v[180:183], v180 offset:3072
	v_lshl_add_u64 v[208:209], s[10:11], 0, v[156:157]
	s_add_i32 m0, s63, 0xc000
	ds_read_b128 v[184:187], v195
	ds_read_b128 v[188:191], v195 offset:1024
	ds_read_b128 v[196:199], v195 offset:2048
	ds_read_b128 v[200:203], v195 offset:3072
	ds_read_b128 v[204:207], v195 offset:4096
	ds_read_b128 v[226:229], v195 offset:5120
	ds_read_b128 v[230:233], v195 offset:6144
	ds_read_b128 v[234:237], v195 offset:7168
	global_load_lds_dwordx4 v[208:209], off
	v_lshl_add_u64 v[208:209], s[10:11], 0, v[158:159]
	s_add_i32 m0, s63, 0xe000
	s_nop 0
	global_load_lds_dwordx4 v[208:209], off
	s_waitcnt vmcnt(8)
	s_waitcnt lgkmcnt(0)
	s_barrier
	s_waitcnt lgkmcnt(0)
	v_mfma_f32_16x16x32_bf16 v[126:129], v[130:133], v[184:187], v[126:129]
	v_mfma_f32_16x16x32_bf16 v[122:125], v[160:163], v[184:187], v[122:125]
	v_mfma_f32_16x16x32_bf16 v[110:113], v[130:133], v[196:199], v[110:113]
	v_mfma_f32_16x16x32_bf16 v[106:109], v[160:163], v[196:199], v[106:109]
	v_mfma_f32_16x16x32_bf16 v[94:97], v[130:133], v[204:207], v[94:97]
	v_mfma_f32_16x16x32_bf16 v[90:93], v[160:163], v[204:207], v[90:93]
	v_mfma_f32_16x16x32_bf16 v[78:81], v[130:133], v[230:233], v[78:81]
	v_mfma_f32_16x16x32_bf16 v[74:77], v[160:163], v[230:233], v[74:77]
	v_mfma_f32_16x16x32_bf16 v[126:129], v[134:137], v[188:191], v[126:129]
	v_mfma_f32_16x16x32_bf16 v[122:125], v[164:167], v[188:191], v[122:125]
	v_mfma_f32_16x16x32_bf16 v[110:113], v[134:137], v[200:203], v[110:113]
	v_mfma_f32_16x16x32_bf16 v[106:109], v[164:167], v[200:203], v[106:109]
	v_mfma_f32_16x16x32_bf16 v[94:97], v[134:137], v[226:229], v[94:97]
	v_mfma_f32_16x16x32_bf16 v[90:93], v[164:167], v[226:229], v[90:93]
	v_mfma_f32_16x16x32_bf16 v[78:81], v[134:137], v[234:237], v[78:81]
	v_mfma_f32_16x16x32_bf16 v[74:77], v[164:167], v[234:237], v[74:77]
	v_mfma_f32_16x16x32_bf16 v[118:121], v[168:171], v[184:187], v[118:121]
	v_mfma_f32_16x16x32_bf16 v[114:117], v[176:179], v[184:187], v[114:117]
	v_mfma_f32_16x16x32_bf16 v[102:105], v[168:171], v[196:199], v[102:105]
	v_mfma_f32_16x16x32_bf16 v[98:101], v[176:179], v[196:199], v[98:101]
	v_mfma_f32_16x16x32_bf16 v[86:89], v[168:171], v[204:207], v[86:89]
	v_mfma_f32_16x16x32_bf16 v[82:85], v[176:179], v[204:207], v[82:85]
	v_mfma_f32_16x16x32_bf16 v[70:73], v[168:171], v[230:233], v[70:73]
	v_mfma_f32_16x16x32_bf16 v[66:69], v[176:179], v[230:233], v[66:69]
	v_mfma_f32_16x16x32_bf16 v[118:121], v[172:175], v[188:191], v[118:121]
	v_mfma_f32_16x16x32_bf16 v[114:117], v[180:183], v[188:191], v[114:117]
	v_mfma_f32_16x16x32_bf16 v[102:105], v[172:175], v[200:203], v[102:105]
	v_mfma_f32_16x16x32_bf16 v[98:101], v[180:183], v[200:203], v[98:101]
	v_mfma_f32_16x16x32_bf16 v[86:89], v[172:175], v[226:229], v[86:89]
	v_mfma_f32_16x16x32_bf16 v[82:85], v[180:183], v[226:229], v[82:85]
	v_mfma_f32_16x16x32_bf16 v[70:73], v[172:175], v[234:237], v[70:73]
	v_mfma_f32_16x16x32_bf16 v[66:69], v[180:183], v[234:237], v[66:69]
	s_barrier
	s_add_i32 s78, s78, s62
	v_lshl_add_u64 v[208:209], s[50:51], 0, v[0:1]
	s_mov_b32 m0, s78
	ds_read_b128 v[184:187], v195 offset:16384
	ds_read_b128 v[188:191], v195 offset:17408
	ds_read_b128 v[196:199], v195 offset:18432
	ds_read_b128 v[200:203], v195 offset:19456
	ds_read_b128 v[204:207], v195 offset:20480
	ds_read_b128 v[226:229], v195 offset:21504
	ds_read_b128 v[230:233], v195 offset:22528
	ds_read_b128 v[234:237], v195 offset:23552
	global_load_lds_dwordx4 v[208:209], off
	s_add_i32 m0, s78, 0x2000
	s_add_u32 s78, s50, 0x80000
	v_lshl_add_u64 v[238:239], s[50:51], 0, v[150:151]
	s_addc_u32 s79, s51, 0
	s_add_i32 s80, s80, s62
	global_load_lds_dwordx4 v[238:239], off
	v_lshl_add_u64 v[240:241], s[78:79], 0, v[0:1]
	s_mov_b32 m0, s80
	v_lshl_add_u64 v[242:243], s[52:53], 0, v[148:149]
	global_load_lds_dwordx4 v[240:241], off
	v_lshl_add_u64 v[240:241], s[78:79], 0, v[150:151]
	s_add_i32 m0, s80, 0x2000
	s_nop 0
	global_load_lds_dwordx4 v[240:241], off
	v_lshl_add_u64 v[240:241], s[52:53], 0, v[146:147]
	s_mov_b32 m0, s63
	s_nop 0
	global_load_lds_dwordx4 v[240:241], off
	s_mov_b32 m0, s68
	s_nop 0
	global_load_lds_dwordx4 v[242:243], off
	s_waitcnt vmcnt(8)
	s_waitcnt lgkmcnt(0)
	s_barrier
; #define PG8_STAGE(bufoff, gbase, voff) do { _Pragma("unroll") for (int _i = 0; _i < 2; ++_i) \
;         __builtin_amdgcn_global_load_lds((const unsigned*)((const char*)(gbase) + (voff)[_i]), (PG8_LAS unsigned*)(lds + (bufoff) + ldsw + _i * 8192), 16, 0, 0); } while (0)
; #define PG8_LDA(dst, b, h) do { _Pragma("unroll") for (int m = 0; m < 4; ++m) _Pragma("unroll") for (int k = 0; k < 2; ++k) dst[m][k] = *(const PG8_LAS bf16x8*)(lds + PG8_SA(b, h) + aoff + m * 2048 + k * 1024); } while (0)
; #define PG8_LDB(dst, b, h) do { _Pragma("unroll") for (int n = 0; n < 2; ++n) _Pragma("unroll") for (int k = 0; k < 2; ++k) dst[n][k] = *(const PG8_LAS bf16x8*)(lds + PG8_SB(b, h) + boff + n * 2048 + k * 1024); } while (0)
; #define PG8_MMA(ai, bj, At, Bt) do { __builtin_amdgcn_s_setprio(1); _Pragma("unroll") for (int m = 0; m < 4; ++m) _Pragma("unroll") for (int n = 0; n < 2; ++n) _Pragma("unroll") for (int k = 0; k < 2; ++k) \
;         acc[ai][bj][m][n] = __builtin_amdgcn_mfma_f32_16x16x32_bf16(Bt[n][k], At[m][k], acc[ai][bj][m][n], 0, 0, 0); __builtin_amdgcn_s_setprio(0); } while (0)
; #define PG8_WAIT_V(n) asm volatile("s_waitcnt vmcnt(" #n ")" ::: "memory")
; #define PG8_WAIT_L(n) asm volatile("s_waitcnt lgkmcnt(" #n ")" ::: "memory")
; #define PG8_BAR __builtin_amdgcn_s_barrier()
; #define PG8_SCHED __builtin_amdgcn_sched_barrier(0)
; template <class Epi, class Sched, bool ALIGN_EPI = false, bool SP2 = false>
; __device__ __forceinline__ void gemm_phase(PG8_LAS unsigned char* lds, const Gemm g, const Sched& S, const Epi& E) {
;     ...
;             PG8_WAIT_V(8); PG8_WAIT_L(0); PG8_BAR; PG8_MMA(1, 0, At, B0); PG8_MMA(1, 1, At, B1); PG8_BAR; PG8_SCHED;
;             PG8_LDB(B0, 1, 0); PG8_LDB(B1, 1, 1); PG8_SCHED; PG8_LDA(At, 1, 0); PG8_STAGE(PG8_SA(0, 1), a2 + hstep, voffA);
;             PG8_WAIT_V(8); PG8_WAIT_L(0); PG8_BAR; PG8_MMA(0, 0, At, B0); PG8_MMA(0, 1, At, B1); PG8_BAR; PG8_SCHED;
	s_waitcnt lgkmcnt(0)
	v_mfma_f32_16x16x32_bf16 v[62:65], v[130:133], v[184:187], v[62:65]
	v_mfma_f32_16x16x32_bf16 v[58:61], v[160:163], v[184:187], v[58:61]
	v_mfma_f32_16x16x32_bf16 v[46:49], v[130:133], v[196:199], v[46:49]
	v_mfma_f32_16x16x32_bf16 v[42:45], v[160:163], v[196:199], v[42:45]
	v_mfma_f32_16x16x32_bf16 v[30:33], v[130:133], v[204:207], v[30:33]
	v_mfma_f32_16x16x32_bf16 v[26:29], v[160:163], v[204:207], v[26:29]
	v_mfma_f32_16x16x32_bf16 v[14:17], v[130:133], v[230:233], v[14:17]
	v_mfma_f32_16x16x32_bf16 v[10:13], v[160:163], v[230:233], v[10:13]
	v_mfma_f32_16x16x32_bf16 v[62:65], v[134:137], v[188:191], v[62:65]
	v_mfma_f32_16x16x32_bf16 v[58:61], v[164:167], v[188:191], v[58:61]
	v_mfma_f32_16x16x32_bf16 v[46:49], v[134:137], v[200:203], v[46:49]
	v_mfma_f32_16x16x32_bf16 v[42:45], v[164:167], v[200:203], v[42:45]
	v_mfma_f32_16x16x32_bf16 v[30:33], v[134:137], v[226:229], v[30:33]
	v_mfma_f32_16x16x32_bf16 v[26:29], v[164:167], v[226:229], v[26:29]
	v_mfma_f32_16x16x32_bf16 v[14:17], v[134:137], v[234:237], v[14:17]
	v_mfma_f32_16x16x32_bf16 v[10:13], v[164:167], v[234:237], v[10:13]
	v_mfma_f32_16x16x32_bf16 v[54:57], v[168:171], v[184:187], v[54:57]
	v_mfma_f32_16x16x32_bf16 v[50:53], v[176:179], v[184:187], v[50:53]
	v_mfma_f32_16x16x32_bf16 v[38:41], v[168:171], v[196:199], v[38:41]
	v_mfma_f32_16x16x32_bf16 v[34:37], v[176:179], v[196:199], v[34:37]
	v_mfma_f32_16x16x32_bf16 v[22:25], v[168:171], v[204:207], v[22:25]
	v_mfma_f32_16x16x32_bf16 v[18:21], v[176:179], v[204:207], v[18:21]
	v_mfma_f32_16x16x32_bf16 v[6:9], v[168:171], v[230:233], v[6:9]
	v_mfma_f32_16x16x32_bf16 v[2:5], v[176:179], v[230:233], v[2:5]
	v_mfma_f32_16x16x32_bf16 v[54:57], v[172:175], v[188:191], v[54:57]
	v_mfma_f32_16x16x32_bf16 v[50:53], v[180:183], v[188:191], v[50:53]
	v_mfma_f32_16x16x32_bf16 v[38:41], v[172:175], v[200:203], v[38:41]
	v_mfma_f32_16x16x32_bf16 v[34:37], v[180:183], v[200:203], v[34:37]
	v_mfma_f32_16x16x32_bf16 v[22:25], v[172:175], v[226:229], v[22:25]
	v_mfma_f32_16x16x32_bf16 v[18:21], v[180:183], v[226:229], v[18:21]
	v_mfma_f32_16x16x32_bf16 v[6:9], v[172:175], v[234:237], v[6:9]
	v_mfma_f32_16x16x32_bf16 v[2:5], v[180:183], v[234:237], v[2:5]
	s_barrier
	s_add_i32 s78, 0, 0x18000
	s_add_i32 s79, 0, 0x1c000
	v_add_u32_e32 v164, s78, v193
	v_add_u32_e32 v180, s79, v193
	ds_read_b128 v[130:133], v164
	ds_read_b128 v[134:137], v164 offset:1024
	ds_read_b128 v[160:163], v164 offset:2048
	ds_read_b128 v[164:167], v164 offset:3072
	ds_read_b128 v[168:171], v180
	ds_read_b128 v[172:175], v180 offset:1024
	ds_read_b128 v[176:179], v180 offset:2048
	ds_read_b128 v[180:183], v180 offset:3072
	s_add_u32 s52, s52, 0x80000
	s_addc_u32 s53, s53, 0
	s_mov_b32 m0, s69
	v_lshl_add_u64 v[244:245], s[52:53], 0, v[146:147]
	ds_read_b128 v[184:187], v195 offset:32768
	ds_read_b128 v[188:191], v195 offset:33792
	ds_read_b128 v[196:199], v195 offset:34816
	ds_read_b128 v[200:203], v195 offset:35840
	ds_read_b128 v[204:207], v195 offset:36864
	ds_read_b128 v[226:229], v195 offset:37888
	ds_read_b128 v[230:233], v195 offset:38912
	ds_read_b128 v[234:237], v195 offset:39936
	global_load_lds_dwordx4 v[244:245], off
	v_lshl_add_u64 v[244:245], s[52:53], 0, v[148:149]
	s_mov_b32 m0, s70
	s_nop 0
	global_load_lds_dwordx4 v[244:245], off
	s_waitcnt vmcnt(8)
	s_waitcnt lgkmcnt(0)
	s_barrier
	s_waitcnt lgkmcnt(0)
	v_mfma_f32_16x16x32_bf16 v[126:129], v[130:133], v[184:187], v[126:129]
	v_mfma_f32_16x16x32_bf16 v[122:125], v[160:163], v[184:187], v[122:125]
	v_mfma_f32_16x16x32_bf16 v[110:113], v[130:133], v[196:199], v[110:113]
	v_mfma_f32_16x16x32_bf16 v[106:109], v[160:163], v[196:199], v[106:109]
	v_mfma_f32_16x16x32_bf16 v[94:97], v[130:133], v[204:207], v[94:97]
	v_mfma_f32_16x16x32_bf16 v[90:93], v[160:163], v[204:207], v[90:93]
	v_mfma_f32_16x16x32_bf16 v[78:81], v[130:133], v[230:233], v[78:81]
	v_mfma_f32_16x16x32_bf16 v[74:77], v[160:163], v[230:233], v[74:77]
	v_mfma_f32_16x16x32_bf16 v[126:129], v[134:137], v[188:191], v[126:129]
	v_mfma_f32_16x16x32_bf16 v[122:125], v[164:167], v[188:191], v[122:125]
	v_mfma_f32_16x16x32_bf16 v[110:113], v[134:137], v[200:203], v[110:113]
	v_mfma_f32_16x16x32_bf16 v[106:109], v[164:167], v[200:203], v[106:109]
	v_mfma_f32_16x16x32_bf16 v[94:97], v[134:137], v[226:229], v[94:97]
	v_mfma_f32_16x16x32_bf16 v[90:93], v[164:167], v[226:229], v[90:93]
	v_mfma_f32_16x16x32_bf16 v[78:81], v[134:137], v[234:237], v[78:81]
	v_mfma_f32_16x16x32_bf16 v[74:77], v[164:167], v[234:237], v[74:77]
	v_mfma_f32_16x16x32_bf16 v[118:121], v[168:171], v[184:187], v[118:121]
	v_mfma_f32_16x16x32_bf16 v[114:117], v[176:179], v[184:187], v[114:117]
	v_mfma_f32_16x16x32_bf16 v[102:105], v[168:171], v[196:199], v[102:105]
	v_mfma_f32_16x16x32_bf16 v[98:101], v[176:179], v[196:199], v[98:101]
	v_mfma_f32_16x16x32_bf16 v[86:89], v[168:171], v[204:207], v[86:89]
	v_mfma_f32_16x16x32_bf16 v[82:85], v[176:179], v[204:207], v[82:85]
	v_mfma_f32_16x16x32_bf16 v[70:73], v[168:171], v[230:233], v[70:73]
	v_mfma_f32_16x16x32_bf16 v[66:69], v[176:179], v[230:233], v[66:69]
	v_mfma_f32_16x16x32_bf16 v[118:121], v[172:175], v[188:191], v[118:121]
	v_mfma_f32_16x16x32_bf16 v[114:117], v[180:183], v[188:191], v[114:117]
	v_mfma_f32_16x16x32_bf16 v[102:105], v[172:175], v[200:203], v[102:105]
	v_mfma_f32_16x16x32_bf16 v[98:101], v[180:183], v[200:203], v[98:101]
	v_mfma_f32_16x16x32_bf16 v[86:89], v[172:175], v[226:229], v[86:89]
	v_mfma_f32_16x16x32_bf16 v[82:85], v[180:183], v[226:229], v[82:85]
	v_mfma_f32_16x16x32_bf16 v[70:73], v[172:175], v[234:237], v[70:73]
	v_mfma_f32_16x16x32_bf16 v[66:69], v[180:183], v[234:237], v[66:69]
	s_barrier
; #define PG8_STAGE(bufoff, gbase, voff) do { _Pragma("unroll") for (int _i = 0; _i < 2; ++_i) \
;         __builtin_amdgcn_global_load_lds((const unsigned*)((const char*)(gbase) + (voff)[_i]), (PG8_LAS unsigned*)(lds + (bufoff) + ldsw + _i * 8192), 16, 0, 0); } while (0)
; #define PG8_LDA(dst, b, h) do { _Pragma("unroll") for (int m = 0; m < 4; ++m) _Pragma("unroll") for (int k = 0; k < 2; ++k) dst[m][k] = *(const PG8_LAS bf16x8*)(lds + PG8_SA(b, h) + aoff + m * 2048 + k * 1024); } while (0)
; #define PG8_MMA(ai, bj, At, Bt) do { __builtin_amdgcn_s_setprio(1); _Pragma("unroll") for (int m = 0; m < 4; ++m) _Pragma("unroll") for (int n = 0; n < 2; ++n) _Pragma("unroll") for (int k = 0; k < 2; ++k) \
;         acc[ai][bj][m][n] = __builtin_amdgcn_mfma_f32_16x16x32_bf16(Bt[n][k], At[m][k], acc[ai][bj][m][n], 0, 0, 0); __builtin_amdgcn_s_setprio(0); } while (0)
; #define PG8_WAIT_V(n) asm volatile("s_waitcnt vmcnt(" #n ")" ::: "memory")
; #define PG8_WAIT_L(n) asm volatile("s_waitcnt lgkmcnt(" #n ")" ::: "memory")
; #define PG8_BAR __builtin_amdgcn_s_barrier()
; #define PG8_SCHED __builtin_amdgcn_sched_barrier(0)
; template <class Epi, class Sched, bool ALIGN_EPI = false, bool SP2 = false>
; __device__ __forceinline__ void gemm_phase(PG8_LAS unsigned char* lds, const Gemm g, const Sched& S, const Epi& E) {
;     ...
;             PG8_LDA(At, 1, 1); PG8_STAGE(PG8_SB(1, 0), b3, voffB); PG8_STAGE(PG8_SB(1, 1), b3 + hstep, voffB); PG8_STAGE(PG8_SA(1, 0), a3, voffA);
;             PG8_WAIT_V(8); PG8_WAIT_L(0); PG8_BAR; PG8_MMA(1, 0, At, B0); PG8_MMA(1, 1, At, B1); PG8_BAR; PG8_SCHED;
	s_add_i32 s52, s78, s62
	v_lshl_add_u64 v[208:209], v[208:209], 0, s[0:1]
	s_mov_b32 m0, s52
	ds_read_b128 v[184:187], v195 offset:49152
	ds_read_b128 v[188:191], v195 offset:50176
	ds_read_b128 v[196:199], v195 offset:51200
	ds_read_b128 v[200:203], v195 offset:52224
	ds_read_b128 v[204:207], v195 offset:53248
	ds_read_b128 v[226:229], v195 offset:54272
	ds_read_b128 v[230:233], v195 offset:55296
	ds_read_b128 v[234:237], v195 offset:56320
	global_load_lds_dwordx4 v[208:209], off
	s_add_i32 m0, s52, 0x2000
	s_add_u32 s50, s50, 0x80080
	v_lshl_add_u64 v[208:209], v[238:239], 0, s[0:1]
	s_addc_u32 s51, s51, 0
	s_add_i32 s52, s79, s62
	global_load_lds_dwordx4 v[208:209], off
	v_lshl_add_u64 v[208:209], s[50:51], 0, v[0:1]
	s_mov_b32 m0, s52
	s_nop 0
	global_load_lds_dwordx4 v[208:209], off
	v_lshl_add_u64 v[208:209], s[50:51], 0, v[150:151]
	s_add_i32 m0, s52, 0x2000
	s_nop 0
	global_load_lds_dwordx4 v[208:209], off
	v_lshl_add_u64 v[208:209], v[240:241], 0, s[0:1]
	s_mov_b32 m0, s71
	s_nop 0
	global_load_lds_dwordx4 v[208:209], off
	v_lshl_add_u64 v[208:209], v[242:243], 0, s[0:1]
	s_mov_b32 m0, s72
	s_nop 0
	global_load_lds_dwordx4 v[208:209], off
	s_waitcnt vmcnt(8)
	s_waitcnt lgkmcnt(0)
	s_barrier
	s_waitcnt lgkmcnt(0)
	v_mfma_f32_16x16x32_bf16 v[62:65], v[130:133], v[184:187], v[62:65]
	v_mfma_f32_16x16x32_bf16 v[58:61], v[160:163], v[184:187], v[58:61]
	v_mfma_f32_16x16x32_bf16 v[46:49], v[130:133], v[196:199], v[46:49]
	v_mfma_f32_16x16x32_bf16 v[42:45], v[160:163], v[196:199], v[42:45]
	v_mfma_f32_16x16x32_bf16 v[30:33], v[130:133], v[204:207], v[30:33]
	v_mfma_f32_16x16x32_bf16 v[26:29], v[160:163], v[204:207], v[26:29]
	v_mfma_f32_16x16x32_bf16 v[14:17], v[130:133], v[230:233], v[14:17]
	v_mfma_f32_16x16x32_bf16 v[10:13], v[160:163], v[230:233], v[10:13]
	v_mfma_f32_16x16x32_bf16 v[62:65], v[134:137], v[188:191], v[62:65]
	v_mfma_f32_16x16x32_bf16 v[58:61], v[164:167], v[188:191], v[58:61]
	v_mfma_f32_16x16x32_bf16 v[46:49], v[134:137], v[200:203], v[46:49]
	v_mfma_f32_16x16x32_bf16 v[42:45], v[164:167], v[200:203], v[42:45]
	v_mfma_f32_16x16x32_bf16 v[30:33], v[134:137], v[226:229], v[30:33]
	v_mfma_f32_16x16x32_bf16 v[26:29], v[164:167], v[226:229], v[26:29]
	v_mfma_f32_16x16x32_bf16 v[14:17], v[134:137], v[234:237], v[14:17]
	v_mfma_f32_16x16x32_bf16 v[10:13], v[164:167], v[234:237], v[10:13]
	v_mfma_f32_16x16x32_bf16 v[54:57], v[168:171], v[184:187], v[54:57]
	v_mfma_f32_16x16x32_bf16 v[50:53], v[176:179], v[184:187], v[50:53]
	v_mfma_f32_16x16x32_bf16 v[38:41], v[168:171], v[196:199], v[38:41]
	v_mfma_f32_16x16x32_bf16 v[34:37], v[176:179], v[196:199], v[34:37]
	v_mfma_f32_16x16x32_bf16 v[22:25], v[168:171], v[204:207], v[22:25]
	v_mfma_f32_16x16x32_bf16 v[18:21], v[176:179], v[204:207], v[18:21]
	v_mfma_f32_16x16x32_bf16 v[6:9], v[168:171], v[230:233], v[6:9]
	v_mfma_f32_16x16x32_bf16 v[2:5], v[176:179], v[230:233], v[2:5]
	v_mfma_f32_16x16x32_bf16 v[54:57], v[172:175], v[188:191], v[54:57]
	v_mfma_f32_16x16x32_bf16 v[50:53], v[180:183], v[188:191], v[50:53]
	v_mfma_f32_16x16x32_bf16 v[38:41], v[172:175], v[200:203], v[38:41]
	v_mfma_f32_16x16x32_bf16 v[34:37], v[180:183], v[200:203], v[34:37]
	v_mfma_f32_16x16x32_bf16 v[22:25], v[172:175], v[226:229], v[22:25]
	v_mfma_f32_16x16x32_bf16 v[18:21], v[180:183], v[226:229], v[18:21]
	v_mfma_f32_16x16x32_bf16 v[6:9], v[172:175], v[234:237], v[6:9]
	v_mfma_f32_16x16x32_bf16 v[2:5], v[180:183], v[234:237], v[2:5]
	s_barrier
	s_add_i32 s77, s77, 2
	s_add_u32 s10, s10, 0x100
	s_addc_u32 s11, s11, 0
	s_add_u32 s75, s75, 0x100
	s_addc_u32 s76, s76, 0
	s_cmp_gt_u32 s77, 29
	s_cbranch_scc0 .LBB0_335
	s_and_b64 vcc, exec, s[38:39]
	s_cbranch_vccz .LBB0_338
	s_barrier

; #define LAS __attribute__((address_space(3)))
; #define WSB(name, type, off) type* name; { GAS unsigned char* w_ = (GAS unsigned char*)P.ws; OPQ64(w_); name = (type*)(w_ + (off)); }
; __device__ __forceinline__ void sample_out_block(LAS unsigned char* lds, const bf16_t* A, const bf16_t* Bt, int K, bf16_t* xb, float* sspart, int blk, int tid) {
;     const int wave = tid >> 6, lane = tid & 63, l15 = lane & 15, g = lane >> 4;
;     const int rt = blk >> 5, cg = blk & 31, r0 = T_P + 32 * rt;
;     const int kq = K >> 3;
;     f32x4 acc[2][4];
; #pragma unroll
;     for (int ra = 0; ra < 2; ++ra)
; #pragma unroll
;         for (int nt = 0; nt < 4; ++nt) acc[ra][nt] = (f32x4){0.f, 0.f, 0.f, 0.f};
;     {
;         const bf16_t* ap = A + (size_t)(r0 + l15) * K + wave * kq + 8 * g;
;         const bf16_t* bp = Bt + (size_t)(64 * cg + l15) * K + wave * kq + 8 * g;
; __global__ void __launch_bounds__(NTHREADS, 2) hybrid_fwd(Params P) {
;     ...
;             if (PH(7)) {
;                 PHASE_IDS
;                 WSB(X, float, WS_X) WSB(XB, bf16_t, WS_XB) WSB(SS, float, WS_SS) WSB(MIX, bf16_t, WS_MIX) WSB(WoutR, bf16_t, WS_WOUTR)
;                 pg8::EpiRes E{XB, SS};
;                 for (int blk = bid; blk < 256; blk += G) sample_out_block(lds, MIX, WoutR + (size_t)li * 2048 * 4096, 4096, XB, SS, blk, tid);
.Lprio_2:
.LBB0_538:
	v_readlane_b32 s6, v254, 0
	s_cmp_ge_i32 s62, s6
	v_readlane_b32 s7, v254, 1
	s_cselect_b64 s[18:19], -1, 0
	s_and_b64 s[6:7], s[18:19], s[8:9]
	s_andn2_b64 vcc, exec, s[6:7]
	s_cbranch_vccnz .LBB0_593
	v_readlane_b32 s8, v254, 40
	v_readlane_b32 s10, v254, 42
	v_readlane_b32 s11, v254, 43
	v_mov_b32_e32 v6, v139
	s_mov_b32 s31, s90
	s_mov_b64 s[6:7], s[10:11]
	s_mov_b64 s[6:7], s[10:11]
	s_add_u32 s20, s6, 0x11c00000
	s_addc_u32 s21, s7, 0
	s_mov_b64 s[6:7], s[10:11]
	s_add_u32 s22, s6, 0x13d00000
	s_addc_u32 s23, s7, 0
	s_mov_b64 s[6:7], s[10:11]
	s_add_u32 s24, s6, 0x20408000
	s_addc_u32 s25, s7, 0
	s_mov_b64 s[6:7], s[10:11]
	s_add_u32 s28, s6, 0x9a00000
	s_addc_u32 s29, s7, 0
	v_readlane_b32 s6, v254, 52
	s_lshl_b32 s30, s6, 23
	s_cmpk_gt_i32 s31, 0xff
	v_readlane_b32 s9, v254, 41
	v_readlane_b32 s7, v254, 53
	s_cbranch_scc1 .LBB0_551
	v_ashrrev_i32_e32 v8, 6, v6
	s_lshl_b32 s6, s30, 1
	v_lshlrev_b32_e32 v2, 9, v8
	s_add_u32 s6, s28, s6
	s_waitcnt lgkmcnt(0)
	v_ashrrev_i32_e32 v3, 31, v2
	s_addc_u32 s7, s29, 0
	v_lshlrev_b64 v[4:5], 1, v[2:3]
	v_lshl_add_u64 v[2:3], s[24:25], 0, v[4:5]
	v_and_b32_e32 v0, 48, v6
	v_lshl_add_u64 v[4:5], s[6:7], 0, v[4:5]
	v_lshl_add_u64 v[2:3], v[2:3], 0, v[0:1]
	v_lshl_add_u64 v[4:5], v[4:5], 0, v[0:1]
	v_lshrrev_b32_e32 v0, 2, v6
	v_and_b32_e32 v7, 63, v6
	v_and_b32_e32 v30, 15, v6
	v_and_b32_e32 v0, 12, v0
	v_lshlrev_b32_e32 v9, 13, v8
	v_lshl_add_u32 v10, v7, 4, 0
	v_lshlrev_b32_e32 v11, 12, v8
	v_lshl_or_b32 v31, v8, 4, v0
	v_lshlrev_b32_e32 v0, 1, v30
	v_cmp_gt_i32_e64 s[6:7], 2, v8
	v_lshl_add_u64 v[6:7], s[20:21], 0, v[0:1]
	v_cmp_eq_u32_e64 s[8:9], 0, v30
	v_add_u32_e32 v32, v10, v9
	v_add_u32_e32 v33, v10, v11
	s_mov_b32 s34, s31
	s_branch .LBB0_542

; #define PG8_STAGE(bufoff, gbase, voff) do { _Pragma("unroll") for (int _i = 0; _i < 2; ++_i) \
;         __builtin_amdgcn_global_load_lds((const unsigned*)((const char*)(gbase) + (voff)[_i]), (PG8_LAS unsigned*)(lds + (bufoff) + ldsw + _i * 8192), 16, 0, 0); } while (0)
; #define PG8_LDA(dst, b, h) do { _Pragma("unroll") for (int m = 0; m < 4; ++m) _Pragma("unroll") for (int k = 0; k < 2; ++k) dst[m][k] = *(const PG8_LAS bf16x8*)(lds + PG8_SA(b, h) + aoff + m * 2048 + k * 1024); } while (0)
; #define PG8_LDB(dst, b, h) do { _Pragma("unroll") for (int n = 0; n < 2; ++n) _Pragma("unroll") for (int k = 0; k < 2; ++k) dst[n][k] = *(const PG8_LAS bf16x8*)(lds + PG8_SB(b, h) + boff + n * 2048 + k * 1024); } while (0)
; #define PG8_MMA(ai, bj, At, Bt) do { __builtin_amdgcn_s_setprio(1); _Pragma("unroll") for (int m = 0; m < 4; ++m) _Pragma("unroll") for (int n = 0; n < 2; ++n) _Pragma("unroll") for (int k = 0; k < 2; ++k) \
;         acc[ai][bj][m][n] = __builtin_amdgcn_mfma_f32_16x16x32_bf16(Bt[n][k], At[m][k], acc[ai][bj][m][n], 0, 0, 0); __builtin_amdgcn_s_setprio(0); } while (0)
; #define PG8_WAIT_V(n) asm volatile("s_waitcnt vmcnt(" #n ")" ::: "memory")
; #define PG8_WAIT_L(n) asm volatile("s_waitcnt lgkmcnt(" #n ")" ::: "memory")
; #define PG8_BAR __builtin_amdgcn_s_barrier()
; #define PG8_SCHED __builtin_amdgcn_sched_barrier(0)
; template <class Epi, class Sched, bool ALIGN_EPI = false, bool SP2 = false>
; __device__ __forceinline__ void gemm_phase(PG8_LAS unsigned char* lds, const Gemm g, const Sched& S, const Epi& E) {
;     ...
;             PG8_LDB(B0, 0, 0); PG8_LDB(B1, 0, 1); PG8_SCHED; PG8_LDA(At, 0, 0); PG8_STAGE(PG8_SA(1, 1), a1 + hstep, voffA);
;             PG8_WAIT_V(8); PG8_WAIT_L(0); PG8_BAR; PG8_MMA(0, 0, At, B0); PG8_MMA(0, 1, At, B1); PG8_BAR; PG8_SCHED;
;             PG8_LDA(At, 0, 1); PG8_STAGE(PG8_SB(0, 0), b2, voffB); PG8_STAGE(PG8_SB(0, 1), b2 + hstep, voffB); PG8_STAGE(PG8_SA(0, 0), a2, voffA);
.LBB0_570:
	s_add_u32 s42, s40, 0x100
	s_addc_u32 s43, s41, 0
	s_add_i32 s72, 0, 0x10000
	s_cmp_eq_u32 s71, 60
	s_cselect_b32 s47, s29, s43
	s_cselect_b32 s46, s37, s42
	v_add_u32_e32 v136, s72, v192
	s_cselect_b32 s45, s27, s70
	s_cselect_b32 s44, s39, s69
	s_add_i32 s73, 0, 0x14000
	ds_read_b128 v[146:149], v136
	ds_read_b128 v[150:153], v136 offset:1024
	ds_read_b128 v[154:157], v136 offset:2048
	ds_read_b128 v[158:161], v136 offset:3072
	v_add_u32_e32 v136, s73, v192
	ds_read_b128 v[162:165], v136
	ds_read_b128 v[166:169], v136 offset:1024
	ds_read_b128 v[170:173], v136 offset:2048
	ds_read_b128 v[174:177], v136 offset:3072
	v_lshl_add_u64 v[136:137], s[40:41], 0, v[132:133]
	s_add_i32 m0, s52, 0xc000
	ds_read_b128 v[178:181], v194
	ds_read_b128 v[182:185], v194 offset:1024
	ds_read_b128 v[186:189], v194 offset:2048
	ds_read_b128 v[196:199], v194 offset:3072
	ds_read_b128 v[200:203], v194 offset:4096
	ds_read_b128 v[204:207], v194 offset:5120
	ds_read_b128 v[226:229], v194 offset:6144
	ds_read_b128 v[230:233], v194 offset:7168
	global_load_lds_dwordx4 v[136:137], off
	v_lshl_add_u64 v[136:137], s[40:41], 0, v[134:135]
	s_add_i32 m0, s52, 0xe000
	s_nop 0
	global_load_lds_dwordx4 v[136:137], off
	s_waitcnt vmcnt(8)
	s_waitcnt lgkmcnt(0)
	s_barrier
	s_waitcnt lgkmcnt(0)
	v_mfma_f32_16x16x32_bf16 v[126:129], v[146:149], v[178:181], v[126:129]
	v_mfma_f32_16x16x32_bf16 v[122:125], v[154:157], v[178:181], v[122:125]
	v_mfma_f32_16x16x32_bf16 v[110:113], v[146:149], v[186:189], v[110:113]
	v_mfma_f32_16x16x32_bf16 v[106:109], v[154:157], v[186:189], v[106:109]
	v_mfma_f32_16x16x32_bf16 v[94:97], v[146:149], v[200:203], v[94:97]
	v_mfma_f32_16x16x32_bf16 v[90:93], v[154:157], v[200:203], v[90:93]
	v_mfma_f32_16x16x32_bf16 v[78:81], v[146:149], v[226:229], v[78:81]
	v_mfma_f32_16x16x32_bf16 v[74:77], v[154:157], v[226:229], v[74:77]
	v_mfma_f32_16x16x32_bf16 v[126:129], v[150:153], v[182:185], v[126:129]
	v_mfma_f32_16x16x32_bf16 v[122:125], v[158:161], v[182:185], v[122:125]
	v_mfma_f32_16x16x32_bf16 v[110:113], v[150:153], v[196:199], v[110:113]
	v_mfma_f32_16x16x32_bf16 v[106:109], v[158:161], v[196:199], v[106:109]
	v_mfma_f32_16x16x32_bf16 v[94:97], v[150:153], v[204:207], v[94:97]
	v_mfma_f32_16x16x32_bf16 v[90:93], v[158:161], v[204:207], v[90:93]
	v_mfma_f32_16x16x32_bf16 v[78:81], v[150:153], v[230:233], v[78:81]
	v_mfma_f32_16x16x32_bf16 v[74:77], v[158:161], v[230:233], v[74:77]
	v_mfma_f32_16x16x32_bf16 v[118:121], v[162:165], v[178:181], v[118:121]
	v_mfma_f32_16x16x32_bf16 v[114:117], v[170:173], v[178:181], v[114:117]
	v_mfma_f32_16x16x32_bf16 v[102:105], v[162:165], v[186:189], v[102:105]
	v_mfma_f32_16x16x32_bf16 v[98:101], v[170:173], v[186:189], v[98:101]
	v_mfma_f32_16x16x32_bf16 v[86:89], v[162:165], v[200:203], v[86:89]
	v_mfma_f32_16x16x32_bf16 v[82:85], v[170:173], v[200:203], v[82:85]
	v_mfma_f32_16x16x32_bf16 v[70:73], v[162:165], v[226:229], v[70:73]
	v_mfma_f32_16x16x32_bf16 v[66:69], v[170:173], v[226:229], v[66:69]
	v_mfma_f32_16x16x32_bf16 v[118:121], v[166:169], v[182:185], v[118:121]
	v_mfma_f32_16x16x32_bf16 v[114:117], v[174:177], v[182:185], v[114:117]
	v_mfma_f32_16x16x32_bf16 v[102:105], v[166:169], v[196:199], v[102:105]
	v_mfma_f32_16x16x32_bf16 v[98:101], v[174:177], v[196:199], v[98:101]
	v_mfma_f32_16x16x32_bf16 v[86:89], v[166:169], v[204:207], v[86:89]
	v_mfma_f32_16x16x32_bf16 v[82:85], v[174:177], v[204:207], v[82:85]
	v_mfma_f32_16x16x32_bf16 v[70:73], v[166:169], v[230:233], v[70:73]
	v_mfma_f32_16x16x32_bf16 v[66:69], v[174:177], v[230:233], v[66:69]
	s_barrier
	s_add_i32 s40, s72, s51
	v_lshl_add_u64 v[136:137], s[44:45], 0, v[0:1]
	s_mov_b32 m0, s40
	ds_read_b128 v[178:181], v194 offset:16384
	ds_read_b128 v[182:185], v194 offset:17408
	ds_read_b128 v[186:189], v194 offset:18432
	ds_read_b128 v[196:199], v194 offset:19456
	ds_read_b128 v[200:203], v194 offset:20480
	ds_read_b128 v[204:207], v194 offset:21504
	ds_read_b128 v[226:229], v194 offset:22528
	ds_read_b128 v[230:233], v194 offset:23552
	global_load_lds_dwordx4 v[136:137], off
	s_add_i32 m0, s40, 0x2000
	s_add_u32 s40, s44, 0x100000
	v_lshl_add_u64 v[190:191], s[44:45], 0, v[130:131]
	s_addc_u32 s41, s45, 0
	s_add_i32 s72, s73, s51
	global_load_lds_dwordx4 v[190:191], off
	v_lshl_add_u64 v[208:209], s[40:41], 0, v[0:1]
	s_mov_b32 m0, s72
	v_lshl_add_u64 v[234:235], s[46:47], 0, v[130:131]
	global_load_lds_dwordx4 v[208:209], off
	v_lshl_add_u64 v[208:209], s[40:41], 0, v[130:131]
	s_add_i32 m0, s72, 0x2000
	s_nop 0
	global_load_lds_dwordx4 v[208:209], off
	v_lshl_add_u64 v[208:209], s[46:47], 0, v[0:1]
	s_mov_b32 m0, s52
	s_nop 0
	global_load_lds_dwordx4 v[208:209], off
	s_mov_b32 m0, s53
	s_nop 0
	global_load_lds_dwordx4 v[234:235], off
	s_waitcnt vmcnt(8)
	s_waitcnt lgkmcnt(0)
	s_barrier
; #define PG8_STAGE(bufoff, gbase, voff) do { _Pragma("unroll") for (int _i = 0; _i < 2; ++_i) \
;         __builtin_amdgcn_global_load_lds((const unsigned*)((const char*)(gbase) + (voff)[_i]), (PG8_LAS unsigned*)(lds + (bufoff) + ldsw + _i * 8192), 16, 0, 0); } while (0)
; #define PG8_LDA(dst, b, h) do { _Pragma("unroll") for (int m = 0; m < 4; ++m) _Pragma("unroll") for (int k = 0; k < 2; ++k) dst[m][k] = *(const PG8_LAS bf16x8*)(lds + PG8_SA(b, h) + aoff + m * 2048 + k * 1024); } while (0)
; #define PG8_LDB(dst, b, h) do { _Pragma("unroll") for (int n = 0; n < 2; ++n) _Pragma("unroll") for (int k = 0; k < 2; ++k) dst[n][k] = *(const PG8_LAS bf16x8*)(lds + PG8_SB(b, h) + boff + n * 2048 + k * 1024); } while (0)
; #define PG8_MMA(ai, bj, At, Bt) do { __builtin_amdgcn_s_setprio(1); _Pragma("unroll") for (int m = 0; m < 4; ++m) _Pragma("unroll") for (int n = 0; n < 2; ++n) _Pragma("unroll") for (int k = 0; k < 2; ++k) \
;         acc[ai][bj][m][n] = __builtin_amdgcn_mfma_f32_16x16x32_bf16(Bt[n][k], At[m][k], acc[ai][bj][m][n], 0, 0, 0); __builtin_amdgcn_s_setprio(0); } while (0)
; #define PG8_WAIT_V(n) asm volatile("s_waitcnt vmcnt(" #n ")" ::: "memory")
; #define PG8_WAIT_L(n) asm volatile("s_waitcnt lgkmcnt(" #n ")" ::: "memory")
; #define PG8_BAR __builtin_amdgcn_s_barrier()
; #define PG8_SCHED __builtin_amdgcn_sched_barrier(0)
; template <class Epi, class Sched, bool ALIGN_EPI = false, bool SP2 = false>
; __device__ __forceinline__ void gemm_phase(PG8_LAS unsigned char* lds, const Gemm g, const Sched& S, const Epi& E) {
;     ...
;             PG8_WAIT_V(8); PG8_WAIT_L(0); PG8_BAR; PG8_MMA(1, 0, At, B0); PG8_MMA(1, 1, At, B1); PG8_BAR; PG8_SCHED;
;             PG8_LDB(B0, 1, 0); PG8_LDB(B1, 1, 1); PG8_SCHED; PG8_LDA(At, 1, 0); PG8_STAGE(PG8_SA(0, 1), a2 + hstep, voffA);
;             PG8_WAIT_V(8); PG8_WAIT_L(0); PG8_BAR; PG8_MMA(0, 0, At, B0); PG8_MMA(0, 1, At, B1); PG8_BAR; PG8_SCHED;
	s_waitcnt lgkmcnt(0)
	v_mfma_f32_16x16x32_bf16 v[62:65], v[146:149], v[178:181], v[62:65]
	v_mfma_f32_16x16x32_bf16 v[58:61], v[154:157], v[178:181], v[58:61]
	v_mfma_f32_16x16x32_bf16 v[46:49], v[146:149], v[186:189], v[46:49]
	v_mfma_f32_16x16x32_bf16 v[42:45], v[154:157], v[186:189], v[42:45]
	v_mfma_f32_16x16x32_bf16 v[30:33], v[146:149], v[200:203], v[30:33]
	v_mfma_f32_16x16x32_bf16 v[26:29], v[154:157], v[200:203], v[26:29]
	v_mfma_f32_16x16x32_bf16 v[14:17], v[146:149], v[226:229], v[14:17]
	v_mfma_f32_16x16x32_bf16 v[10:13], v[154:157], v[226:229], v[10:13]
	v_mfma_f32_16x16x32_bf16 v[62:65], v[150:153], v[182:185], v[62:65]
	v_mfma_f32_16x16x32_bf16 v[58:61], v[158:161], v[182:185], v[58:61]
	v_mfma_f32_16x16x32_bf16 v[46:49], v[150:153], v[196:199], v[46:49]
	v_mfma_f32_16x16x32_bf16 v[42:45], v[158:161], v[196:199], v[42:45]
	v_mfma_f32_16x16x32_bf16 v[30:33], v[150:153], v[204:207], v[30:33]
	v_mfma_f32_16x16x32_bf16 v[26:29], v[158:161], v[204:207], v[26:29]
	v_mfma_f32_16x16x32_bf16 v[14:17], v[150:153], v[230:233], v[14:17]
	v_mfma_f32_16x16x32_bf16 v[10:13], v[158:161], v[230:233], v[10:13]
	v_mfma_f32_16x16x32_bf16 v[54:57], v[162:165], v[178:181], v[54:57]
	v_mfma_f32_16x16x32_bf16 v[50:53], v[170:173], v[178:181], v[50:53]
	v_mfma_f32_16x16x32_bf16 v[38:41], v[162:165], v[186:189], v[38:41]
	v_mfma_f32_16x16x32_bf16 v[34:37], v[170:173], v[186:189], v[34:37]
	v_mfma_f32_16x16x32_bf16 v[22:25], v[162:165], v[200:203], v[22:25]
	v_mfma_f32_16x16x32_bf16 v[18:21], v[170:173], v[200:203], v[18:21]
	v_mfma_f32_16x16x32_bf16 v[6:9], v[162:165], v[226:229], v[6:9]
	v_mfma_f32_16x16x32_bf16 v[2:5], v[170:173], v[226:229], v[2:5]
	v_mfma_f32_16x16x32_bf16 v[54:57], v[166:169], v[182:185], v[54:57]
	v_mfma_f32_16x16x32_bf16 v[50:53], v[174:177], v[182:185], v[50:53]
	v_mfma_f32_16x16x32_bf16 v[38:41], v[166:169], v[196:199], v[38:41]
	v_mfma_f32_16x16x32_bf16 v[34:37], v[174:177], v[196:199], v[34:37]
	v_mfma_f32_16x16x32_bf16 v[22:25], v[166:169], v[204:207], v[22:25]
	v_mfma_f32_16x16x32_bf16 v[18:21], v[174:177], v[204:207], v[18:21]
	v_mfma_f32_16x16x32_bf16 v[6:9], v[166:169], v[230:233], v[6:9]
	v_mfma_f32_16x16x32_bf16 v[2:5], v[174:177], v[230:233], v[2:5]
	s_barrier
	s_add_i32 s72, 0, 0x18000
	s_add_i32 s73, 0, 0x1c000
	v_add_u32_e32 v158, s72, v192
	v_add_u32_e32 v174, s73, v192
	ds_read_b128 v[146:149], v158
	ds_read_b128 v[150:153], v158 offset:1024
	ds_read_b128 v[154:157], v158 offset:2048
	ds_read_b128 v[158:161], v158 offset:3072
	ds_read_b128 v[162:165], v174
	ds_read_b128 v[166:169], v174 offset:1024
	ds_read_b128 v[170:173], v174 offset:2048
	ds_read_b128 v[174:177], v174 offset:3072
	s_add_u32 s40, s46, 0x100000
	s_addc_u32 s41, s47, 0
	s_mov_b32 m0, s54
	v_lshl_add_u64 v[236:237], s[40:41], 0, v[0:1]
	ds_read_b128 v[178:181], v194 offset:32768
	ds_read_b128 v[182:185], v194 offset:33792
	ds_read_b128 v[186:189], v194 offset:34816
	ds_read_b128 v[196:199], v194 offset:35840
	ds_read_b128 v[200:203], v194 offset:36864
	ds_read_b128 v[204:207], v194 offset:37888
	ds_read_b128 v[226:229], v194 offset:38912
	ds_read_b128 v[230:233], v194 offset:39936
	global_load_lds_dwordx4 v[236:237], off
	v_lshl_add_u64 v[236:237], s[40:41], 0, v[130:131]
	s_mov_b32 m0, s55
	s_nop 0
	global_load_lds_dwordx4 v[236:237], off
	s_waitcnt vmcnt(8)
	s_waitcnt lgkmcnt(0)
	s_barrier
	s_waitcnt lgkmcnt(0)
	v_mfma_f32_16x16x32_bf16 v[126:129], v[146:149], v[178:181], v[126:129]
	v_mfma_f32_16x16x32_bf16 v[122:125], v[154:157], v[178:181], v[122:125]
	v_mfma_f32_16x16x32_bf16 v[110:113], v[146:149], v[186:189], v[110:113]
	v_mfma_f32_16x16x32_bf16 v[106:109], v[154:157], v[186:189], v[106:109]
	v_mfma_f32_16x16x32_bf16 v[94:97], v[146:149], v[200:203], v[94:97]
	v_mfma_f32_16x16x32_bf16 v[90:93], v[154:157], v[200:203], v[90:93]
	v_mfma_f32_16x16x32_bf16 v[78:81], v[146:149], v[226:229], v[78:81]
	v_mfma_f32_16x16x32_bf16 v[74:77], v[154:157], v[226:229], v[74:77]
	v_mfma_f32_16x16x32_bf16 v[126:129], v[150:153], v[182:185], v[126:129]
	v_mfma_f32_16x16x32_bf16 v[122:125], v[158:161], v[182:185], v[122:125]
	v_mfma_f32_16x16x32_bf16 v[110:113], v[150:153], v[196:199], v[110:113]
	v_mfma_f32_16x16x32_bf16 v[106:109], v[158:161], v[196:199], v[106:109]
	v_mfma_f32_16x16x32_bf16 v[94:97], v[150:153], v[204:207], v[94:97]
	v_mfma_f32_16x16x32_bf16 v[90:93], v[158:161], v[204:207], v[90:93]
	v_mfma_f32_16x16x32_bf16 v[78:81], v[150:153], v[230:233], v[78:81]
	v_mfma_f32_16x16x32_bf16 v[74:77], v[158:161], v[230:233], v[74:77]
	v_mfma_f32_16x16x32_bf16 v[118:121], v[162:165], v[178:181], v[118:121]
	v_mfma_f32_16x16x32_bf16 v[114:117], v[170:173], v[178:181], v[114:117]
	v_mfma_f32_16x16x32_bf16 v[102:105], v[162:165], v[186:189], v[102:105]
	v_mfma_f32_16x16x32_bf16 v[98:101], v[170:173], v[186:189], v[98:101]
	v_mfma_f32_16x16x32_bf16 v[86:89], v[162:165], v[200:203], v[86:89]
	v_mfma_f32_16x16x32_bf16 v[82:85], v[170:173], v[200:203], v[82:85]
	v_mfma_f32_16x16x32_bf16 v[70:73], v[162:165], v[226:229], v[70:73]
	v_mfma_f32_16x16x32_bf16 v[66:69], v[170:173], v[226:229], v[66:69]
	v_mfma_f32_16x16x32_bf16 v[118:121], v[166:169], v[182:185], v[118:121]
	v_mfma_f32_16x16x32_bf16 v[114:117], v[174:177], v[182:185], v[114:117]
	v_mfma_f32_16x16x32_bf16 v[102:105], v[166:169], v[196:199], v[102:105]
	v_mfma_f32_16x16x32_bf16 v[98:101], v[174:177], v[196:199], v[98:101]
	v_mfma_f32_16x16x32_bf16 v[86:89], v[166:169], v[204:207], v[86:89]
	v_mfma_f32_16x16x32_bf16 v[82:85], v[174:177], v[204:207], v[82:85]
	v_mfma_f32_16x16x32_bf16 v[70:73], v[166:169], v[230:233], v[70:73]
	v_mfma_f32_16x16x32_bf16 v[66:69], v[174:177], v[230:233], v[66:69]
	s_barrier
; #define PG8_STAGE(bufoff, gbase, voff) do { _Pragma("unroll") for (int _i = 0; _i < 2; ++_i) \
;         __builtin_amdgcn_global_load_lds((const unsigned*)((const char*)(gbase) + (voff)[_i]), (PG8_LAS unsigned*)(lds + (bufoff) + ldsw + _i * 8192), 16, 0, 0); } while (0)
; #define PG8_LDA(dst, b, h) do { _Pragma("unroll") for (int m = 0; m < 4; ++m) _Pragma("unroll") for (int k = 0; k < 2; ++k) dst[m][k] = *(const PG8_LAS bf16x8*)(lds + PG8_SA(b, h) + aoff + m * 2048 + k * 1024); } while (0)
; #define PG8_MMA(ai, bj, At, Bt) do { __builtin_amdgcn_s_setprio(1); _Pragma("unroll") for (int m = 0; m < 4; ++m) _Pragma("unroll") for (int n = 0; n < 2; ++n) _Pragma("unroll") for (int k = 0; k < 2; ++k) \
;         acc[ai][bj][m][n] = __builtin_amdgcn_mfma_f32_16x16x32_bf16(Bt[n][k], At[m][k], acc[ai][bj][m][n], 0, 0, 0); __builtin_amdgcn_s_setprio(0); } while (0)
; #define PG8_WAIT_V(n) asm volatile("s_waitcnt vmcnt(" #n ")" ::: "memory")
; #define PG8_WAIT_L(n) asm volatile("s_waitcnt lgkmcnt(" #n ")" ::: "memory")
; #define PG8_BAR __builtin_amdgcn_s_barrier()
; #define PG8_SCHED __builtin_amdgcn_sched_barrier(0)
; template <class Epi, class Sched, bool ALIGN_EPI = false, bool SP2 = false>
; __device__ __forceinline__ void gemm_phase(PG8_LAS unsigned char* lds, const Gemm g, const Sched& S, const Epi& E) {
;     ...
;             PG8_LDA(At, 1, 1); PG8_STAGE(PG8_SB(1, 0), b3, voffB); PG8_STAGE(PG8_SB(1, 1), b3 + hstep, voffB); PG8_STAGE(PG8_SA(1, 0), a3, voffA);
;             PG8_WAIT_V(8); PG8_WAIT_L(0); PG8_BAR; PG8_MMA(1, 0, At, B0); PG8_MMA(1, 1, At, B1); PG8_BAR; PG8_SCHED;
	s_add_i32 s40, s72, s51
	v_lshl_add_u64 v[136:137], v[136:137], 0, s[0:1]
	s_mov_b32 m0, s40
	ds_read_b128 v[178:181], v194 offset:49152
	ds_read_b128 v[182:185], v194 offset:50176
	ds_read_b128 v[186:189], v194 offset:51200
	ds_read_b128 v[196:199], v194 offset:52224
	ds_read_b128 v[200:203], v194 offset:53248
	ds_read_b128 v[204:207], v194 offset:54272
	ds_read_b128 v[226:229], v194 offset:55296
	ds_read_b128 v[230:233], v194 offset:56320
	global_load_lds_dwordx4 v[136:137], off
	s_add_i32 m0, s40, 0x2000
	s_add_u32 s40, s44, 0x100080
	v_lshl_add_u64 v[136:137], v[190:191], 0, s[0:1]
	s_addc_u32 s41, s45, 0
	s_add_i32 s44, s73, s51
	global_load_lds_dwordx4 v[136:137], off
	v_lshl_add_u64 v[136:137], s[40:41], 0, v[0:1]
	s_mov_b32 m0, s44
	s_nop 0
	global_load_lds_dwordx4 v[136:137], off
	v_lshl_add_u64 v[136:137], s[40:41], 0, v[130:131]
	s_add_i32 m0, s44, 0x2000
	s_nop 0
	global_load_lds_dwordx4 v[136:137], off
	v_lshl_add_u64 v[136:137], v[208:209], 0, s[0:1]
	s_mov_b32 m0, s57
	s_nop 0
	global_load_lds_dwordx4 v[136:137], off
	v_lshl_add_u64 v[136:137], v[234:235], 0, s[0:1]
	s_mov_b32 m0, s62
	s_nop 0
	global_load_lds_dwordx4 v[136:137], off
	s_waitcnt vmcnt(8)
	s_waitcnt lgkmcnt(0)
	s_barrier
	s_waitcnt lgkmcnt(0)
	v_mfma_f32_16x16x32_bf16 v[62:65], v[146:149], v[178:181], v[62:65]
	v_mfma_f32_16x16x32_bf16 v[58:61], v[154:157], v[178:181], v[58:61]
	v_mfma_f32_16x16x32_bf16 v[46:49], v[146:149], v[186:189], v[46:49]
	v_mfma_f32_16x16x32_bf16 v[42:45], v[154:157], v[186:189], v[42:45]
	v_mfma_f32_16x16x32_bf16 v[30:33], v[146:149], v[200:203], v[30:33]
	v_mfma_f32_16x16x32_bf16 v[26:29], v[154:157], v[200:203], v[26:29]
	v_mfma_f32_16x16x32_bf16 v[14:17], v[146:149], v[226:229], v[14:17]
	v_mfma_f32_16x16x32_bf16 v[10:13], v[154:157], v[226:229], v[10:13]
	v_mfma_f32_16x16x32_bf16 v[62:65], v[150:153], v[182:185], v[62:65]
	v_mfma_f32_16x16x32_bf16 v[58:61], v[158:161], v[182:185], v[58:61]
	v_mfma_f32_16x16x32_bf16 v[46:49], v[150:153], v[196:199], v[46:49]
	v_mfma_f32_16x16x32_bf16 v[42:45], v[158:161], v[196:199], v[42:45]
	v_mfma_f32_16x16x32_bf16 v[30:33], v[150:153], v[204:207], v[30:33]
	v_mfma_f32_16x16x32_bf16 v[26:29], v[158:161], v[204:207], v[26:29]
	v_mfma_f32_16x16x32_bf16 v[14:17], v[150:153], v[230:233], v[14:17]
	v_mfma_f32_16x16x32_bf16 v[10:13], v[158:161], v[230:233], v[10:13]
	v_mfma_f32_16x16x32_bf16 v[54:57], v[162:165], v[178:181], v[54:57]
	v_mfma_f32_16x16x32_bf16 v[50:53], v[170:173], v[178:181], v[50:53]
	v_mfma_f32_16x16x32_bf16 v[38:41], v[162:165], v[186:189], v[38:41]
	v_mfma_f32_16x16x32_bf16 v[34:37], v[170:173], v[186:189], v[34:37]
	v_mfma_f32_16x16x32_bf16 v[22:25], v[162:165], v[200:203], v[22:25]
	v_mfma_f32_16x16x32_bf16 v[18:21], v[170:173], v[200:203], v[18:21]
	v_mfma_f32_16x16x32_bf16 v[6:9], v[162:165], v[226:229], v[6:9]
	v_mfma_f32_16x16x32_bf16 v[2:5], v[170:173], v[226:229], v[2:5]
	v_mfma_f32_16x16x32_bf16 v[54:57], v[166:169], v[182:185], v[54:57]
	v_mfma_f32_16x16x32_bf16 v[50:53], v[174:177], v[182:185], v[50:53]
	v_mfma_f32_16x16x32_bf16 v[38:41], v[166:169], v[196:199], v[38:41]
	v_mfma_f32_16x16x32_bf16 v[34:37], v[174:177], v[196:199], v[34:37]
	v_mfma_f32_16x16x32_bf16 v[22:25], v[166:169], v[204:207], v[22:25]
	v_mfma_f32_16x16x32_bf16 v[18:21], v[174:177], v[204:207], v[18:21]
	v_mfma_f32_16x16x32_bf16 v[6:9], v[166:169], v[230:233], v[6:9]
	v_mfma_f32_16x16x32_bf16 v[2:5], v[174:177], v[230:233], v[2:5]
	s_barrier
	s_add_i32 s71, s71, 2
	s_add_u32 s69, s69, 0x100
	s_addc_u32 s70, s70, 0
	s_cmp_gt_u32 s71, 61
	s_mov_b64 s[40:41], s[42:43]
	s_cbranch_scc0 .LBB0_570
	s_and_b64 vcc, exec, s[12:13]
	s_cbranch_vccz .LBB0_573
	s_barrier

; #define PG8_STAGE(bufoff, gbase, voff) do { _Pragma("unroll") for (int _i = 0; _i < 2; ++_i) \
;         __builtin_amdgcn_global_load_lds((const unsigned*)((const char*)(gbase) + (voff)[_i]), (PG8_LAS unsigned*)(lds + (bufoff) + ldsw + _i * 8192), 16, 0, 0); } while (0)
; #define PG8_LDA(dst, b, h) do { _Pragma("unroll") for (int m = 0; m < 4; ++m) _Pragma("unroll") for (int k = 0; k < 2; ++k) dst[m][k] = *(const PG8_LAS bf16x8*)(lds + PG8_SA(b, h) + aoff + m * 2048 + k * 1024); } while (0)
; #define PG8_LDB(dst, b, h) do { _Pragma("unroll") for (int n = 0; n < 2; ++n) _Pragma("unroll") for (int k = 0; k < 2; ++k) dst[n][k] = *(const PG8_LAS bf16x8*)(lds + PG8_SB(b, h) + boff + n * 2048 + k * 1024); } while (0)
; #define PG8_MMA(ai, bj, At, Bt) do { __builtin_amdgcn_s_setprio(1); _Pragma("unroll") for (int m = 0; m < 4; ++m) _Pragma("unroll") for (int n = 0; n < 2; ++n) _Pragma("unroll") for (int k = 0; k < 2; ++k) \
;         acc[ai][bj][m][n] = __builtin_amdgcn_mfma_f32_16x16x32_bf16(Bt[n][k], At[m][k], acc[ai][bj][m][n], 0, 0, 0); __builtin_amdgcn_s_setprio(0); } while (0)
; #define PG8_WAIT_V(n) asm volatile("s_waitcnt vmcnt(" #n ")" ::: "memory")
; #define PG8_WAIT_L(n) asm volatile("s_waitcnt lgkmcnt(" #n ")" ::: "memory")
; #define PG8_BAR __builtin_amdgcn_s_barrier()
; #define PG8_SCHED __builtin_amdgcn_sched_barrier(0)
; template <class Epi, class Sched, bool ALIGN_EPI = false, bool SP2 = false>
; __device__ __forceinline__ void gemm_phase(PG8_LAS unsigned char* lds, const Gemm g, const Sched& S, const Epi& E) {
;     ...
;             PG8_LDB(B0, 0, 0); PG8_LDB(B1, 0, 1); PG8_SCHED; PG8_LDA(At, 0, 0); PG8_STAGE(PG8_SA(1, 1), a1 + hstep, voffA);
;             PG8_WAIT_V(8); PG8_WAIT_L(0); PG8_BAR; PG8_MMA(0, 0, At, B0); PG8_MMA(0, 1, At, B1); PG8_BAR; PG8_SCHED;
;             PG8_LDA(At, 0, 1); PG8_STAGE(PG8_SB(0, 0), b2, voffB); PG8_STAGE(PG8_SB(0, 1), b2 + hstep, voffB); PG8_STAGE(PG8_SA(0, 0), a2, voffA);
.LBB0_668:
	s_add_u32 s10, s8, 0xfff80080
	s_addc_u32 s11, s9, -1
	s_add_i32 s53, 0, 0x10000
	s_cmp_eq_u32 s52, 28
	s_cselect_b32 s35, s7, s11
	s_cselect_b32 s34, s27, s10
	s_cselect_b32 s11, s25, s51
	s_cselect_b32 s10, s36, s37
	s_add_i32 s56, 0, 0x14000
	v_add_u32_e32 v164, s53, v192
	v_add_u32_e32 v180, s56, v192
	ds_read_b128 v[130:133], v164
	ds_read_b128 v[134:137], v164 offset:1024
	ds_read_b128 v[160:163], v164 offset:2048
	ds_read_b128 v[164:167], v164 offset:3072
	ds_read_b128 v[168:171], v180
	ds_read_b128 v[172:175], v180 offset:1024
	ds_read_b128 v[176:179], v180 offset:2048
	ds_read_b128 v[180:183], v180 offset:3072
	v_lshl_add_u64 v[208:209], s[8:9], 0, v[156:157]
	s_add_i32 m0, s23, 0xc000
	ds_read_b128 v[184:187], v194
	ds_read_b128 v[188:191], v194 offset:1024
	ds_read_b128 v[196:199], v194 offset:2048
	ds_read_b128 v[200:203], v194 offset:3072
	ds_read_b128 v[204:207], v194 offset:4096
	ds_read_b128 v[226:229], v194 offset:5120
	ds_read_b128 v[230:233], v194 offset:6144
	ds_read_b128 v[234:237], v194 offset:7168
	global_load_lds_dwordx4 v[208:209], off
	v_lshl_add_u64 v[208:209], s[8:9], 0, v[158:159]
	s_add_i32 m0, s23, 0xe000
	s_nop 0
	global_load_lds_dwordx4 v[208:209], off
	s_waitcnt vmcnt(8)
	s_waitcnt lgkmcnt(0)
	s_barrier
	s_waitcnt lgkmcnt(0)
	v_mfma_f32_16x16x32_bf16 v[126:129], v[130:133], v[184:187], v[126:129]
	v_mfma_f32_16x16x32_bf16 v[122:125], v[160:163], v[184:187], v[122:125]
	v_mfma_f32_16x16x32_bf16 v[110:113], v[130:133], v[196:199], v[110:113]
	v_mfma_f32_16x16x32_bf16 v[106:109], v[160:163], v[196:199], v[106:109]
	v_mfma_f32_16x16x32_bf16 v[94:97], v[130:133], v[204:207], v[94:97]
	v_mfma_f32_16x16x32_bf16 v[90:93], v[160:163], v[204:207], v[90:93]
	v_mfma_f32_16x16x32_bf16 v[78:81], v[130:133], v[230:233], v[78:81]
	v_mfma_f32_16x16x32_bf16 v[74:77], v[160:163], v[230:233], v[74:77]
	v_mfma_f32_16x16x32_bf16 v[126:129], v[134:137], v[188:191], v[126:129]
	v_mfma_f32_16x16x32_bf16 v[122:125], v[164:167], v[188:191], v[122:125]
	v_mfma_f32_16x16x32_bf16 v[110:113], v[134:137], v[200:203], v[110:113]
	v_mfma_f32_16x16x32_bf16 v[106:109], v[164:167], v[200:203], v[106:109]
	v_mfma_f32_16x16x32_bf16 v[94:97], v[134:137], v[226:229], v[94:97]
	v_mfma_f32_16x16x32_bf16 v[90:93], v[164:167], v[226:229], v[90:93]
	v_mfma_f32_16x16x32_bf16 v[78:81], v[134:137], v[234:237], v[78:81]
	v_mfma_f32_16x16x32_bf16 v[74:77], v[164:167], v[234:237], v[74:77]
	v_mfma_f32_16x16x32_bf16 v[118:121], v[168:171], v[184:187], v[118:121]
	v_mfma_f32_16x16x32_bf16 v[114:117], v[176:179], v[184:187], v[114:117]
	v_mfma_f32_16x16x32_bf16 v[102:105], v[168:171], v[196:199], v[102:105]
	v_mfma_f32_16x16x32_bf16 v[98:101], v[176:179], v[196:199], v[98:101]
	v_mfma_f32_16x16x32_bf16 v[86:89], v[168:171], v[204:207], v[86:89]
	v_mfma_f32_16x16x32_bf16 v[82:85], v[176:179], v[204:207], v[82:85]
	v_mfma_f32_16x16x32_bf16 v[70:73], v[168:171], v[230:233], v[70:73]
	v_mfma_f32_16x16x32_bf16 v[66:69], v[176:179], v[230:233], v[66:69]
	v_mfma_f32_16x16x32_bf16 v[118:121], v[172:175], v[188:191], v[118:121]
	v_mfma_f32_16x16x32_bf16 v[114:117], v[180:183], v[188:191], v[114:117]
	v_mfma_f32_16x16x32_bf16 v[102:105], v[172:175], v[200:203], v[102:105]
	v_mfma_f32_16x16x32_bf16 v[98:101], v[180:183], v[200:203], v[98:101]
	v_mfma_f32_16x16x32_bf16 v[86:89], v[172:175], v[226:229], v[86:89]
	v_mfma_f32_16x16x32_bf16 v[82:85], v[180:183], v[226:229], v[82:85]
	v_mfma_f32_16x16x32_bf16 v[70:73], v[172:175], v[234:237], v[70:73]
	v_mfma_f32_16x16x32_bf16 v[66:69], v[180:183], v[234:237], v[66:69]
	s_barrier
	s_add_i32 s53, s53, s43
	v_lshl_add_u64 v[208:209], s[10:11], 0, v[0:1]
	s_mov_b32 m0, s53
	ds_read_b128 v[184:187], v194 offset:16384
	ds_read_b128 v[188:191], v194 offset:17408
	ds_read_b128 v[196:199], v194 offset:18432
	ds_read_b128 v[200:203], v194 offset:19456
	ds_read_b128 v[204:207], v194 offset:20480
	ds_read_b128 v[226:229], v194 offset:21504
	ds_read_b128 v[230:233], v194 offset:22528
	ds_read_b128 v[234:237], v194 offset:23552
	global_load_lds_dwordx4 v[208:209], off
	s_add_i32 m0, s53, 0x2000
	s_add_u32 s54, s10, 0x80000
	v_lshl_add_u64 v[238:239], s[10:11], 0, v[150:151]
	s_addc_u32 s55, s11, 0
	s_add_i32 s53, s56, s43
	global_load_lds_dwordx4 v[238:239], off
	v_lshl_add_u64 v[240:241], s[54:55], 0, v[0:1]
	s_mov_b32 m0, s53
	v_lshl_add_u64 v[242:243], s[34:35], 0, v[148:149]
	global_load_lds_dwordx4 v[240:241], off
	v_lshl_add_u64 v[240:241], s[54:55], 0, v[150:151]
	s_add_i32 m0, s53, 0x2000
	s_nop 0
	global_load_lds_dwordx4 v[240:241], off
	v_lshl_add_u64 v[240:241], s[34:35], 0, v[146:147]
	s_mov_b32 m0, s23
	s_nop 0
	global_load_lds_dwordx4 v[240:241], off
	s_mov_b32 m0, s44
	s_nop 0
	global_load_lds_dwordx4 v[242:243], off
	s_waitcnt vmcnt(8)
	s_waitcnt lgkmcnt(0)
	s_barrier
; #define PG8_STAGE(bufoff, gbase, voff) do { _Pragma("unroll") for (int _i = 0; _i < 2; ++_i) \
;         __builtin_amdgcn_global_load_lds((const unsigned*)((const char*)(gbase) + (voff)[_i]), (PG8_LAS unsigned*)(lds + (bufoff) + ldsw + _i * 8192), 16, 0, 0); } while (0)
; #define PG8_LDA(dst, b, h) do { _Pragma("unroll") for (int m = 0; m < 4; ++m) _Pragma("unroll") for (int k = 0; k < 2; ++k) dst[m][k] = *(const PG8_LAS bf16x8*)(lds + PG8_SA(b, h) + aoff + m * 2048 + k * 1024); } while (0)
; #define PG8_LDB(dst, b, h) do { _Pragma("unroll") for (int n = 0; n < 2; ++n) _Pragma("unroll") for (int k = 0; k < 2; ++k) dst[n][k] = *(const PG8_LAS bf16x8*)(lds + PG8_SB(b, h) + boff + n * 2048 + k * 1024); } while (0)
; #define PG8_MMA(ai, bj, At, Bt) do { __builtin_amdgcn_s_setprio(1); _Pragma("unroll") for (int m = 0; m < 4; ++m) _Pragma("unroll") for (int n = 0; n < 2; ++n) _Pragma("unroll") for (int k = 0; k < 2; ++k) \
;         acc[ai][bj][m][n] = __builtin_amdgcn_mfma_f32_16x16x32_bf16(Bt[n][k], At[m][k], acc[ai][bj][m][n], 0, 0, 0); __builtin_amdgcn_s_setprio(0); } while (0)
; #define PG8_WAIT_V(n) asm volatile("s_waitcnt vmcnt(" #n ")" ::: "memory")
; #define PG8_WAIT_L(n) asm volatile("s_waitcnt lgkmcnt(" #n ")" ::: "memory")
; #define PG8_BAR __builtin_amdgcn_s_barrier()
; #define PG8_SCHED __builtin_amdgcn_sched_barrier(0)
; template <class Epi, class Sched, bool ALIGN_EPI = false, bool SP2 = false>
; __device__ __forceinline__ void gemm_phase(PG8_LAS unsigned char* lds, const Gemm g, const Sched& S, const Epi& E) {
;     ...
;             PG8_WAIT_V(8); PG8_WAIT_L(0); PG8_BAR; PG8_MMA(1, 0, At, B0); PG8_MMA(1, 1, At, B1); PG8_BAR; PG8_SCHED;
;             PG8_LDB(B0, 1, 0); PG8_LDB(B1, 1, 1); PG8_SCHED; PG8_LDA(At, 1, 0); PG8_STAGE(PG8_SA(0, 1), a2 + hstep, voffA);
;             PG8_WAIT_V(8); PG8_WAIT_L(0); PG8_BAR; PG8_MMA(0, 0, At, B0); PG8_MMA(0, 1, At, B1); PG8_BAR; PG8_SCHED;
	s_waitcnt lgkmcnt(0)
	v_mfma_f32_16x16x32_bf16 v[62:65], v[130:133], v[184:187], v[62:65]
	v_mfma_f32_16x16x32_bf16 v[58:61], v[160:163], v[184:187], v[58:61]
	v_mfma_f32_16x16x32_bf16 v[46:49], v[130:133], v[196:199], v[46:49]
	v_mfma_f32_16x16x32_bf16 v[42:45], v[160:163], v[196:199], v[42:45]
	v_mfma_f32_16x16x32_bf16 v[30:33], v[130:133], v[204:207], v[30:33]
	v_mfma_f32_16x16x32_bf16 v[26:29], v[160:163], v[204:207], v[26:29]
	v_mfma_f32_16x16x32_bf16 v[14:17], v[130:133], v[230:233], v[14:17]
	v_mfma_f32_16x16x32_bf16 v[10:13], v[160:163], v[230:233], v[10:13]
	v_mfma_f32_16x16x32_bf16 v[62:65], v[134:137], v[188:191], v[62:65]
	v_mfma_f32_16x16x32_bf16 v[58:61], v[164:167], v[188:191], v[58:61]
	v_mfma_f32_16x16x32_bf16 v[46:49], v[134:137], v[200:203], v[46:49]
	v_mfma_f32_16x16x32_bf16 v[42:45], v[164:167], v[200:203], v[42:45]
	v_mfma_f32_16x16x32_bf16 v[30:33], v[134:137], v[226:229], v[30:33]
	v_mfma_f32_16x16x32_bf16 v[26:29], v[164:167], v[226:229], v[26:29]
	v_mfma_f32_16x16x32_bf16 v[14:17], v[134:137], v[234:237], v[14:17]
	v_mfma_f32_16x16x32_bf16 v[10:13], v[164:167], v[234:237], v[10:13]
	v_mfma_f32_16x16x32_bf16 v[54:57], v[168:171], v[184:187], v[54:57]
	v_mfma_f32_16x16x32_bf16 v[50:53], v[176:179], v[184:187], v[50:53]
	v_mfma_f32_16x16x32_bf16 v[38:41], v[168:171], v[196:199], v[38:41]
	v_mfma_f32_16x16x32_bf16 v[34:37], v[176:179], v[196:199], v[34:37]
	v_mfma_f32_16x16x32_bf16 v[22:25], v[168:171], v[204:207], v[22:25]
	v_mfma_f32_16x16x32_bf16 v[18:21], v[176:179], v[204:207], v[18:21]
	v_mfma_f32_16x16x32_bf16 v[6:9], v[168:171], v[230:233], v[6:9]
	v_mfma_f32_16x16x32_bf16 v[2:5], v[176:179], v[230:233], v[2:5]
	v_mfma_f32_16x16x32_bf16 v[54:57], v[172:175], v[188:191], v[54:57]
	v_mfma_f32_16x16x32_bf16 v[50:53], v[180:183], v[188:191], v[50:53]
	v_mfma_f32_16x16x32_bf16 v[38:41], v[172:175], v[200:203], v[38:41]
	v_mfma_f32_16x16x32_bf16 v[34:37], v[180:183], v[200:203], v[34:37]
	v_mfma_f32_16x16x32_bf16 v[22:25], v[172:175], v[226:229], v[22:25]
	v_mfma_f32_16x16x32_bf16 v[18:21], v[180:183], v[226:229], v[18:21]
	v_mfma_f32_16x16x32_bf16 v[6:9], v[172:175], v[234:237], v[6:9]
	v_mfma_f32_16x16x32_bf16 v[2:5], v[180:183], v[234:237], v[2:5]
	s_barrier
	s_add_i32 s53, 0, 0x18000
	s_add_i32 s54, 0, 0x1c000
	v_add_u32_e32 v164, s53, v192
	v_add_u32_e32 v180, s54, v192
	ds_read_b128 v[130:133], v164
	ds_read_b128 v[134:137], v164 offset:1024
	ds_read_b128 v[160:163], v164 offset:2048
	ds_read_b128 v[164:167], v164 offset:3072
	ds_read_b128 v[168:171], v180
	ds_read_b128 v[172:175], v180 offset:1024
	ds_read_b128 v[176:179], v180 offset:2048
	ds_read_b128 v[180:183], v180 offset:3072
	s_add_u32 s34, s34, 0x80000
	s_addc_u32 s35, s35, 0
	s_mov_b32 m0, s45
	v_lshl_add_u64 v[244:245], s[34:35], 0, v[146:147]
	ds_read_b128 v[184:187], v194 offset:32768
	ds_read_b128 v[188:191], v194 offset:33792
	ds_read_b128 v[196:199], v194 offset:34816
	ds_read_b128 v[200:203], v194 offset:35840
	ds_read_b128 v[204:207], v194 offset:36864
	ds_read_b128 v[226:229], v194 offset:37888
	ds_read_b128 v[230:233], v194 offset:38912
	ds_read_b128 v[234:237], v194 offset:39936
	global_load_lds_dwordx4 v[244:245], off
	v_lshl_add_u64 v[244:245], s[34:35], 0, v[148:149]
	s_mov_b32 m0, s46
	s_nop 0
	global_load_lds_dwordx4 v[244:245], off
	s_waitcnt vmcnt(8)
	s_waitcnt lgkmcnt(0)
	s_barrier
	s_waitcnt lgkmcnt(0)
	v_mfma_f32_16x16x32_bf16 v[126:129], v[130:133], v[184:187], v[126:129]
	v_mfma_f32_16x16x32_bf16 v[122:125], v[160:163], v[184:187], v[122:125]
	v_mfma_f32_16x16x32_bf16 v[110:113], v[130:133], v[196:199], v[110:113]
	v_mfma_f32_16x16x32_bf16 v[106:109], v[160:163], v[196:199], v[106:109]
	v_mfma_f32_16x16x32_bf16 v[94:97], v[130:133], v[204:207], v[94:97]
	v_mfma_f32_16x16x32_bf16 v[90:93], v[160:163], v[204:207], v[90:93]
	v_mfma_f32_16x16x32_bf16 v[78:81], v[130:133], v[230:233], v[78:81]
	v_mfma_f32_16x16x32_bf16 v[74:77], v[160:163], v[230:233], v[74:77]
	v_mfma_f32_16x16x32_bf16 v[126:129], v[134:137], v[188:191], v[126:129]
	v_mfma_f32_16x16x32_bf16 v[122:125], v[164:167], v[188:191], v[122:125]
	v_mfma_f32_16x16x32_bf16 v[110:113], v[134:137], v[200:203], v[110:113]
	v_mfma_f32_16x16x32_bf16 v[106:109], v[164:167], v[200:203], v[106:109]
	v_mfma_f32_16x16x32_bf16 v[94:97], v[134:137], v[226:229], v[94:97]
	v_mfma_f32_16x16x32_bf16 v[90:93], v[164:167], v[226:229], v[90:93]
	v_mfma_f32_16x16x32_bf16 v[78:81], v[134:137], v[234:237], v[78:81]
	v_mfma_f32_16x16x32_bf16 v[74:77], v[164:167], v[234:237], v[74:77]
	v_mfma_f32_16x16x32_bf16 v[118:121], v[168:171], v[184:187], v[118:121]
	v_mfma_f32_16x16x32_bf16 v[114:117], v[176:179], v[184:187], v[114:117]
	v_mfma_f32_16x16x32_bf16 v[102:105], v[168:171], v[196:199], v[102:105]
	v_mfma_f32_16x16x32_bf16 v[98:101], v[176:179], v[196:199], v[98:101]
	v_mfma_f32_16x16x32_bf16 v[86:89], v[168:171], v[204:207], v[86:89]
	v_mfma_f32_16x16x32_bf16 v[82:85], v[176:179], v[204:207], v[82:85]
	v_mfma_f32_16x16x32_bf16 v[70:73], v[168:171], v[230:233], v[70:73]
	v_mfma_f32_16x16x32_bf16 v[66:69], v[176:179], v[230:233], v[66:69]
	v_mfma_f32_16x16x32_bf16 v[118:121], v[172:175], v[188:191], v[118:121]
	v_mfma_f32_16x16x32_bf16 v[114:117], v[180:183], v[188:191], v[114:117]
	v_mfma_f32_16x16x32_bf16 v[102:105], v[172:175], v[200:203], v[102:105]
	v_mfma_f32_16x16x32_bf16 v[98:101], v[180:183], v[200:203], v[98:101]
	v_mfma_f32_16x16x32_bf16 v[86:89], v[172:175], v[226:229], v[86:89]
	v_mfma_f32_16x16x32_bf16 v[82:85], v[180:183], v[226:229], v[82:85]
	v_mfma_f32_16x16x32_bf16 v[70:73], v[172:175], v[234:237], v[70:73]
	v_mfma_f32_16x16x32_bf16 v[66:69], v[180:183], v[234:237], v[66:69]
	s_barrier
; #define PG8_STAGE(bufoff, gbase, voff) do { _Pragma("unroll") for (int _i = 0; _i < 2; ++_i) \
;         __builtin_amdgcn_global_load_lds((const unsigned*)((const char*)(gbase) + (voff)[_i]), (PG8_LAS unsigned*)(lds + (bufoff) + ldsw + _i * 8192), 16, 0, 0); } while (0)
; #define PG8_LDA(dst, b, h) do { _Pragma("unroll") for (int m = 0; m < 4; ++m) _Pragma("unroll") for (int k = 0; k < 2; ++k) dst[m][k] = *(const PG8_LAS bf16x8*)(lds + PG8_SA(b, h) + aoff + m * 2048 + k * 1024); } while (0)
; #define PG8_MMA(ai, bj, At, Bt) do { __builtin_amdgcn_s_setprio(1); _Pragma("unroll") for (int m = 0; m < 4; ++m) _Pragma("unroll") for (int n = 0; n < 2; ++n) _Pragma("unroll") for (int k = 0; k < 2; ++k) \
;         acc[ai][bj][m][n] = __builtin_amdgcn_mfma_f32_16x16x32_bf16(Bt[n][k], At[m][k], acc[ai][bj][m][n], 0, 0, 0); __builtin_amdgcn_s_setprio(0); } while (0)
; #define PG8_WAIT_V(n) asm volatile("s_waitcnt vmcnt(" #n ")" ::: "memory")
; #define PG8_WAIT_L(n) asm volatile("s_waitcnt lgkmcnt(" #n ")" ::: "memory")
; #define PG8_BAR __builtin_amdgcn_s_barrier()
; #define PG8_SCHED __builtin_amdgcn_sched_barrier(0)
; template <class Epi, class Sched, bool ALIGN_EPI = false, bool SP2 = false>
; __device__ __forceinline__ void gemm_phase(PG8_LAS unsigned char* lds, const Gemm g, const Sched& S, const Epi& E) {
;     ...
;             PG8_LDA(At, 1, 1); PG8_STAGE(PG8_SB(1, 0), b3, voffB); PG8_STAGE(PG8_SB(1, 1), b3 + hstep, voffB); PG8_STAGE(PG8_SA(1, 0), a3, voffA);
;             PG8_WAIT_V(8); PG8_WAIT_L(0); PG8_BAR; PG8_MMA(1, 0, At, B0); PG8_MMA(1, 1, At, B1); PG8_BAR; PG8_SCHED;
	s_add_i32 s34, s53, s43
	v_lshl_add_u64 v[208:209], v[208:209], 0, s[0:1]
	s_mov_b32 m0, s34
	ds_read_b128 v[184:187], v194 offset:49152
	ds_read_b128 v[188:191], v194 offset:50176
	ds_read_b128 v[196:199], v194 offset:51200
	ds_read_b128 v[200:203], v194 offset:52224
	ds_read_b128 v[204:207], v194 offset:53248
	ds_read_b128 v[226:229], v194 offset:54272
	ds_read_b128 v[230:233], v194 offset:55296
	ds_read_b128 v[234:237], v194 offset:56320
	global_load_lds_dwordx4 v[208:209], off
	s_add_i32 m0, s34, 0x2000
	s_add_u32 s10, s10, 0x80080
	v_lshl_add_u64 v[208:209], v[238:239], 0, s[0:1]
	s_addc_u32 s11, s11, 0
	s_add_i32 s34, s54, s43
	global_load_lds_dwordx4 v[208:209], off
	v_lshl_add_u64 v[208:209], s[10:11], 0, v[0:1]
	s_mov_b32 m0, s34
	s_nop 0
	global_load_lds_dwordx4 v[208:209], off
	v_lshl_add_u64 v[208:209], s[10:11], 0, v[150:151]
	s_add_i32 m0, s34, 0x2000
	s_nop 0
	global_load_lds_dwordx4 v[208:209], off
	v_lshl_add_u64 v[208:209], v[240:241], 0, s[0:1]
	s_mov_b32 m0, s47
	s_nop 0
	global_load_lds_dwordx4 v[208:209], off
	v_lshl_add_u64 v[208:209], v[242:243], 0, s[0:1]
	s_mov_b32 m0, s48
	s_nop 0
	global_load_lds_dwordx4 v[208:209], off
	s_waitcnt vmcnt(8)
	s_waitcnt lgkmcnt(0)
	s_barrier
	s_waitcnt lgkmcnt(0)
	v_mfma_f32_16x16x32_bf16 v[62:65], v[130:133], v[184:187], v[62:65]
	v_mfma_f32_16x16x32_bf16 v[58:61], v[160:163], v[184:187], v[58:61]
	v_mfma_f32_16x16x32_bf16 v[46:49], v[130:133], v[196:199], v[46:49]
	v_mfma_f32_16x16x32_bf16 v[42:45], v[160:163], v[196:199], v[42:45]
	v_mfma_f32_16x16x32_bf16 v[30:33], v[130:133], v[204:207], v[30:33]
	v_mfma_f32_16x16x32_bf16 v[26:29], v[160:163], v[204:207], v[26:29]
	v_mfma_f32_16x16x32_bf16 v[14:17], v[130:133], v[230:233], v[14:17]
	v_mfma_f32_16x16x32_bf16 v[10:13], v[160:163], v[230:233], v[10:13]
	v_mfma_f32_16x16x32_bf16 v[62:65], v[134:137], v[188:191], v[62:65]
	v_mfma_f32_16x16x32_bf16 v[58:61], v[164:167], v[188:191], v[58:61]
	v_mfma_f32_16x16x32_bf16 v[46:49], v[134:137], v[200:203], v[46:49]
	v_mfma_f32_16x16x32_bf16 v[42:45], v[164:167], v[200:203], v[42:45]
	v_mfma_f32_16x16x32_bf16 v[30:33], v[134:137], v[226:229], v[30:33]
	v_mfma_f32_16x16x32_bf16 v[26:29], v[164:167], v[226:229], v[26:29]
	v_mfma_f32_16x16x32_bf16 v[14:17], v[134:137], v[234:237], v[14:17]
	v_mfma_f32_16x16x32_bf16 v[10:13], v[164:167], v[234:237], v[10:13]
	v_mfma_f32_16x16x32_bf16 v[54:57], v[168:171], v[184:187], v[54:57]
	v_mfma_f32_16x16x32_bf16 v[50:53], v[176:179], v[184:187], v[50:53]
	v_mfma_f32_16x16x32_bf16 v[38:41], v[168:171], v[196:199], v[38:41]
	v_mfma_f32_16x16x32_bf16 v[34:37], v[176:179], v[196:199], v[34:37]
	v_mfma_f32_16x16x32_bf16 v[22:25], v[168:171], v[204:207], v[22:25]
	v_mfma_f32_16x16x32_bf16 v[18:21], v[176:179], v[204:207], v[18:21]
	v_mfma_f32_16x16x32_bf16 v[6:9], v[168:171], v[230:233], v[6:9]
	v_mfma_f32_16x16x32_bf16 v[2:5], v[176:179], v[230:233], v[2:5]
	v_mfma_f32_16x16x32_bf16 v[54:57], v[172:175], v[188:191], v[54:57]
	v_mfma_f32_16x16x32_bf16 v[50:53], v[180:183], v[188:191], v[50:53]
	v_mfma_f32_16x16x32_bf16 v[38:41], v[172:175], v[200:203], v[38:41]
	v_mfma_f32_16x16x32_bf16 v[34:37], v[180:183], v[200:203], v[34:37]
	v_mfma_f32_16x16x32_bf16 v[22:25], v[172:175], v[226:229], v[22:25]
	v_mfma_f32_16x16x32_bf16 v[18:21], v[180:183], v[226:229], v[18:21]
	v_mfma_f32_16x16x32_bf16 v[6:9], v[172:175], v[234:237], v[6:9]
	v_mfma_f32_16x16x32_bf16 v[2:5], v[180:183], v[234:237], v[2:5]
	s_barrier
	s_add_i32 s52, s52, 2
	s_add_u32 s8, s8, 0x100
	s_addc_u32 s9, s9, 0
	s_add_u32 s37, s37, 0x100
	s_addc_u32 s51, s51, 0
	s_cmp_gt_u32 s52, 29
	s_cbranch_scc0 .LBB0_668
	s_and_b64 vcc, exec, s[20:21]
	s_cbranch_vccz .LBB0_671
	s_barrier

; #define PG8_STAGE(bufoff, gbase, voff) do { _Pragma("unroll") for (int _i = 0; _i < 2; ++_i) \
;         __builtin_amdgcn_global_load_lds((const unsigned*)((const char*)(gbase) + (voff)[_i]), (PG8_LAS unsigned*)(lds + (bufoff) + ldsw + _i * 8192), 16, 0, 0); } while (0)
; #define PG8_LDA(dst, b, h) do { _Pragma("unroll") for (int m = 0; m < 4; ++m) _Pragma("unroll") for (int k = 0; k < 2; ++k) dst[m][k] = *(const PG8_LAS bf16x8*)(lds + PG8_SA(b, h) + aoff + m * 2048 + k * 1024); } while (0)
; #define PG8_LDB(dst, b, h) do { _Pragma("unroll") for (int n = 0; n < 2; ++n) _Pragma("unroll") for (int k = 0; k < 2; ++k) dst[n][k] = *(const PG8_LAS bf16x8*)(lds + PG8_SB(b, h) + boff + n * 2048 + k * 1024); } while (0)
; #define PG8_MMA(ai, bj, At, Bt) do { __builtin_amdgcn_s_setprio(1); _Pragma("unroll") for (int m = 0; m < 4; ++m) _Pragma("unroll") for (int n = 0; n < 2; ++n) _Pragma("unroll") for (int k = 0; k < 2; ++k) \
;         acc[ai][bj][m][n] = __builtin_amdgcn_mfma_f32_16x16x32_bf16(Bt[n][k], At[m][k], acc[ai][bj][m][n], 0, 0, 0); __builtin_amdgcn_s_setprio(0); } while (0)
; #define PG8_WAIT_V(n) asm volatile("s_waitcnt vmcnt(" #n ")" ::: "memory")
; #define PG8_WAIT_L(n) asm volatile("s_waitcnt lgkmcnt(" #n ")" ::: "memory")
; #define PG8_BAR __builtin_amdgcn_s_barrier()
; #define PG8_SCHED __builtin_amdgcn_sched_barrier(0)
; template <class Epi, class Sched, bool ALIGN_EPI = false, bool SP2 = false>
; __device__ __forceinline__ void gemm_phase(PG8_LAS unsigned char* lds, const Gemm g, const Sched& S, const Epi& E) {
;     ...
;             PG8_LDB(B0, 0, 0); PG8_LDB(B1, 0, 1); PG8_SCHED; PG8_LDA(At, 0, 0); PG8_STAGE(PG8_SA(1, 1), a1 + hstep, voffA);
;             PG8_WAIT_V(8); PG8_WAIT_L(0); PG8_BAR; PG8_MMA(0, 0, At, B0); PG8_MMA(0, 1, At, B1); PG8_BAR; PG8_SCHED;
;             PG8_LDA(At, 0, 1); PG8_STAGE(PG8_SB(0, 0), b2, voffB); PG8_STAGE(PG8_SB(0, 1), b2 + hstep, voffB); PG8_STAGE(PG8_SA(0, 0), a2, voffA);
.LBB0_808:
	s_add_u32 s30, s8, 0xfff80080
	s_addc_u32 s31, s9, -1
	s_add_i32 s62, 0, 0x10000
	s_cmp_eq_u32 s57, 28
	s_cselect_b32 s35, s5, s31
	s_cselect_b32 s34, s7, s30
	v_add_u32_e32 v0, s62, v192
	s_cselect_b32 s31, s23, s56
	s_cselect_b32 s30, s25, s55
	s_add_i32 s68, 0, 0x14000
	ds_read_b128 v[130:133], v0
	ds_read_b128 v[134:137], v0 offset:1024
	ds_read_b128 v[160:163], v0 offset:2048
	ds_read_b128 v[164:167], v0 offset:3072
	v_add_u32_e32 v0, s68, v192
	ds_read_b128 v[168:171], v0
	ds_read_b128 v[172:175], v0 offset:1024
	ds_read_b128 v[176:179], v0 offset:2048
	ds_read_b128 v[180:183], v0 offset:3072
	v_lshl_add_u64 v[208:209], s[8:9], 0, v[156:157]
	s_add_i32 m0, s42, 0xc000
	ds_read_b128 v[184:187], v194
	ds_read_b128 v[188:191], v194 offset:1024
	ds_read_b128 v[196:199], v194 offset:2048
	ds_read_b128 v[200:203], v194 offset:3072
	ds_read_b128 v[204:207], v194 offset:4096
	ds_read_b128 v[226:229], v194 offset:5120
	ds_read_b128 v[230:233], v194 offset:6144
	ds_read_b128 v[234:237], v194 offset:7168
	global_load_lds_dwordx4 v[208:209], off
	v_lshl_add_u64 v[208:209], s[8:9], 0, v[158:159]
	s_add_i32 m0, s42, 0xe000
	s_nop 0
	global_load_lds_dwordx4 v[208:209], off
	s_waitcnt vmcnt(8)
	s_waitcnt lgkmcnt(0)
	s_barrier
	s_waitcnt lgkmcnt(0)
	v_mfma_f32_16x16x32_bf16 v[126:129], v[130:133], v[184:187], v[126:129]
	v_mfma_f32_16x16x32_bf16 v[122:125], v[160:163], v[184:187], v[122:125]
	v_mfma_f32_16x16x32_bf16 v[110:113], v[130:133], v[196:199], v[110:113]
	v_mfma_f32_16x16x32_bf16 v[106:109], v[160:163], v[196:199], v[106:109]
	v_mfma_f32_16x16x32_bf16 v[94:97], v[130:133], v[204:207], v[94:97]
	v_mfma_f32_16x16x32_bf16 v[90:93], v[160:163], v[204:207], v[90:93]
	v_mfma_f32_16x16x32_bf16 v[78:81], v[130:133], v[230:233], v[78:81]
	v_mfma_f32_16x16x32_bf16 v[74:77], v[160:163], v[230:233], v[74:77]
	v_mfma_f32_16x16x32_bf16 v[126:129], v[134:137], v[188:191], v[126:129]
	v_mfma_f32_16x16x32_bf16 v[122:125], v[164:167], v[188:191], v[122:125]
	v_mfma_f32_16x16x32_bf16 v[110:113], v[134:137], v[200:203], v[110:113]
	v_mfma_f32_16x16x32_bf16 v[106:109], v[164:167], v[200:203], v[106:109]
	v_mfma_f32_16x16x32_bf16 v[94:97], v[134:137], v[226:229], v[94:97]
	v_mfma_f32_16x16x32_bf16 v[90:93], v[164:167], v[226:229], v[90:93]
	v_mfma_f32_16x16x32_bf16 v[78:81], v[134:137], v[234:237], v[78:81]
	v_mfma_f32_16x16x32_bf16 v[74:77], v[164:167], v[234:237], v[74:77]
	v_mfma_f32_16x16x32_bf16 v[118:121], v[168:171], v[184:187], v[118:121]
	v_mfma_f32_16x16x32_bf16 v[114:117], v[176:179], v[184:187], v[114:117]
	v_mfma_f32_16x16x32_bf16 v[102:105], v[168:171], v[196:199], v[102:105]
	v_mfma_f32_16x16x32_bf16 v[98:101], v[176:179], v[196:199], v[98:101]
	v_mfma_f32_16x16x32_bf16 v[86:89], v[168:171], v[204:207], v[86:89]
	v_mfma_f32_16x16x32_bf16 v[82:85], v[176:179], v[204:207], v[82:85]
	v_mfma_f32_16x16x32_bf16 v[70:73], v[168:171], v[230:233], v[70:73]
	v_mfma_f32_16x16x32_bf16 v[66:69], v[176:179], v[230:233], v[66:69]
	v_mfma_f32_16x16x32_bf16 v[118:121], v[172:175], v[188:191], v[118:121]
	v_mfma_f32_16x16x32_bf16 v[114:117], v[180:183], v[188:191], v[114:117]
	v_mfma_f32_16x16x32_bf16 v[102:105], v[172:175], v[200:203], v[102:105]
	v_mfma_f32_16x16x32_bf16 v[98:101], v[180:183], v[200:203], v[98:101]
	v_mfma_f32_16x16x32_bf16 v[86:89], v[172:175], v[226:229], v[86:89]
	v_mfma_f32_16x16x32_bf16 v[82:85], v[180:183], v[226:229], v[82:85]
	v_mfma_f32_16x16x32_bf16 v[70:73], v[172:175], v[234:237], v[70:73]
	v_mfma_f32_16x16x32_bf16 v[66:69], v[180:183], v[234:237], v[66:69]
	s_barrier
	s_add_i32 s62, s62, s41
	v_lshl_add_u64 v[208:209], s[30:31], 0, v[148:149]
	s_mov_b32 m0, s62
	ds_read_b128 v[184:187], v194 offset:16384
	ds_read_b128 v[188:191], v194 offset:17408
	ds_read_b128 v[196:199], v194 offset:18432
	ds_read_b128 v[200:203], v194 offset:19456
	ds_read_b128 v[204:207], v194 offset:20480
	ds_read_b128 v[226:229], v194 offset:21504
	ds_read_b128 v[230:233], v194 offset:22528
	ds_read_b128 v[234:237], v194 offset:23552
	global_load_lds_dwordx4 v[208:209], off
	s_add_i32 m0, s62, 0x2000
	s_add_u32 s62, s30, 0x80000
	v_lshl_add_u64 v[238:239], s[30:31], 0, v[152:153]
	s_addc_u32 s63, s31, 0
	s_add_i32 s68, s68, s41
	global_load_lds_dwordx4 v[238:239], off
	v_lshl_add_u64 v[240:241], s[62:63], 0, v[148:149]
	s_mov_b32 m0, s68
	v_lshl_add_u64 v[242:243], s[34:35], 0, v[150:151]
	global_load_lds_dwordx4 v[240:241], off
	v_lshl_add_u64 v[240:241], s[62:63], 0, v[152:153]
	s_add_i32 m0, s68, 0x2000
	s_nop 0
	global_load_lds_dwordx4 v[240:241], off
	v_lshl_add_u64 v[240:241], s[34:35], 0, v[146:147]
	s_mov_b32 m0, s42
	s_nop 0
	global_load_lds_dwordx4 v[240:241], off
	s_mov_b32 m0, s43
	s_nop 0
	global_load_lds_dwordx4 v[242:243], off
	s_waitcnt vmcnt(8)
	s_waitcnt lgkmcnt(0)
	s_barrier
; #define PG8_STAGE(bufoff, gbase, voff) do { _Pragma("unroll") for (int _i = 0; _i < 2; ++_i) \
;         __builtin_amdgcn_global_load_lds((const unsigned*)((const char*)(gbase) + (voff)[_i]), (PG8_LAS unsigned*)(lds + (bufoff) + ldsw + _i * 8192), 16, 0, 0); } while (0)
; #define PG8_LDA(dst, b, h) do { _Pragma("unroll") for (int m = 0; m < 4; ++m) _Pragma("unroll") for (int k = 0; k < 2; ++k) dst[m][k] = *(const PG8_LAS bf16x8*)(lds + PG8_SA(b, h) + aoff + m * 2048 + k * 1024); } while (0)
; #define PG8_LDB(dst, b, h) do { _Pragma("unroll") for (int n = 0; n < 2; ++n) _Pragma("unroll") for (int k = 0; k < 2; ++k) dst[n][k] = *(const PG8_LAS bf16x8*)(lds + PG8_SB(b, h) + boff + n * 2048 + k * 1024); } while (0)
; #define PG8_MMA(ai, bj, At, Bt) do { __builtin_amdgcn_s_setprio(1); _Pragma("unroll") for (int m = 0; m < 4; ++m) _Pragma("unroll") for (int n = 0; n < 2; ++n) _Pragma("unroll") for (int k = 0; k < 2; ++k) \
;         acc[ai][bj][m][n] = __builtin_amdgcn_mfma_f32_16x16x32_bf16(Bt[n][k], At[m][k], acc[ai][bj][m][n], 0, 0, 0); __builtin_amdgcn_s_setprio(0); } while (0)
; #define PG8_WAIT_V(n) asm volatile("s_waitcnt vmcnt(" #n ")" ::: "memory")
; #define PG8_WAIT_L(n) asm volatile("s_waitcnt lgkmcnt(" #n ")" ::: "memory")
; #define PG8_BAR __builtin_amdgcn_s_barrier()
; #define PG8_SCHED __builtin_amdgcn_sched_barrier(0)
; template <class Epi, class Sched, bool ALIGN_EPI = false, bool SP2 = false>
; __device__ __forceinline__ void gemm_phase(PG8_LAS unsigned char* lds, const Gemm g, const Sched& S, const Epi& E) {
;     ...
;             PG8_WAIT_V(8); PG8_WAIT_L(0); PG8_BAR; PG8_MMA(1, 0, At, B0); PG8_MMA(1, 1, At, B1); PG8_BAR; PG8_SCHED;
;             PG8_LDB(B0, 1, 0); PG8_LDB(B1, 1, 1); PG8_SCHED; PG8_LDA(At, 1, 0); PG8_STAGE(PG8_SA(0, 1), a2 + hstep, voffA);
;             PG8_WAIT_V(8); PG8_WAIT_L(0); PG8_BAR; PG8_MMA(0, 0, At, B0); PG8_MMA(0, 1, At, B1); PG8_BAR; PG8_SCHED;
	s_waitcnt lgkmcnt(0)
	v_mfma_f32_16x16x32_bf16 v[62:65], v[130:133], v[184:187], v[62:65]
	v_mfma_f32_16x16x32_bf16 v[58:61], v[160:163], v[184:187], v[58:61]
	v_mfma_f32_16x16x32_bf16 v[46:49], v[130:133], v[196:199], v[46:49]
	v_mfma_f32_16x16x32_bf16 v[42:45], v[160:163], v[196:199], v[42:45]
	v_mfma_f32_16x16x32_bf16 v[30:33], v[130:133], v[204:207], v[30:33]
	v_mfma_f32_16x16x32_bf16 v[26:29], v[160:163], v[204:207], v[26:29]
	v_mfma_f32_16x16x32_bf16 v[14:17], v[130:133], v[230:233], v[14:17]
	v_mfma_f32_16x16x32_bf16 v[10:13], v[160:163], v[230:233], v[10:13]
	v_mfma_f32_16x16x32_bf16 v[62:65], v[134:137], v[188:191], v[62:65]
	v_mfma_f32_16x16x32_bf16 v[58:61], v[164:167], v[188:191], v[58:61]
	v_mfma_f32_16x16x32_bf16 v[46:49], v[134:137], v[200:203], v[46:49]
	v_mfma_f32_16x16x32_bf16 v[42:45], v[164:167], v[200:203], v[42:45]
	v_mfma_f32_16x16x32_bf16 v[30:33], v[134:137], v[226:229], v[30:33]
	v_mfma_f32_16x16x32_bf16 v[26:29], v[164:167], v[226:229], v[26:29]
	v_mfma_f32_16x16x32_bf16 v[14:17], v[134:137], v[234:237], v[14:17]
	v_mfma_f32_16x16x32_bf16 v[10:13], v[164:167], v[234:237], v[10:13]
	v_mfma_f32_16x16x32_bf16 v[54:57], v[168:171], v[184:187], v[54:57]
	v_mfma_f32_16x16x32_bf16 v[50:53], v[176:179], v[184:187], v[50:53]
	v_mfma_f32_16x16x32_bf16 v[38:41], v[168:171], v[196:199], v[38:41]
	v_mfma_f32_16x16x32_bf16 v[34:37], v[176:179], v[196:199], v[34:37]
	v_mfma_f32_16x16x32_bf16 v[22:25], v[168:171], v[204:207], v[22:25]
	v_mfma_f32_16x16x32_bf16 v[18:21], v[176:179], v[204:207], v[18:21]
	v_mfma_f32_16x16x32_bf16 v[6:9], v[168:171], v[230:233], v[6:9]
	v_mfma_f32_16x16x32_bf16 v[2:5], v[176:179], v[230:233], v[2:5]
	v_mfma_f32_16x16x32_bf16 v[54:57], v[172:175], v[188:191], v[54:57]
	v_mfma_f32_16x16x32_bf16 v[50:53], v[180:183], v[188:191], v[50:53]
	v_mfma_f32_16x16x32_bf16 v[38:41], v[172:175], v[200:203], v[38:41]
	v_mfma_f32_16x16x32_bf16 v[34:37], v[180:183], v[200:203], v[34:37]
	v_mfma_f32_16x16x32_bf16 v[22:25], v[172:175], v[226:229], v[22:25]
	v_mfma_f32_16x16x32_bf16 v[18:21], v[180:183], v[226:229], v[18:21]
	v_mfma_f32_16x16x32_bf16 v[6:9], v[172:175], v[234:237], v[6:9]
	v_mfma_f32_16x16x32_bf16 v[2:5], v[180:183], v[234:237], v[2:5]
	s_barrier
	s_add_i32 s62, 0, 0x18000
	v_add_u32_e32 v0, s62, v192
	s_add_i32 s63, 0, 0x1c000
	ds_read_b128 v[130:133], v0
	ds_read_b128 v[134:137], v0 offset:1024
	ds_read_b128 v[160:163], v0 offset:2048
	ds_read_b128 v[164:167], v0 offset:3072
	v_add_u32_e32 v0, s63, v192
	ds_read_b128 v[168:171], v0
	ds_read_b128 v[172:175], v0 offset:1024
	ds_read_b128 v[176:179], v0 offset:2048
	ds_read_b128 v[180:183], v0 offset:3072
	s_add_u32 s34, s34, 0x80000
	s_addc_u32 s35, s35, 0
	s_mov_b32 m0, s44
	v_lshl_add_u64 v[244:245], s[34:35], 0, v[146:147]
	ds_read_b128 v[184:187], v194 offset:32768
	ds_read_b128 v[188:191], v194 offset:33792
	ds_read_b128 v[196:199], v194 offset:34816
	ds_read_b128 v[200:203], v194 offset:35840
	ds_read_b128 v[204:207], v194 offset:36864
	ds_read_b128 v[226:229], v194 offset:37888
	ds_read_b128 v[230:233], v194 offset:38912
	ds_read_b128 v[234:237], v194 offset:39936
	global_load_lds_dwordx4 v[244:245], off
	v_lshl_add_u64 v[244:245], s[34:35], 0, v[150:151]
	s_mov_b32 m0, s45
	s_nop 0
	global_load_lds_dwordx4 v[244:245], off
	s_waitcnt vmcnt(8)
	s_waitcnt lgkmcnt(0)
	s_barrier
	s_waitcnt lgkmcnt(0)
	v_mfma_f32_16x16x32_bf16 v[126:129], v[130:133], v[184:187], v[126:129]
	v_mfma_f32_16x16x32_bf16 v[122:125], v[160:163], v[184:187], v[122:125]
	v_mfma_f32_16x16x32_bf16 v[110:113], v[130:133], v[196:199], v[110:113]
	v_mfma_f32_16x16x32_bf16 v[106:109], v[160:163], v[196:199], v[106:109]
	v_mfma_f32_16x16x32_bf16 v[94:97], v[130:133], v[204:207], v[94:97]
	v_mfma_f32_16x16x32_bf16 v[90:93], v[160:163], v[204:207], v[90:93]
	v_mfma_f32_16x16x32_bf16 v[78:81], v[130:133], v[230:233], v[78:81]
	v_mfma_f32_16x16x32_bf16 v[74:77], v[160:163], v[230:233], v[74:77]
	v_mfma_f32_16x16x32_bf16 v[126:129], v[134:137], v[188:191], v[126:129]
	v_mfma_f32_16x16x32_bf16 v[122:125], v[164:167], v[188:191], v[122:125]
	v_mfma_f32_16x16x32_bf16 v[110:113], v[134:137], v[200:203], v[110:113]
	v_mfma_f32_16x16x32_bf16 v[106:109], v[164:167], v[200:203], v[106:109]
	v_mfma_f32_16x16x32_bf16 v[94:97], v[134:137], v[226:229], v[94:97]
	v_mfma_f32_16x16x32_bf16 v[90:93], v[164:167], v[226:229], v[90:93]
	v_mfma_f32_16x16x32_bf16 v[78:81], v[134:137], v[234:237], v[78:81]
	v_mfma_f32_16x16x32_bf16 v[74:77], v[164:167], v[234:237], v[74:77]
	v_mfma_f32_16x16x32_bf16 v[118:121], v[168:171], v[184:187], v[118:121]
	v_mfma_f32_16x16x32_bf16 v[114:117], v[176:179], v[184:187], v[114:117]
	v_mfma_f32_16x16x32_bf16 v[102:105], v[168:171], v[196:199], v[102:105]
	v_mfma_f32_16x16x32_bf16 v[98:101], v[176:179], v[196:199], v[98:101]
	v_mfma_f32_16x16x32_bf16 v[86:89], v[168:171], v[204:207], v[86:89]
	v_mfma_f32_16x16x32_bf16 v[82:85], v[176:179], v[204:207], v[82:85]
	v_mfma_f32_16x16x32_bf16 v[70:73], v[168:171], v[230:233], v[70:73]
	v_mfma_f32_16x16x32_bf16 v[66:69], v[176:179], v[230:233], v[66:69]
	v_mfma_f32_16x16x32_bf16 v[118:121], v[172:175], v[188:191], v[118:121]
	v_mfma_f32_16x16x32_bf16 v[114:117], v[180:183], v[188:191], v[114:117]
	v_mfma_f32_16x16x32_bf16 v[102:105], v[172:175], v[200:203], v[102:105]
	v_mfma_f32_16x16x32_bf16 v[98:101], v[180:183], v[200:203], v[98:101]
	v_mfma_f32_16x16x32_bf16 v[86:89], v[172:175], v[226:229], v[86:89]
	v_mfma_f32_16x16x32_bf16 v[82:85], v[180:183], v[226:229], v[82:85]
	v_mfma_f32_16x16x32_bf16 v[70:73], v[172:175], v[234:237], v[70:73]
	v_mfma_f32_16x16x32_bf16 v[66:69], v[180:183], v[234:237], v[66:69]
	s_barrier
; #define PG8_STAGE(bufoff, gbase, voff) do { _Pragma("unroll") for (int _i = 0; _i < 2; ++_i) \
;         __builtin_amdgcn_global_load_lds((const unsigned*)((const char*)(gbase) + (voff)[_i]), (PG8_LAS unsigned*)(lds + (bufoff) + ldsw + _i * 8192), 16, 0, 0); } while (0)
; #define PG8_LDA(dst, b, h) do { _Pragma("unroll") for (int m = 0; m < 4; ++m) _Pragma("unroll") for (int k = 0; k < 2; ++k) dst[m][k] = *(const PG8_LAS bf16x8*)(lds + PG8_SA(b, h) + aoff + m * 2048 + k * 1024); } while (0)
; #define PG8_MMA(ai, bj, At, Bt) do { __builtin_amdgcn_s_setprio(1); _Pragma("unroll") for (int m = 0; m < 4; ++m) _Pragma("unroll") for (int n = 0; n < 2; ++n) _Pragma("unroll") for (int k = 0; k < 2; ++k) \
;         acc[ai][bj][m][n] = __builtin_amdgcn_mfma_f32_16x16x32_bf16(Bt[n][k], At[m][k], acc[ai][bj][m][n], 0, 0, 0); __builtin_amdgcn_s_setprio(0); } while (0)
; #define PG8_WAIT_V(n) asm volatile("s_waitcnt vmcnt(" #n ")" ::: "memory")
; #define PG8_WAIT_L(n) asm volatile("s_waitcnt lgkmcnt(" #n ")" ::: "memory")
; #define PG8_BAR __builtin_amdgcn_s_barrier()
; #define PG8_SCHED __builtin_amdgcn_sched_barrier(0)
; template <class Epi, class Sched, bool ALIGN_EPI = false, bool SP2 = false>
; __device__ __forceinline__ void gemm_phase(PG8_LAS unsigned char* lds, const Gemm g, const Sched& S, const Epi& E) {
;     ...
;             PG8_LDA(At, 1, 1); PG8_STAGE(PG8_SB(1, 0), b3, voffB); PG8_STAGE(PG8_SB(1, 1), b3 + hstep, voffB); PG8_STAGE(PG8_SA(1, 0), a3, voffA);
;             PG8_WAIT_V(8); PG8_WAIT_L(0); PG8_BAR; PG8_MMA(1, 0, At, B0); PG8_MMA(1, 1, At, B1); PG8_BAR; PG8_SCHED;
	s_add_i32 s34, s62, s41
	v_lshl_add_u64 v[208:209], v[208:209], 0, s[0:1]
	s_mov_b32 m0, s34
	ds_read_b128 v[184:187], v194 offset:49152
	ds_read_b128 v[188:191], v194 offset:50176
	ds_read_b128 v[196:199], v194 offset:51200
	ds_read_b128 v[200:203], v194 offset:52224
	ds_read_b128 v[204:207], v194 offset:53248
	ds_read_b128 v[226:229], v194 offset:54272
	ds_read_b128 v[230:233], v194 offset:55296
	ds_read_b128 v[234:237], v194 offset:56320
	global_load_lds_dwordx4 v[208:209], off
	s_add_i32 m0, s34, 0x2000
	s_add_u32 s30, s30, 0x80080
	v_lshl_add_u64 v[208:209], v[238:239], 0, s[0:1]
	s_addc_u32 s31, s31, 0
	s_add_i32 s34, s63, s41
	global_load_lds_dwordx4 v[208:209], off
	v_lshl_add_u64 v[208:209], s[30:31], 0, v[148:149]
	s_mov_b32 m0, s34
	s_nop 0
	global_load_lds_dwordx4 v[208:209], off
	v_lshl_add_u64 v[208:209], s[30:31], 0, v[152:153]
	s_add_i32 m0, s34, 0x2000
	s_nop 0
	global_load_lds_dwordx4 v[208:209], off
	v_lshl_add_u64 v[208:209], v[240:241], 0, s[0:1]
	s_mov_b32 m0, s51
	s_nop 0
	global_load_lds_dwordx4 v[208:209], off
	v_lshl_add_u64 v[208:209], v[242:243], 0, s[0:1]
	s_mov_b32 m0, s52
	s_nop 0
	global_load_lds_dwordx4 v[208:209], off
	s_waitcnt vmcnt(8)
	s_waitcnt lgkmcnt(0)
	s_barrier
	s_waitcnt lgkmcnt(0)
	v_mfma_f32_16x16x32_bf16 v[62:65], v[130:133], v[184:187], v[62:65]
	v_mfma_f32_16x16x32_bf16 v[58:61], v[160:163], v[184:187], v[58:61]
	v_mfma_f32_16x16x32_bf16 v[46:49], v[130:133], v[196:199], v[46:49]
	v_mfma_f32_16x16x32_bf16 v[42:45], v[160:163], v[196:199], v[42:45]
	v_mfma_f32_16x16x32_bf16 v[30:33], v[130:133], v[204:207], v[30:33]
	v_mfma_f32_16x16x32_bf16 v[26:29], v[160:163], v[204:207], v[26:29]
	v_mfma_f32_16x16x32_bf16 v[14:17], v[130:133], v[230:233], v[14:17]
	v_mfma_f32_16x16x32_bf16 v[10:13], v[160:163], v[230:233], v[10:13]
	v_mfma_f32_16x16x32_bf16 v[62:65], v[134:137], v[188:191], v[62:65]
	v_mfma_f32_16x16x32_bf16 v[58:61], v[164:167], v[188:191], v[58:61]
	v_mfma_f32_16x16x32_bf16 v[46:49], v[134:137], v[200:203], v[46:49]
	v_mfma_f32_16x16x32_bf16 v[42:45], v[164:167], v[200:203], v[42:45]
	v_mfma_f32_16x16x32_bf16 v[30:33], v[134:137], v[226:229], v[30:33]
	v_mfma_f32_16x16x32_bf16 v[26:29], v[164:167], v[226:229], v[26:29]
	v_mfma_f32_16x16x32_bf16 v[14:17], v[134:137], v[234:237], v[14:17]
	v_mfma_f32_16x16x32_bf16 v[10:13], v[164:167], v[234:237], v[10:13]
	v_mfma_f32_16x16x32_bf16 v[54:57], v[168:171], v[184:187], v[54:57]
	v_mfma_f32_16x16x32_bf16 v[50:53], v[176:179], v[184:187], v[50:53]
	v_mfma_f32_16x16x32_bf16 v[38:41], v[168:171], v[196:199], v[38:41]
	v_mfma_f32_16x16x32_bf16 v[34:37], v[176:179], v[196:199], v[34:37]
	v_mfma_f32_16x16x32_bf16 v[22:25], v[168:171], v[204:207], v[22:25]
	v_mfma_f32_16x16x32_bf16 v[18:21], v[176:179], v[204:207], v[18:21]
	v_mfma_f32_16x16x32_bf16 v[6:9], v[168:171], v[230:233], v[6:9]
	v_mfma_f32_16x16x32_bf16 v[2:5], v[176:179], v[230:233], v[2:5]
	v_mfma_f32_16x16x32_bf16 v[54:57], v[172:175], v[188:191], v[54:57]
	v_mfma_f32_16x16x32_bf16 v[50:53], v[180:183], v[188:191], v[50:53]
	v_mfma_f32_16x16x32_bf16 v[38:41], v[172:175], v[200:203], v[38:41]
	v_mfma_f32_16x16x32_bf16 v[34:37], v[180:183], v[200:203], v[34:37]
	v_mfma_f32_16x16x32_bf16 v[22:25], v[172:175], v[226:229], v[22:25]
	v_mfma_f32_16x16x32_bf16 v[18:21], v[180:183], v[226:229], v[18:21]
	v_mfma_f32_16x16x32_bf16 v[6:9], v[172:175], v[234:237], v[6:9]
	v_mfma_f32_16x16x32_bf16 v[2:5], v[180:183], v[234:237], v[2:5]
	s_barrier
	s_add_i32 s57, s57, 2
	s_add_u32 s8, s8, 0x100
	s_addc_u32 s9, s9, 0
	s_add_u32 s55, s55, 0x100
	s_addc_u32 s56, s56, 0
	s_cmp_gt_u32 s57, 29
	s_cbranch_scc0 .LBB0_808
	s_and_b64 vcc, exec, s[18:19]
	s_cbranch_vccz .LBB0_811
	s_barrier

; __device__ __forceinline__ void xcd_barrier(const XcdBarrier& b) {
;     ...
;     }
;     __syncthreads();
.LBB0_900:
	s_or_b64 exec, exec, s[6:7]
	s_waitcnt lgkmcnt(0)
	s_barrier
	s_setprio 0

; #define LAS __attribute__((address_space(3)))
; #define WSB(name, type, off) type* name; { GAS unsigned char* w_ = (GAS unsigned char*)P.ws; OPQ64(w_); name = (type*)(w_ + (off)); }
; __device__ __forceinline__ void sample_out_block(LAS unsigned char* lds, const bf16_t* A, const bf16_t* Bt, int K, bf16_t* xb, float* sspart, int blk, int tid) {
;     const int wave = tid >> 6, lane = tid & 63, l15 = lane & 15, g = lane >> 4;
;     const int rt = blk >> 5, cg = blk & 31, r0 = T_P + 32 * rt;
;     const int kq = K >> 3;
;     f32x4 acc[2][4];
; #pragma unroll
;     for (int ra = 0; ra < 2; ++ra)
; #pragma unroll
;         for (int nt = 0; nt < 4; ++nt) acc[ra][nt] = (f32x4){0.f, 0.f, 0.f, 0.f};
;     {
;         const bf16_t* ap = A + (size_t)(r0 + l15) * K + wave * kq + 8 * g;
;         const bf16_t* bp = Bt + (size_t)(64 * cg + l15) * K + wave * kq + 8 * g;
; __global__ void __launch_bounds__(NTHREADS, 2) hybrid_fwd(Params P) {
;     ...
;             if (PH(3)) {
;                 PHASE_IDS
;                 WSB(X, float, WS_X) WSB(XB, bf16_t, WS_XB) WSB(SS, float, WS_SS) WSB(MIX, bf16_t, WS_MIX) WSB(WoutE, bf16_t, WS_WOUTE)
;                 pg8::EpiRes E{XB, SS};
;                 for (int blk = bid; blk < 256; blk += G) sample_out_block(lds, MIX, WoutE + (size_t)li * 2048 * 2048, 2048, XB, SS, blk, tid);
.Lprio_3:
.LBB0_1161:
	v_readlane_b32 s6, v254, 0
	s_cmp_ge_i32 s52, s6
	s_cselect_b64 s[12:13], -1, 0
	s_and_b64 s[4:5], s[12:13], s[4:5]
	s_andn2_b64 vcc, exec, s[4:5]
	v_readlane_b32 s7, v254, 1
	s_cbranch_vccnz .LBB0_1216
	v_readlane_b32 s4, v254, 40
	v_readlane_b32 s5, v254, 41
	v_readlane_b32 s6, v254, 42
	v_readlane_b32 s7, v254, 43
	v_mov_b32_e32 v6, v139
	s_mov_b32 s25, s90
	s_mov_b64 s[4:5], s[6:7]
	s_mov_b64 s[4:5], s[6:7]
	s_add_u32 s14, s4, 0x11c00000
	s_addc_u32 s15, s5, 0
	s_mov_b64 s[4:5], s[6:7]
	s_add_u32 s16, s4, 0x13d00000
	s_addc_u32 s17, s5, 0
	s_mov_b64 s[4:5], s[6:7]
	s_add_u32 s18, s4, 0x20408000
	s_addc_u32 s19, s5, 0
	s_mov_b64 s[4:5], s[6:7]
	s_add_u32 s22, s4, 0x2a00000
	s_addc_u32 s23, s5, 0
	v_readlane_b32 s4, v254, 52
	s_lshl_b32 s24, s4, 22
	s_cmpk_gt_i32 s25, 0xff
	v_readlane_b32 s5, v254, 53
	s_cbranch_scc1 .LBB0_1174
	v_ashrrev_i32_e32 v8, 6, v6
	s_lshl_b32 s4, s24, 1
	v_lshlrev_b32_e32 v2, 8, v8
	s_add_u32 s4, s22, s4
	s_waitcnt lgkmcnt(0)
	v_ashrrev_i32_e32 v3, 31, v2
	s_addc_u32 s5, s23, 0
	v_lshlrev_b64 v[4:5], 1, v[2:3]
	v_lshl_add_u64 v[2:3], s[18:19], 0, v[4:5]
	v_and_b32_e32 v0, 48, v6
	v_lshl_add_u64 v[4:5], s[4:5], 0, v[4:5]
	v_lshl_add_u64 v[2:3], v[2:3], 0, v[0:1]
	v_lshl_add_u64 v[4:5], v[4:5], 0, v[0:1]
	v_lshrrev_b32_e32 v0, 2, v6
	v_and_b32_e32 v7, 63, v6
	v_and_b32_e32 v30, 15, v6
	v_and_b32_e32 v0, 12, v0
	v_lshlrev_b32_e32 v9, 13, v8
	v_lshl_add_u32 v10, v7, 4, 0
	v_lshlrev_b32_e32 v11, 12, v8
	v_lshl_or_b32 v31, v8, 4, v0
	v_lshlrev_b32_e32 v0, 1, v30
	v_cmp_gt_i32_e64 s[4:5], 2, v8
	v_lshl_add_u64 v[6:7], s[14:15], 0, v[0:1]
	v_cmp_eq_u32_e64 s[6:7], 0, v30
	v_add_u32_e32 v32, v10, v9
	v_add_u32_e32 v33, v10, v11
	s_mov_b32 s26, s25
	s_branch .LBB0_1165

; #define PG8_STAGE(bufoff, gbase, voff) do { _Pragma("unroll") for (int _i = 0; _i < 2; ++_i) \
;         __builtin_amdgcn_global_load_lds((const unsigned*)((const char*)(gbase) + (voff)[_i]), (PG8_LAS unsigned*)(lds + (bufoff) + ldsw + _i * 8192), 16, 0, 0); } while (0)
; #define PG8_LDA(dst, b, h) do { _Pragma("unroll") for (int m = 0; m < 4; ++m) _Pragma("unroll") for (int k = 0; k < 2; ++k) dst[m][k] = *(const PG8_LAS bf16x8*)(lds + PG8_SA(b, h) + aoff + m * 2048 + k * 1024); } while (0)
; #define PG8_LDB(dst, b, h) do { _Pragma("unroll") for (int n = 0; n < 2; ++n) _Pragma("unroll") for (int k = 0; k < 2; ++k) dst[n][k] = *(const PG8_LAS bf16x8*)(lds + PG8_SB(b, h) + boff + n * 2048 + k * 1024); } while (0)
; #define PG8_MMA(ai, bj, At, Bt) do { __builtin_amdgcn_s_setprio(1); _Pragma("unroll") for (int m = 0; m < 4; ++m) _Pragma("unroll") for (int n = 0; n < 2; ++n) _Pragma("unroll") for (int k = 0; k < 2; ++k) \
;         acc[ai][bj][m][n] = __builtin_amdgcn_mfma_f32_16x16x32_bf16(Bt[n][k], At[m][k], acc[ai][bj][m][n], 0, 0, 0); __builtin_amdgcn_s_setprio(0); } while (0)
; #define PG8_WAIT_V(n) asm volatile("s_waitcnt vmcnt(" #n ")" ::: "memory")
; #define PG8_WAIT_L(n) asm volatile("s_waitcnt lgkmcnt(" #n ")" ::: "memory")
; #define PG8_BAR __builtin_amdgcn_s_barrier()
; #define PG8_SCHED __builtin_amdgcn_sched_barrier(0)
; template <class Epi, class Sched, bool ALIGN_EPI = false, bool SP2 = false>
; __device__ __forceinline__ void gemm_phase(PG8_LAS unsigned char* lds, const Gemm g, const Sched& S, const Epi& E) {
;     ...
;             PG8_LDB(B0, 0, 0); PG8_LDB(B1, 0, 1); PG8_SCHED; PG8_LDA(At, 0, 0); PG8_STAGE(PG8_SA(1, 1), a1 + hstep, voffA);
;             PG8_WAIT_V(8); PG8_WAIT_L(0); PG8_BAR; PG8_MMA(0, 0, At, B0); PG8_MMA(0, 1, At, B1); PG8_BAR; PG8_SCHED;
;             PG8_LDA(At, 0, 1); PG8_STAGE(PG8_SB(0, 0), b2, voffB); PG8_STAGE(PG8_SB(0, 1), b2 + hstep, voffB); PG8_STAGE(PG8_SA(0, 0), a2, voffA);
.LBB0_1193:
	s_add_u32 s36, s34, 0x100
	s_addc_u32 s37, s35, 0
	s_add_i32 s62, 0, 0x10000
	s_cmp_eq_u32 s57, 28
	s_cselect_b32 s41, s23, s37
	s_cselect_b32 s40, s29, s36
	v_add_u32_e32 v136, s62, v192
	s_cselect_b32 s39, s21, s56
	s_cselect_b32 s38, s31, s55
	s_add_i32 s63, 0, 0x14000
	ds_read_b128 v[146:149], v136
	ds_read_b128 v[150:153], v136 offset:1024
	ds_read_b128 v[154:157], v136 offset:2048
	ds_read_b128 v[158:161], v136 offset:3072
	v_add_u32_e32 v136, s63, v192
	ds_read_b128 v[162:165], v136
	ds_read_b128 v[166:169], v136 offset:1024
	ds_read_b128 v[170:173], v136 offset:2048
	ds_read_b128 v[174:177], v136 offset:3072
	v_lshl_add_u64 v[136:137], s[34:35], 0, v[132:133]
	s_add_i32 m0, s46, 0xc000
	ds_read_b128 v[178:181], v194
	ds_read_b128 v[182:185], v194 offset:1024
	ds_read_b128 v[186:189], v194 offset:2048
	ds_read_b128 v[196:199], v194 offset:3072
	ds_read_b128 v[200:203], v194 offset:4096
	ds_read_b128 v[204:207], v194 offset:5120
	ds_read_b128 v[226:229], v194 offset:6144
	ds_read_b128 v[230:233], v194 offset:7168
	global_load_lds_dwordx4 v[136:137], off
	v_lshl_add_u64 v[136:137], s[34:35], 0, v[134:135]
	s_add_i32 m0, s46, 0xe000
	s_nop 0
	global_load_lds_dwordx4 v[136:137], off
	s_waitcnt vmcnt(8)
	s_waitcnt lgkmcnt(0)
	s_barrier
	s_waitcnt lgkmcnt(0)
	v_mfma_f32_16x16x32_bf16 v[126:129], v[146:149], v[178:181], v[126:129]
	v_mfma_f32_16x16x32_bf16 v[122:125], v[154:157], v[178:181], v[122:125]
	v_mfma_f32_16x16x32_bf16 v[110:113], v[146:149], v[186:189], v[110:113]
	v_mfma_f32_16x16x32_bf16 v[106:109], v[154:157], v[186:189], v[106:109]
	v_mfma_f32_16x16x32_bf16 v[94:97], v[146:149], v[200:203], v[94:97]
	v_mfma_f32_16x16x32_bf16 v[90:93], v[154:157], v[200:203], v[90:93]
	v_mfma_f32_16x16x32_bf16 v[78:81], v[146:149], v[226:229], v[78:81]
	v_mfma_f32_16x16x32_bf16 v[74:77], v[154:157], v[226:229], v[74:77]
	v_mfma_f32_16x16x32_bf16 v[126:129], v[150:153], v[182:185], v[126:129]
	v_mfma_f32_16x16x32_bf16 v[122:125], v[158:161], v[182:185], v[122:125]
	v_mfma_f32_16x16x32_bf16 v[110:113], v[150:153], v[196:199], v[110:113]
	v_mfma_f32_16x16x32_bf16 v[106:109], v[158:161], v[196:199], v[106:109]
	v_mfma_f32_16x16x32_bf16 v[94:97], v[150:153], v[204:207], v[94:97]
	v_mfma_f32_16x16x32_bf16 v[90:93], v[158:161], v[204:207], v[90:93]
	v_mfma_f32_16x16x32_bf16 v[78:81], v[150:153], v[230:233], v[78:81]
	v_mfma_f32_16x16x32_bf16 v[74:77], v[158:161], v[230:233], v[74:77]
	v_mfma_f32_16x16x32_bf16 v[118:121], v[162:165], v[178:181], v[118:121]
	v_mfma_f32_16x16x32_bf16 v[114:117], v[170:173], v[178:181], v[114:117]
	v_mfma_f32_16x16x32_bf16 v[102:105], v[162:165], v[186:189], v[102:105]
	v_mfma_f32_16x16x32_bf16 v[98:101], v[170:173], v[186:189], v[98:101]
	v_mfma_f32_16x16x32_bf16 v[86:89], v[162:165], v[200:203], v[86:89]
	v_mfma_f32_16x16x32_bf16 v[82:85], v[170:173], v[200:203], v[82:85]
	v_mfma_f32_16x16x32_bf16 v[70:73], v[162:165], v[226:229], v[70:73]
	v_mfma_f32_16x16x32_bf16 v[66:69], v[170:173], v[226:229], v[66:69]
	v_mfma_f32_16x16x32_bf16 v[118:121], v[166:169], v[182:185], v[118:121]
	v_mfma_f32_16x16x32_bf16 v[114:117], v[174:177], v[182:185], v[114:117]
	v_mfma_f32_16x16x32_bf16 v[102:105], v[166:169], v[196:199], v[102:105]
	v_mfma_f32_16x16x32_bf16 v[98:101], v[174:177], v[196:199], v[98:101]
	v_mfma_f32_16x16x32_bf16 v[86:89], v[166:169], v[204:207], v[86:89]
	v_mfma_f32_16x16x32_bf16 v[82:85], v[174:177], v[204:207], v[82:85]
	v_mfma_f32_16x16x32_bf16 v[70:73], v[166:169], v[230:233], v[70:73]
	v_mfma_f32_16x16x32_bf16 v[66:69], v[174:177], v[230:233], v[66:69]
	s_barrier
	s_add_i32 s34, s62, s45
	v_lshl_add_u64 v[136:137], s[38:39], 0, v[0:1]
	s_mov_b32 m0, s34
	ds_read_b128 v[178:181], v194 offset:16384
	ds_read_b128 v[182:185], v194 offset:17408
	ds_read_b128 v[186:189], v194 offset:18432
	ds_read_b128 v[196:199], v194 offset:19456
	ds_read_b128 v[200:203], v194 offset:20480
	ds_read_b128 v[204:207], v194 offset:21504
	ds_read_b128 v[226:229], v194 offset:22528
	ds_read_b128 v[230:233], v194 offset:23552
	global_load_lds_dwordx4 v[136:137], off
	s_add_i32 m0, s34, 0x2000
	s_add_u32 s34, s38, 0x80000
	v_lshl_add_u64 v[190:191], s[38:39], 0, v[130:131]
	s_addc_u32 s35, s39, 0
	s_add_i32 s62, s63, s45
	global_load_lds_dwordx4 v[190:191], off
	v_lshl_add_u64 v[208:209], s[34:35], 0, v[0:1]
	s_mov_b32 m0, s62
	v_lshl_add_u64 v[234:235], s[40:41], 0, v[130:131]
	global_load_lds_dwordx4 v[208:209], off
	v_lshl_add_u64 v[208:209], s[34:35], 0, v[130:131]
	s_add_i32 m0, s62, 0x2000
	s_nop 0
	global_load_lds_dwordx4 v[208:209], off
	v_lshl_add_u64 v[208:209], s[40:41], 0, v[0:1]
	s_mov_b32 m0, s46
	s_nop 0
	global_load_lds_dwordx4 v[208:209], off
	s_mov_b32 m0, s47
	s_nop 0
	global_load_lds_dwordx4 v[234:235], off
	s_waitcnt vmcnt(8)
	s_waitcnt lgkmcnt(0)
	s_barrier
; #define PG8_STAGE(bufoff, gbase, voff) do { _Pragma("unroll") for (int _i = 0; _i < 2; ++_i) \
;         __builtin_amdgcn_global_load_lds((const unsigned*)((const char*)(gbase) + (voff)[_i]), (PG8_LAS unsigned*)(lds + (bufoff) + ldsw + _i * 8192), 16, 0, 0); } while (0)
; #define PG8_LDA(dst, b, h) do { _Pragma("unroll") for (int m = 0; m < 4; ++m) _Pragma("unroll") for (int k = 0; k < 2; ++k) dst[m][k] = *(const PG8_LAS bf16x8*)(lds + PG8_SA(b, h) + aoff + m * 2048 + k * 1024); } while (0)
; #define PG8_LDB(dst, b, h) do { _Pragma("unroll") for (int n = 0; n < 2; ++n) _Pragma("unroll") for (int k = 0; k < 2; ++k) dst[n][k] = *(const PG8_LAS bf16x8*)(lds + PG8_SB(b, h) + boff + n * 2048 + k * 1024); } while (0)
; #define PG8_MMA(ai, bj, At, Bt) do { __builtin_amdgcn_s_setprio(1); _Pragma("unroll") for (int m = 0; m < 4; ++m) _Pragma("unroll") for (int n = 0; n < 2; ++n) _Pragma("unroll") for (int k = 0; k < 2; ++k) \
;         acc[ai][bj][m][n] = __builtin_amdgcn_mfma_f32_16x16x32_bf16(Bt[n][k], At[m][k], acc[ai][bj][m][n], 0, 0, 0); __builtin_amdgcn_s_setprio(0); } while (0)
; #define PG8_WAIT_V(n) asm volatile("s_waitcnt vmcnt(" #n ")" ::: "memory")
; #define PG8_WAIT_L(n) asm volatile("s_waitcnt lgkmcnt(" #n ")" ::: "memory")
; #define PG8_BAR __builtin_amdgcn_s_barrier()
; #define PG8_SCHED __builtin_amdgcn_sched_barrier(0)
; template <class Epi, class Sched, bool ALIGN_EPI = false, bool SP2 = false>
; __device__ __forceinline__ void gemm_phase(PG8_LAS unsigned char* lds, const Gemm g, const Sched& S, const Epi& E) {
;     ...
;             PG8_WAIT_V(8); PG8_WAIT_L(0); PG8_BAR; PG8_MMA(1, 0, At, B0); PG8_MMA(1, 1, At, B1); PG8_BAR; PG8_SCHED;
;             PG8_LDB(B0, 1, 0); PG8_LDB(B1, 1, 1); PG8_SCHED; PG8_LDA(At, 1, 0); PG8_STAGE(PG8_SA(0, 1), a2 + hstep, voffA);
;             PG8_WAIT_V(8); PG8_WAIT_L(0); PG8_BAR; PG8_MMA(0, 0, At, B0); PG8_MMA(0, 1, At, B1); PG8_BAR; PG8_SCHED;
	s_waitcnt lgkmcnt(0)
	v_mfma_f32_16x16x32_bf16 v[62:65], v[146:149], v[178:181], v[62:65]
	v_mfma_f32_16x16x32_bf16 v[58:61], v[154:157], v[178:181], v[58:61]
	v_mfma_f32_16x16x32_bf16 v[46:49], v[146:149], v[186:189], v[46:49]
	v_mfma_f32_16x16x32_bf16 v[42:45], v[154:157], v[186:189], v[42:45]
	v_mfma_f32_16x16x32_bf16 v[30:33], v[146:149], v[200:203], v[30:33]
	v_mfma_f32_16x16x32_bf16 v[26:29], v[154:157], v[200:203], v[26:29]
	v_mfma_f32_16x16x32_bf16 v[14:17], v[146:149], v[226:229], v[14:17]
	v_mfma_f32_16x16x32_bf16 v[10:13], v[154:157], v[226:229], v[10:13]
	v_mfma_f32_16x16x32_bf16 v[62:65], v[150:153], v[182:185], v[62:65]
	v_mfma_f32_16x16x32_bf16 v[58:61], v[158:161], v[182:185], v[58:61]
	v_mfma_f32_16x16x32_bf16 v[46:49], v[150:153], v[196:199], v[46:49]
	v_mfma_f32_16x16x32_bf16 v[42:45], v[158:161], v[196:199], v[42:45]
	v_mfma_f32_16x16x32_bf16 v[30:33], v[150:153], v[204:207], v[30:33]
	v_mfma_f32_16x16x32_bf16 v[26:29], v[158:161], v[204:207], v[26:29]
	v_mfma_f32_16x16x32_bf16 v[14:17], v[150:153], v[230:233], v[14:17]
	v_mfma_f32_16x16x32_bf16 v[10:13], v[158:161], v[230:233], v[10:13]
	v_mfma_f32_16x16x32_bf16 v[54:57], v[162:165], v[178:181], v[54:57]
	v_mfma_f32_16x16x32_bf16 v[50:53], v[170:173], v[178:181], v[50:53]
	v_mfma_f32_16x16x32_bf16 v[38:41], v[162:165], v[186:189], v[38:41]
	v_mfma_f32_16x16x32_bf16 v[34:37], v[170:173], v[186:189], v[34:37]
	v_mfma_f32_16x16x32_bf16 v[22:25], v[162:165], v[200:203], v[22:25]
	v_mfma_f32_16x16x32_bf16 v[18:21], v[170:173], v[200:203], v[18:21]
	v_mfma_f32_16x16x32_bf16 v[6:9], v[162:165], v[226:229], v[6:9]
	v_mfma_f32_16x16x32_bf16 v[2:5], v[170:173], v[226:229], v[2:5]
	v_mfma_f32_16x16x32_bf16 v[54:57], v[166:169], v[182:185], v[54:57]
	v_mfma_f32_16x16x32_bf16 v[50:53], v[174:177], v[182:185], v[50:53]
	v_mfma_f32_16x16x32_bf16 v[38:41], v[166:169], v[196:199], v[38:41]
	v_mfma_f32_16x16x32_bf16 v[34:37], v[174:177], v[196:199], v[34:37]
	v_mfma_f32_16x16x32_bf16 v[22:25], v[166:169], v[204:207], v[22:25]
	v_mfma_f32_16x16x32_bf16 v[18:21], v[174:177], v[204:207], v[18:21]
	v_mfma_f32_16x16x32_bf16 v[6:9], v[166:169], v[230:233], v[6:9]
	v_mfma_f32_16x16x32_bf16 v[2:5], v[174:177], v[230:233], v[2:5]
	s_barrier
	s_add_i32 s62, 0, 0x18000
	s_add_i32 s63, 0, 0x1c000
	v_add_u32_e32 v158, s62, v192
	v_add_u32_e32 v174, s63, v192
	ds_read_b128 v[146:149], v158
	ds_read_b128 v[150:153], v158 offset:1024
	ds_read_b128 v[154:157], v158 offset:2048
	ds_read_b128 v[158:161], v158 offset:3072
	ds_read_b128 v[162:165], v174
	ds_read_b128 v[166:169], v174 offset:1024
	ds_read_b128 v[170:173], v174 offset:2048
	ds_read_b128 v[174:177], v174 offset:3072
	s_add_u32 s34, s40, 0x80000
	s_addc_u32 s35, s41, 0
	s_mov_b32 m0, s48
	v_lshl_add_u64 v[236:237], s[34:35], 0, v[0:1]
	ds_read_b128 v[178:181], v194 offset:32768
	ds_read_b128 v[182:185], v194 offset:33792
	ds_read_b128 v[186:189], v194 offset:34816
	ds_read_b128 v[196:199], v194 offset:35840
	ds_read_b128 v[200:203], v194 offset:36864
	ds_read_b128 v[204:207], v194 offset:37888
	ds_read_b128 v[226:229], v194 offset:38912
	ds_read_b128 v[230:233], v194 offset:39936
	global_load_lds_dwordx4 v[236:237], off
	v_lshl_add_u64 v[236:237], s[34:35], 0, v[130:131]
	s_mov_b32 m0, s49
	s_nop 0
	global_load_lds_dwordx4 v[236:237], off
	s_waitcnt vmcnt(8)
	s_waitcnt lgkmcnt(0)
	s_barrier
	s_waitcnt lgkmcnt(0)
	v_mfma_f32_16x16x32_bf16 v[126:129], v[146:149], v[178:181], v[126:129]
	v_mfma_f32_16x16x32_bf16 v[122:125], v[154:157], v[178:181], v[122:125]
	v_mfma_f32_16x16x32_bf16 v[110:113], v[146:149], v[186:189], v[110:113]
	v_mfma_f32_16x16x32_bf16 v[106:109], v[154:157], v[186:189], v[106:109]
	v_mfma_f32_16x16x32_bf16 v[94:97], v[146:149], v[200:203], v[94:97]
	v_mfma_f32_16x16x32_bf16 v[90:93], v[154:157], v[200:203], v[90:93]
	v_mfma_f32_16x16x32_bf16 v[78:81], v[146:149], v[226:229], v[78:81]
	v_mfma_f32_16x16x32_bf16 v[74:77], v[154:157], v[226:229], v[74:77]
	v_mfma_f32_16x16x32_bf16 v[126:129], v[150:153], v[182:185], v[126:129]
	v_mfma_f32_16x16x32_bf16 v[122:125], v[158:161], v[182:185], v[122:125]
	v_mfma_f32_16x16x32_bf16 v[110:113], v[150:153], v[196:199], v[110:113]
	v_mfma_f32_16x16x32_bf16 v[106:109], v[158:161], v[196:199], v[106:109]
	v_mfma_f32_16x16x32_bf16 v[94:97], v[150:153], v[204:207], v[94:97]
	v_mfma_f32_16x16x32_bf16 v[90:93], v[158:161], v[204:207], v[90:93]
	v_mfma_f32_16x16x32_bf16 v[78:81], v[150:153], v[230:233], v[78:81]
	v_mfma_f32_16x16x32_bf16 v[74:77], v[158:161], v[230:233], v[74:77]
	v_mfma_f32_16x16x32_bf16 v[118:121], v[162:165], v[178:181], v[118:121]
	v_mfma_f32_16x16x32_bf16 v[114:117], v[170:173], v[178:181], v[114:117]
	v_mfma_f32_16x16x32_bf16 v[102:105], v[162:165], v[186:189], v[102:105]
	v_mfma_f32_16x16x32_bf16 v[98:101], v[170:173], v[186:189], v[98:101]
	v_mfma_f32_16x16x32_bf16 v[86:89], v[162:165], v[200:203], v[86:89]
	v_mfma_f32_16x16x32_bf16 v[82:85], v[170:173], v[200:203], v[82:85]
	v_mfma_f32_16x16x32_bf16 v[70:73], v[162:165], v[226:229], v[70:73]
	v_mfma_f32_16x16x32_bf16 v[66:69], v[170:173], v[226:229], v[66:69]
	v_mfma_f32_16x16x32_bf16 v[118:121], v[166:169], v[182:185], v[118:121]
	v_mfma_f32_16x16x32_bf16 v[114:117], v[174:177], v[182:185], v[114:117]
	v_mfma_f32_16x16x32_bf16 v[102:105], v[166:169], v[196:199], v[102:105]
	v_mfma_f32_16x16x32_bf16 v[98:101], v[174:177], v[196:199], v[98:101]
	v_mfma_f32_16x16x32_bf16 v[86:89], v[166:169], v[204:207], v[86:89]
	v_mfma_f32_16x16x32_bf16 v[82:85], v[174:177], v[204:207], v[82:85]
	v_mfma_f32_16x16x32_bf16 v[70:73], v[166:169], v[230:233], v[70:73]
	v_mfma_f32_16x16x32_bf16 v[66:69], v[174:177], v[230:233], v[66:69]
	s_barrier
; #define PG8_STAGE(bufoff, gbase, voff) do { _Pragma("unroll") for (int _i = 0; _i < 2; ++_i) \
;         __builtin_amdgcn_global_load_lds((const unsigned*)((const char*)(gbase) + (voff)[_i]), (PG8_LAS unsigned*)(lds + (bufoff) + ldsw + _i * 8192), 16, 0, 0); } while (0)
; #define PG8_LDA(dst, b, h) do { _Pragma("unroll") for (int m = 0; m < 4; ++m) _Pragma("unroll") for (int k = 0; k < 2; ++k) dst[m][k] = *(const PG8_LAS bf16x8*)(lds + PG8_SA(b, h) + aoff + m * 2048 + k * 1024); } while (0)
; #define PG8_MMA(ai, bj, At, Bt) do { __builtin_amdgcn_s_setprio(1); _Pragma("unroll") for (int m = 0; m < 4; ++m) _Pragma("unroll") for (int n = 0; n < 2; ++n) _Pragma("unroll") for (int k = 0; k < 2; ++k) \
;         acc[ai][bj][m][n] = __builtin_amdgcn_mfma_f32_16x16x32_bf16(Bt[n][k], At[m][k], acc[ai][bj][m][n], 0, 0, 0); __builtin_amdgcn_s_setprio(0); } while (0)
; #define PG8_WAIT_V(n) asm volatile("s_waitcnt vmcnt(" #n ")" ::: "memory")
; #define PG8_WAIT_L(n) asm volatile("s_waitcnt lgkmcnt(" #n ")" ::: "memory")
; #define PG8_BAR __builtin_amdgcn_s_barrier()
; #define PG8_SCHED __builtin_amdgcn_sched_barrier(0)
; template <class Epi, class Sched, bool ALIGN_EPI = false, bool SP2 = false>
; __device__ __forceinline__ void gemm_phase(PG8_LAS unsigned char* lds, const Gemm g, const Sched& S, const Epi& E) {
;     ...
;             PG8_LDA(At, 1, 1); PG8_STAGE(PG8_SB(1, 0), b3, voffB); PG8_STAGE(PG8_SB(1, 1), b3 + hstep, voffB); PG8_STAGE(PG8_SA(1, 0), a3, voffA);
;             PG8_WAIT_V(8); PG8_WAIT_L(0); PG8_BAR; PG8_MMA(1, 0, At, B0); PG8_MMA(1, 1, At, B1); PG8_BAR; PG8_SCHED;
	s_add_i32 s34, s62, s45
	v_lshl_add_u64 v[136:137], v[136:137], 0, s[0:1]
	s_mov_b32 m0, s34
	ds_read_b128 v[178:181], v194 offset:49152
	ds_read_b128 v[182:185], v194 offset:50176
	ds_read_b128 v[186:189], v194 offset:51200
	ds_read_b128 v[196:199], v194 offset:52224
	ds_read_b128 v[200:203], v194 offset:53248
	ds_read_b128 v[204:207], v194 offset:54272
	ds_read_b128 v[226:229], v194 offset:55296
	ds_read_b128 v[230:233], v194 offset:56320
	global_load_lds_dwordx4 v[136:137], off
	s_add_i32 m0, s34, 0x2000
	s_add_u32 s34, s38, 0x80080
	v_lshl_add_u64 v[136:137], v[190:191], 0, s[0:1]
	s_addc_u32 s35, s39, 0
	s_add_i32 s38, s63, s45
	global_load_lds_dwordx4 v[136:137], off
	v_lshl_add_u64 v[136:137], s[34:35], 0, v[0:1]
	s_mov_b32 m0, s38
	s_nop 0
	global_load_lds_dwordx4 v[136:137], off
	v_lshl_add_u64 v[136:137], s[34:35], 0, v[130:131]
	s_add_i32 m0, s38, 0x2000
	s_nop 0
	global_load_lds_dwordx4 v[136:137], off
	v_lshl_add_u64 v[136:137], v[208:209], 0, s[0:1]
	s_mov_b32 m0, s51
	s_nop 0
	global_load_lds_dwordx4 v[136:137], off
	v_lshl_add_u64 v[136:137], v[234:235], 0, s[0:1]
	s_mov_b32 m0, s52
	s_nop 0
	global_load_lds_dwordx4 v[136:137], off
	s_waitcnt vmcnt(8)
	s_waitcnt lgkmcnt(0)
	s_barrier
	s_waitcnt lgkmcnt(0)
	v_mfma_f32_16x16x32_bf16 v[62:65], v[146:149], v[178:181], v[62:65]
	v_mfma_f32_16x16x32_bf16 v[58:61], v[154:157], v[178:181], v[58:61]
	v_mfma_f32_16x16x32_bf16 v[46:49], v[146:149], v[186:189], v[46:49]
	v_mfma_f32_16x16x32_bf16 v[42:45], v[154:157], v[186:189], v[42:45]
	v_mfma_f32_16x16x32_bf16 v[30:33], v[146:149], v[200:203], v[30:33]
	v_mfma_f32_16x16x32_bf16 v[26:29], v[154:157], v[200:203], v[26:29]
	v_mfma_f32_16x16x32_bf16 v[14:17], v[146:149], v[226:229], v[14:17]
	v_mfma_f32_16x16x32_bf16 v[10:13], v[154:157], v[226:229], v[10:13]
	v_mfma_f32_16x16x32_bf16 v[62:65], v[150:153], v[182:185], v[62:65]
	v_mfma_f32_16x16x32_bf16 v[58:61], v[158:161], v[182:185], v[58:61]
	v_mfma_f32_16x16x32_bf16 v[46:49], v[150:153], v[196:199], v[46:49]
	v_mfma_f32_16x16x32_bf16 v[42:45], v[158:161], v[196:199], v[42:45]
	v_mfma_f32_16x16x32_bf16 v[30:33], v[150:153], v[204:207], v[30:33]
	v_mfma_f32_16x16x32_bf16 v[26:29], v[158:161], v[204:207], v[26:29]
	v_mfma_f32_16x16x32_bf16 v[14:17], v[150:153], v[230:233], v[14:17]
	v_mfma_f32_16x16x32_bf16 v[10:13], v[158:161], v[230:233], v[10:13]
	v_mfma_f32_16x16x32_bf16 v[54:57], v[162:165], v[178:181], v[54:57]
	v_mfma_f32_16x16x32_bf16 v[50:53], v[170:173], v[178:181], v[50:53]
	v_mfma_f32_16x16x32_bf16 v[38:41], v[162:165], v[186:189], v[38:41]
	v_mfma_f32_16x16x32_bf16 v[34:37], v[170:173], v[186:189], v[34:37]
	v_mfma_f32_16x16x32_bf16 v[22:25], v[162:165], v[200:203], v[22:25]
	v_mfma_f32_16x16x32_bf16 v[18:21], v[170:173], v[200:203], v[18:21]
	v_mfma_f32_16x16x32_bf16 v[6:9], v[162:165], v[226:229], v[6:9]
	v_mfma_f32_16x16x32_bf16 v[2:5], v[170:173], v[226:229], v[2:5]
	v_mfma_f32_16x16x32_bf16 v[54:57], v[166:169], v[182:185], v[54:57]
	v_mfma_f32_16x16x32_bf16 v[50:53], v[174:177], v[182:185], v[50:53]
	v_mfma_f32_16x16x32_bf16 v[38:41], v[166:169], v[196:199], v[38:41]
	v_mfma_f32_16x16x32_bf16 v[34:37], v[174:177], v[196:199], v[34:37]
	v_mfma_f32_16x16x32_bf16 v[22:25], v[166:169], v[204:207], v[22:25]
	v_mfma_f32_16x16x32_bf16 v[18:21], v[174:177], v[204:207], v[18:21]
	v_mfma_f32_16x16x32_bf16 v[6:9], v[166:169], v[230:233], v[6:9]
	v_mfma_f32_16x16x32_bf16 v[2:5], v[174:177], v[230:233], v[2:5]
	s_barrier
	s_add_i32 s57, s57, 2
	s_add_u32 s55, s55, 0x100
	s_addc_u32 s56, s56, 0
	s_cmp_gt_u32 s57, 29
	s_mov_b64 s[34:35], s[36:37]
	s_cbranch_scc0 .LBB0_1193
	s_and_b64 vcc, exec, s[10:11]
	s_cbranch_vccz .LBB0_1196
	s_barrier

; #define PG8_STAGE(bufoff, gbase, voff) do { _Pragma("unroll") for (int _i = 0; _i < 2; ++_i) \
;         __builtin_amdgcn_global_load_lds((const unsigned*)((const char*)(gbase) + (voff)[_i]), (PG8_LAS unsigned*)(lds + (bufoff) + ldsw + _i * 8192), 16, 0, 0); } while (0)
; #define PG8_LDA(dst, b, h) do { _Pragma("unroll") for (int m = 0; m < 4; ++m) _Pragma("unroll") for (int k = 0; k < 2; ++k) dst[m][k] = *(const PG8_LAS bf16x8*)(lds + PG8_SA(b, h) + aoff + m * 2048 + k * 1024); } while (0)
; #define PG8_LDB(dst, b, h) do { _Pragma("unroll") for (int n = 0; n < 2; ++n) _Pragma("unroll") for (int k = 0; k < 2; ++k) dst[n][k] = *(const PG8_LAS bf16x8*)(lds + PG8_SB(b, h) + boff + n * 2048 + k * 1024); } while (0)
; #define PG8_MMA(ai, bj, At, Bt) do { __builtin_amdgcn_s_setprio(1); _Pragma("unroll") for (int m = 0; m < 4; ++m) _Pragma("unroll") for (int n = 0; n < 2; ++n) _Pragma("unroll") for (int k = 0; k < 2; ++k) \
;         acc[ai][bj][m][n] = __builtin_amdgcn_mfma_f32_16x16x32_bf16(Bt[n][k], At[m][k], acc[ai][bj][m][n], 0, 0, 0); __builtin_amdgcn_s_setprio(0); } while (0)
; #define PG8_WAIT_V(n) asm volatile("s_waitcnt vmcnt(" #n ")" ::: "memory")
; #define PG8_WAIT_L(n) asm volatile("s_waitcnt lgkmcnt(" #n ")" ::: "memory")
; #define PG8_BAR __builtin_amdgcn_s_barrier()
; #define PG8_SCHED __builtin_amdgcn_sched_barrier(0)
; template <class Epi, class Sched, bool ALIGN_EPI = false, bool SP2 = false>
; __device__ __forceinline__ void gemm_phase(PG8_LAS unsigned char* lds, const Gemm g, const Sched& S, const Epi& E) {
;     ...
;             PG8_LDB(B0, 0, 0); PG8_LDB(B1, 0, 1); PG8_SCHED; PG8_LDA(At, 0, 0); PG8_STAGE(PG8_SA(1, 1), a1 + hstep, voffA);
;             PG8_WAIT_V(8); PG8_WAIT_L(0); PG8_BAR; PG8_MMA(0, 0, At, B0); PG8_MMA(0, 1, At, B1); PG8_BAR; PG8_SCHED;
;             PG8_LDA(At, 0, 1); PG8_STAGE(PG8_SB(0, 0), b2, voffB); PG8_STAGE(PG8_SB(0, 1), b2 + hstep, voffB); PG8_STAGE(PG8_SA(0, 0), a2, voffA);
.LBB0_1295:
	s_add_u32 s36, s34, 0xfff80080
	s_addc_u32 s37, s35, -1
	s_add_i32 s75, 0, 0x10000
	s_cmp_eq_u32 s74, 12
	s_cselect_b32 s39, s7, s37
	s_cselect_b32 s38, s9, s36
	s_cselect_b32 s37, s25, s73
	s_cselect_b32 s36, s27, s72
	s_add_i32 s78, 0, 0x14000
	v_add_u32_e32 v164, s75, v179
	v_add_u32_e32 v176, s78, v179
	ds_read_b128 v[130:133], v164
	ds_read_b128 v[134:137], v164 offset:1024
	ds_read_b128 v[160:163], v164 offset:2048
	ds_read_b128 v[164:167], v164 offset:3072
	ds_read_b128 v[168:171], v176
	ds_read_b128 v[172:175], v176 offset:1024
	ds_read_b128 v[180:183], v176 offset:2048
	ds_read_b128 v[184:187], v176 offset:3072
	v_lshl_add_u64 v[176:177], s[34:35], 0, v[156:157]
	s_add_i32 m0, s55, 0xc000
	ds_read_b128 v[188:191], v193
	ds_read_b128 v[194:197], v193 offset:1024
	ds_read_b128 v[198:201], v193 offset:2048
	ds_read_b128 v[202:205], v193 offset:3072
	ds_read_b128 v[206:209], v193 offset:4096
	ds_read_b128 v[226:229], v193 offset:5120
	ds_read_b128 v[230:233], v193 offset:6144
	ds_read_b128 v[234:237], v193 offset:7168
	global_load_lds_dwordx4 v[176:177], off
	v_lshl_add_u64 v[176:177], s[34:35], 0, v[158:159]
	s_add_i32 m0, s55, 0xe000
	s_nop 0
	global_load_lds_dwordx4 v[176:177], off
	s_waitcnt vmcnt(8)
	s_waitcnt lgkmcnt(0)
	s_barrier
	s_waitcnt lgkmcnt(0)
	v_mfma_f32_16x16x32_bf16 v[126:129], v[130:133], v[188:191], v[126:129]
	v_mfma_f32_16x16x32_bf16 v[122:125], v[160:163], v[188:191], v[122:125]
	v_mfma_f32_16x16x32_bf16 v[110:113], v[130:133], v[198:201], v[110:113]
	v_mfma_f32_16x16x32_bf16 v[106:109], v[160:163], v[198:201], v[106:109]
	v_mfma_f32_16x16x32_bf16 v[94:97], v[130:133], v[206:209], v[94:97]
	v_mfma_f32_16x16x32_bf16 v[90:93], v[160:163], v[206:209], v[90:93]
	v_mfma_f32_16x16x32_bf16 v[78:81], v[130:133], v[230:233], v[78:81]
	v_mfma_f32_16x16x32_bf16 v[74:77], v[160:163], v[230:233], v[74:77]
	v_mfma_f32_16x16x32_bf16 v[126:129], v[134:137], v[194:197], v[126:129]
	v_mfma_f32_16x16x32_bf16 v[122:125], v[164:167], v[194:197], v[122:125]
	v_mfma_f32_16x16x32_bf16 v[110:113], v[134:137], v[202:205], v[110:113]
	v_mfma_f32_16x16x32_bf16 v[106:109], v[164:167], v[202:205], v[106:109]
	v_mfma_f32_16x16x32_bf16 v[94:97], v[134:137], v[226:229], v[94:97]
	v_mfma_f32_16x16x32_bf16 v[90:93], v[164:167], v[226:229], v[90:93]
	v_mfma_f32_16x16x32_bf16 v[78:81], v[134:137], v[234:237], v[78:81]
	v_mfma_f32_16x16x32_bf16 v[74:77], v[164:167], v[234:237], v[74:77]
	v_mfma_f32_16x16x32_bf16 v[118:121], v[168:171], v[188:191], v[118:121]
	v_mfma_f32_16x16x32_bf16 v[114:117], v[180:183], v[188:191], v[114:117]
	v_mfma_f32_16x16x32_bf16 v[102:105], v[168:171], v[198:201], v[102:105]
	v_mfma_f32_16x16x32_bf16 v[98:101], v[180:183], v[198:201], v[98:101]
	v_mfma_f32_16x16x32_bf16 v[86:89], v[168:171], v[206:209], v[86:89]
	v_mfma_f32_16x16x32_bf16 v[82:85], v[180:183], v[206:209], v[82:85]
	v_mfma_f32_16x16x32_bf16 v[70:73], v[168:171], v[230:233], v[70:73]
	v_mfma_f32_16x16x32_bf16 v[66:69], v[180:183], v[230:233], v[66:69]
	v_mfma_f32_16x16x32_bf16 v[118:121], v[172:175], v[194:197], v[118:121]
	v_mfma_f32_16x16x32_bf16 v[114:117], v[184:187], v[194:197], v[114:117]
	v_mfma_f32_16x16x32_bf16 v[102:105], v[172:175], v[202:205], v[102:105]
	v_mfma_f32_16x16x32_bf16 v[98:101], v[184:187], v[202:205], v[98:101]
	v_mfma_f32_16x16x32_bf16 v[86:89], v[172:175], v[226:229], v[86:89]
	v_mfma_f32_16x16x32_bf16 v[82:85], v[184:187], v[226:229], v[82:85]
	v_mfma_f32_16x16x32_bf16 v[70:73], v[172:175], v[234:237], v[70:73]
	v_mfma_f32_16x16x32_bf16 v[66:69], v[184:187], v[234:237], v[66:69]
	s_barrier
	s_add_i32 s75, s75, s54
	v_lshl_add_u64 v[176:177], s[36:37], 0, v[0:1]
	s_mov_b32 m0, s75
	ds_read_b128 v[188:191], v193 offset:16384
	ds_read_b128 v[194:197], v193 offset:17408
	ds_read_b128 v[198:201], v193 offset:18432
	ds_read_b128 v[202:205], v193 offset:19456
	ds_read_b128 v[206:209], v193 offset:20480
	ds_read_b128 v[226:229], v193 offset:21504
	ds_read_b128 v[230:233], v193 offset:22528
	ds_read_b128 v[234:237], v193 offset:23552
	global_load_lds_dwordx4 v[176:177], off
	s_add_i32 m0, s75, 0x2000
	s_add_u32 s76, s36, 0x80000
	v_lshl_add_u64 v[238:239], s[36:37], 0, v[150:151]
	s_addc_u32 s77, s37, 0
	s_add_i32 s75, s78, s54
	global_load_lds_dwordx4 v[238:239], off
	v_lshl_add_u64 v[240:241], s[76:77], 0, v[0:1]
	s_mov_b32 m0, s75
	v_lshl_add_u64 v[242:243], s[38:39], 0, v[148:149]
	global_load_lds_dwordx4 v[240:241], off
	v_lshl_add_u64 v[240:241], s[76:77], 0, v[150:151]
	s_add_i32 m0, s75, 0x2000
	s_nop 0
	global_load_lds_dwordx4 v[240:241], off
	v_lshl_add_u64 v[240:241], s[38:39], 0, v[146:147]
	s_mov_b32 m0, s55
	s_nop 0
	global_load_lds_dwordx4 v[240:241], off
	s_mov_b32 m0, s56
	s_nop 0
	global_load_lds_dwordx4 v[242:243], off
	s_waitcnt vmcnt(8)
	s_waitcnt lgkmcnt(0)
	s_barrier
; #define PG8_STAGE(bufoff, gbase, voff) do { _Pragma("unroll") for (int _i = 0; _i < 2; ++_i) \
;         __builtin_amdgcn_global_load_lds((const unsigned*)((const char*)(gbase) + (voff)[_i]), (PG8_LAS unsigned*)(lds + (bufoff) + ldsw + _i * 8192), 16, 0, 0); } while (0)
; #define PG8_LDA(dst, b, h) do { _Pragma("unroll") for (int m = 0; m < 4; ++m) _Pragma("unroll") for (int k = 0; k < 2; ++k) dst[m][k] = *(const PG8_LAS bf16x8*)(lds + PG8_SA(b, h) + aoff + m * 2048 + k * 1024); } while (0)
; #define PG8_LDB(dst, b, h) do { _Pragma("unroll") for (int n = 0; n < 2; ++n) _Pragma("unroll") for (int k = 0; k < 2; ++k) dst[n][k] = *(const PG8_LAS bf16x8*)(lds + PG8_SB(b, h) + boff + n * 2048 + k * 1024); } while (0)
; #define PG8_MMA(ai, bj, At, Bt) do { __builtin_amdgcn_s_setprio(1); _Pragma("unroll") for (int m = 0; m < 4; ++m) _Pragma("unroll") for (int n = 0; n < 2; ++n) _Pragma("unroll") for (int k = 0; k < 2; ++k) \
;         acc[ai][bj][m][n] = __builtin_amdgcn_mfma_f32_16x16x32_bf16(Bt[n][k], At[m][k], acc[ai][bj][m][n], 0, 0, 0); __builtin_amdgcn_s_setprio(0); } while (0)
; #define PG8_WAIT_V(n) asm volatile("s_waitcnt vmcnt(" #n ")" ::: "memory")
; #define PG8_WAIT_L(n) asm volatile("s_waitcnt lgkmcnt(" #n ")" ::: "memory")
; #define PG8_BAR __builtin_amdgcn_s_barrier()
; #define PG8_SCHED __builtin_amdgcn_sched_barrier(0)
; template <class Epi, class Sched, bool ALIGN_EPI = false, bool SP2 = false>
; __device__ __forceinline__ void gemm_phase(PG8_LAS unsigned char* lds, const Gemm g, const Sched& S, const Epi& E) {
;     ...
;             PG8_WAIT_V(8); PG8_WAIT_L(0); PG8_BAR; PG8_MMA(1, 0, At, B0); PG8_MMA(1, 1, At, B1); PG8_BAR; PG8_SCHED;
;             PG8_LDB(B0, 1, 0); PG8_LDB(B1, 1, 1); PG8_SCHED; PG8_LDA(At, 1, 0); PG8_STAGE(PG8_SA(0, 1), a2 + hstep, voffA);
;             PG8_WAIT_V(8); PG8_WAIT_L(0); PG8_BAR; PG8_MMA(0, 0, At, B0); PG8_MMA(0, 1, At, B1); PG8_BAR; PG8_SCHED;
	s_waitcnt lgkmcnt(0)
	v_mfma_f32_16x16x32_bf16 v[62:65], v[130:133], v[188:191], v[62:65]
	v_mfma_f32_16x16x32_bf16 v[58:61], v[160:163], v[188:191], v[58:61]
	v_mfma_f32_16x16x32_bf16 v[46:49], v[130:133], v[198:201], v[46:49]
	v_mfma_f32_16x16x32_bf16 v[42:45], v[160:163], v[198:201], v[42:45]
	v_mfma_f32_16x16x32_bf16 v[30:33], v[130:133], v[206:209], v[30:33]
	v_mfma_f32_16x16x32_bf16 v[26:29], v[160:163], v[206:209], v[26:29]
	v_mfma_f32_16x16x32_bf16 v[14:17], v[130:133], v[230:233], v[14:17]
	v_mfma_f32_16x16x32_bf16 v[10:13], v[160:163], v[230:233], v[10:13]
	v_mfma_f32_16x16x32_bf16 v[62:65], v[134:137], v[194:197], v[62:65]
	v_mfma_f32_16x16x32_bf16 v[58:61], v[164:167], v[194:197], v[58:61]
	v_mfma_f32_16x16x32_bf16 v[46:49], v[134:137], v[202:205], v[46:49]
	v_mfma_f32_16x16x32_bf16 v[42:45], v[164:167], v[202:205], v[42:45]
	v_mfma_f32_16x16x32_bf16 v[30:33], v[134:137], v[226:229], v[30:33]
	v_mfma_f32_16x16x32_bf16 v[26:29], v[164:167], v[226:229], v[26:29]
	v_mfma_f32_16x16x32_bf16 v[14:17], v[134:137], v[234:237], v[14:17]
	v_mfma_f32_16x16x32_bf16 v[10:13], v[164:167], v[234:237], v[10:13]
	v_mfma_f32_16x16x32_bf16 v[54:57], v[168:171], v[188:191], v[54:57]
	v_mfma_f32_16x16x32_bf16 v[50:53], v[180:183], v[188:191], v[50:53]
	v_mfma_f32_16x16x32_bf16 v[38:41], v[168:171], v[198:201], v[38:41]
	v_mfma_f32_16x16x32_bf16 v[34:37], v[180:183], v[198:201], v[34:37]
	v_mfma_f32_16x16x32_bf16 v[22:25], v[168:171], v[206:209], v[22:25]
	v_mfma_f32_16x16x32_bf16 v[18:21], v[180:183], v[206:209], v[18:21]
	v_mfma_f32_16x16x32_bf16 v[6:9], v[168:171], v[230:233], v[6:9]
	v_mfma_f32_16x16x32_bf16 v[2:5], v[180:183], v[230:233], v[2:5]
	v_mfma_f32_16x16x32_bf16 v[54:57], v[172:175], v[194:197], v[54:57]
	v_mfma_f32_16x16x32_bf16 v[50:53], v[184:187], v[194:197], v[50:53]
	v_mfma_f32_16x16x32_bf16 v[38:41], v[172:175], v[202:205], v[38:41]
	v_mfma_f32_16x16x32_bf16 v[34:37], v[184:187], v[202:205], v[34:37]
	v_mfma_f32_16x16x32_bf16 v[22:25], v[172:175], v[226:229], v[22:25]
	v_mfma_f32_16x16x32_bf16 v[18:21], v[184:187], v[226:229], v[18:21]
	v_mfma_f32_16x16x32_bf16 v[6:9], v[172:175], v[234:237], v[6:9]
	v_mfma_f32_16x16x32_bf16 v[2:5], v[184:187], v[234:237], v[2:5]
	s_barrier
	s_add_i32 s75, 0, 0x18000
	s_add_i32 s76, 0, 0x1c000
	v_add_u32_e32 v164, s75, v179
	v_add_u32_e32 v178, s76, v179
	ds_read_b128 v[130:133], v164
	ds_read_b128 v[134:137], v164 offset:1024
	ds_read_b128 v[160:163], v164 offset:2048
	ds_read_b128 v[164:167], v164 offset:3072
	ds_read_b128 v[168:171], v178
	ds_read_b128 v[172:175], v178 offset:1024
	ds_read_b128 v[180:183], v178 offset:2048
	ds_read_b128 v[184:187], v178 offset:3072
	s_add_u32 s38, s38, 0x80000
	s_addc_u32 s39, s39, 0
	s_mov_b32 m0, s57
	v_lshl_add_u64 v[244:245], s[38:39], 0, v[146:147]
	ds_read_b128 v[188:191], v193 offset:32768
	ds_read_b128 v[194:197], v193 offset:33792
	ds_read_b128 v[198:201], v193 offset:34816
	ds_read_b128 v[202:205], v193 offset:35840
	ds_read_b128 v[206:209], v193 offset:36864
	ds_read_b128 v[226:229], v193 offset:37888
	ds_read_b128 v[230:233], v193 offset:38912
	ds_read_b128 v[234:237], v193 offset:39936
	global_load_lds_dwordx4 v[244:245], off
	v_lshl_add_u64 v[244:245], s[38:39], 0, v[148:149]
	s_mov_b32 m0, s63
	s_nop 0
	global_load_lds_dwordx4 v[244:245], off
	s_waitcnt vmcnt(8)
	s_waitcnt lgkmcnt(0)
	s_barrier
	s_waitcnt lgkmcnt(0)
	v_mfma_f32_16x16x32_bf16 v[126:129], v[130:133], v[188:191], v[126:129]
	v_mfma_f32_16x16x32_bf16 v[122:125], v[160:163], v[188:191], v[122:125]
	v_mfma_f32_16x16x32_bf16 v[110:113], v[130:133], v[198:201], v[110:113]
	v_mfma_f32_16x16x32_bf16 v[106:109], v[160:163], v[198:201], v[106:109]
	v_mfma_f32_16x16x32_bf16 v[94:97], v[130:133], v[206:209], v[94:97]
	v_mfma_f32_16x16x32_bf16 v[90:93], v[160:163], v[206:209], v[90:93]
	v_mfma_f32_16x16x32_bf16 v[78:81], v[130:133], v[230:233], v[78:81]
	v_mfma_f32_16x16x32_bf16 v[74:77], v[160:163], v[230:233], v[74:77]
	v_mfma_f32_16x16x32_bf16 v[126:129], v[134:137], v[194:197], v[126:129]
	v_mfma_f32_16x16x32_bf16 v[122:125], v[164:167], v[194:197], v[122:125]
	v_mfma_f32_16x16x32_bf16 v[110:113], v[134:137], v[202:205], v[110:113]
	v_mfma_f32_16x16x32_bf16 v[106:109], v[164:167], v[202:205], v[106:109]
	v_mfma_f32_16x16x32_bf16 v[94:97], v[134:137], v[226:229], v[94:97]
	v_mfma_f32_16x16x32_bf16 v[90:93], v[164:167], v[226:229], v[90:93]
	v_mfma_f32_16x16x32_bf16 v[78:81], v[134:137], v[234:237], v[78:81]
	v_mfma_f32_16x16x32_bf16 v[74:77], v[164:167], v[234:237], v[74:77]
	v_mfma_f32_16x16x32_bf16 v[118:121], v[168:171], v[188:191], v[118:121]
	v_mfma_f32_16x16x32_bf16 v[114:117], v[180:183], v[188:191], v[114:117]
	v_mfma_f32_16x16x32_bf16 v[102:105], v[168:171], v[198:201], v[102:105]
	v_mfma_f32_16x16x32_bf16 v[98:101], v[180:183], v[198:201], v[98:101]
	v_mfma_f32_16x16x32_bf16 v[86:89], v[168:171], v[206:209], v[86:89]
	v_mfma_f32_16x16x32_bf16 v[82:85], v[180:183], v[206:209], v[82:85]
	v_mfma_f32_16x16x32_bf16 v[70:73], v[168:171], v[230:233], v[70:73]
	v_mfma_f32_16x16x32_bf16 v[66:69], v[180:183], v[230:233], v[66:69]
	v_mfma_f32_16x16x32_bf16 v[118:121], v[172:175], v[194:197], v[118:121]
	v_mfma_f32_16x16x32_bf16 v[114:117], v[184:187], v[194:197], v[114:117]
	v_mfma_f32_16x16x32_bf16 v[102:105], v[172:175], v[202:205], v[102:105]
	v_mfma_f32_16x16x32_bf16 v[98:101], v[184:187], v[202:205], v[98:101]
	v_mfma_f32_16x16x32_bf16 v[86:89], v[172:175], v[226:229], v[86:89]
	v_mfma_f32_16x16x32_bf16 v[82:85], v[184:187], v[226:229], v[82:85]
	v_mfma_f32_16x16x32_bf16 v[70:73], v[172:175], v[234:237], v[70:73]
	v_mfma_f32_16x16x32_bf16 v[66:69], v[184:187], v[234:237], v[66:69]
	s_barrier
; #define PG8_STAGE(bufoff, gbase, voff) do { _Pragma("unroll") for (int _i = 0; _i < 2; ++_i) \
;         __builtin_amdgcn_global_load_lds((const unsigned*)((const char*)(gbase) + (voff)[_i]), (PG8_LAS unsigned*)(lds + (bufoff) + ldsw + _i * 8192), 16, 0, 0); } while (0)
; #define PG8_LDA(dst, b, h) do { _Pragma("unroll") for (int m = 0; m < 4; ++m) _Pragma("unroll") for (int k = 0; k < 2; ++k) dst[m][k] = *(const PG8_LAS bf16x8*)(lds + PG8_SA(b, h) + aoff + m * 2048 + k * 1024); } while (0)
; #define PG8_MMA(ai, bj, At, Bt) do { __builtin_amdgcn_s_setprio(1); _Pragma("unroll") for (int m = 0; m < 4; ++m) _Pragma("unroll") for (int n = 0; n < 2; ++n) _Pragma("unroll") for (int k = 0; k < 2; ++k) \
;         acc[ai][bj][m][n] = __builtin_amdgcn_mfma_f32_16x16x32_bf16(Bt[n][k], At[m][k], acc[ai][bj][m][n], 0, 0, 0); __builtin_amdgcn_s_setprio(0); } while (0)
; #define PG8_WAIT_V(n) asm volatile("s_waitcnt vmcnt(" #n ")" ::: "memory")
; #define PG8_WAIT_L(n) asm volatile("s_waitcnt lgkmcnt(" #n ")" ::: "memory")
; #define PG8_BAR __builtin_amdgcn_s_barrier()
; #define PG8_SCHED __builtin_amdgcn_sched_barrier(0)
; template <class Epi, class Sched, bool ALIGN_EPI = false, bool SP2 = false>
; __device__ __forceinline__ void gemm_phase(PG8_LAS unsigned char* lds, const Gemm g, const Sched& S, const Epi& E) {
;     ...
;             PG8_LDA(At, 1, 1); PG8_STAGE(PG8_SB(1, 0), b3, voffB); PG8_STAGE(PG8_SB(1, 1), b3 + hstep, voffB); PG8_STAGE(PG8_SA(1, 0), a3, voffA);
;             PG8_WAIT_V(8); PG8_WAIT_L(0); PG8_BAR; PG8_MMA(1, 0, At, B0); PG8_MMA(1, 1, At, B1); PG8_BAR; PG8_SCHED;
	s_add_i32 s38, s75, s54
	v_lshl_add_u64 v[176:177], v[176:177], 0, s[0:1]
	s_mov_b32 m0, s38
	ds_read_b128 v[188:191], v193 offset:49152
	ds_read_b128 v[194:197], v193 offset:50176
	ds_read_b128 v[198:201], v193 offset:51200
	ds_read_b128 v[202:205], v193 offset:52224
	ds_read_b128 v[206:209], v193 offset:53248
	ds_read_b128 v[226:229], v193 offset:54272
	ds_read_b128 v[230:233], v193 offset:55296
	ds_read_b128 v[234:237], v193 offset:56320
	global_load_lds_dwordx4 v[176:177], off
	s_add_i32 m0, s38, 0x2000
	s_add_u32 s36, s36, 0x80080
	v_lshl_add_u64 v[176:177], v[238:239], 0, s[0:1]
	s_addc_u32 s37, s37, 0
	s_add_i32 s38, s76, s54
	global_load_lds_dwordx4 v[176:177], off
	v_lshl_add_u64 v[176:177], s[36:37], 0, v[0:1]
	s_mov_b32 m0, s38
	s_nop 0
	global_load_lds_dwordx4 v[176:177], off
	v_lshl_add_u64 v[176:177], s[36:37], 0, v[150:151]
	s_add_i32 m0, s38, 0x2000
	s_nop 0
	global_load_lds_dwordx4 v[176:177], off
	v_lshl_add_u64 v[176:177], v[240:241], 0, s[0:1]
	s_mov_b32 m0, s68
	s_nop 0
	global_load_lds_dwordx4 v[176:177], off
	v_lshl_add_u64 v[176:177], v[242:243], 0, s[0:1]
	s_mov_b32 m0, s69
	s_nop 0
	global_load_lds_dwordx4 v[176:177], off
	s_waitcnt vmcnt(8)
	s_waitcnt lgkmcnt(0)
	s_barrier
	s_waitcnt lgkmcnt(0)
	v_mfma_f32_16x16x32_bf16 v[62:65], v[130:133], v[188:191], v[62:65]
	v_mfma_f32_16x16x32_bf16 v[58:61], v[160:163], v[188:191], v[58:61]
	v_mfma_f32_16x16x32_bf16 v[46:49], v[130:133], v[198:201], v[46:49]
	v_mfma_f32_16x16x32_bf16 v[42:45], v[160:163], v[198:201], v[42:45]
	v_mfma_f32_16x16x32_bf16 v[30:33], v[130:133], v[206:209], v[30:33]
	v_mfma_f32_16x16x32_bf16 v[26:29], v[160:163], v[206:209], v[26:29]
	v_mfma_f32_16x16x32_bf16 v[14:17], v[130:133], v[230:233], v[14:17]
	v_mfma_f32_16x16x32_bf16 v[10:13], v[160:163], v[230:233], v[10:13]
	v_mfma_f32_16x16x32_bf16 v[62:65], v[134:137], v[194:197], v[62:65]
	v_mfma_f32_16x16x32_bf16 v[58:61], v[164:167], v[194:197], v[58:61]
	v_mfma_f32_16x16x32_bf16 v[46:49], v[134:137], v[202:205], v[46:49]
	v_mfma_f32_16x16x32_bf16 v[42:45], v[164:167], v[202:205], v[42:45]
	v_mfma_f32_16x16x32_bf16 v[30:33], v[134:137], v[226:229], v[30:33]
	v_mfma_f32_16x16x32_bf16 v[26:29], v[164:167], v[226:229], v[26:29]
	v_mfma_f32_16x16x32_bf16 v[14:17], v[134:137], v[234:237], v[14:17]
	v_mfma_f32_16x16x32_bf16 v[10:13], v[164:167], v[234:237], v[10:13]
	v_mfma_f32_16x16x32_bf16 v[54:57], v[168:171], v[188:191], v[54:57]
	v_mfma_f32_16x16x32_bf16 v[50:53], v[180:183], v[188:191], v[50:53]
	v_mfma_f32_16x16x32_bf16 v[38:41], v[168:171], v[198:201], v[38:41]
	v_mfma_f32_16x16x32_bf16 v[34:37], v[180:183], v[198:201], v[34:37]
	v_mfma_f32_16x16x32_bf16 v[22:25], v[168:171], v[206:209], v[22:25]
	v_mfma_f32_16x16x32_bf16 v[18:21], v[180:183], v[206:209], v[18:21]
	v_mfma_f32_16x16x32_bf16 v[6:9], v[168:171], v[230:233], v[6:9]
	v_mfma_f32_16x16x32_bf16 v[2:5], v[180:183], v[230:233], v[2:5]
	v_mfma_f32_16x16x32_bf16 v[54:57], v[172:175], v[194:197], v[54:57]
	v_mfma_f32_16x16x32_bf16 v[50:53], v[184:187], v[194:197], v[50:53]
	v_mfma_f32_16x16x32_bf16 v[38:41], v[172:175], v[202:205], v[38:41]
	v_mfma_f32_16x16x32_bf16 v[34:37], v[184:187], v[202:205], v[34:37]
	v_mfma_f32_16x16x32_bf16 v[22:25], v[172:175], v[226:229], v[22:25]
	v_mfma_f32_16x16x32_bf16 v[18:21], v[184:187], v[226:229], v[18:21]
	v_mfma_f32_16x16x32_bf16 v[6:9], v[172:175], v[234:237], v[6:9]
	v_mfma_f32_16x16x32_bf16 v[2:5], v[184:187], v[234:237], v[2:5]
	s_barrier
	s_add_i32 s74, s74, 2
	s_add_u32 s34, s34, 0x100
	s_addc_u32 s35, s35, 0
	s_add_u32 s72, s72, 0x100
	s_addc_u32 s73, s73, 0
	s_cmp_gt_u32 s74, 13
	s_cbranch_scc0 .LBB0_1295
	s_and_b64 vcc, exec, s[22:23]
	s_cbranch_vccz .LBB0_1298
	s_barrier

; #define LAS __attribute__((address_space(3)))
; #define WSB(name, type, off) type* name; { GAS unsigned char* w_ = (GAS unsigned char*)P.ws; OPQ64(w_); name = (type*)(w_ + (off)); }
; __device__ __forceinline__ void sample_out_block(LAS unsigned char* lds, const bf16_t* A, const bf16_t* Bt, int K, bf16_t* xb, float* sspart, int blk, int tid) {
;     const int wave = tid >> 6, lane = tid & 63, l15 = lane & 15, g = lane >> 4;
;     const int rt = blk >> 5, cg = blk & 31, r0 = T_P + 32 * rt;
;     const int kq = K >> 3;
;     f32x4 acc[2][4];
; #pragma unroll
;     for (int ra = 0; ra < 2; ++ra)
; #pragma unroll
;         for (int nt = 0; nt < 4; ++nt) acc[ra][nt] = (f32x4){0.f, 0.f, 0.f, 0.f};
;     {
;         const bf16_t* ap = A + (size_t)(r0 + l15) * K + wave * kq + 8 * g;
;         const bf16_t* bp = Bt + (size_t)(64 * cg + l15) * K + wave * kq + 8 * g;
; __global__ void __launch_bounds__(NTHREADS, 2) hybrid_fwd(Params P) {
;     ...
;         if (PH(10)) {
;                 PHASE_IDS
;             WSB(X, float, WS_X) WSB(XB, bf16_t, WS_XB) WSB(SS, float, WS_SS) WSB(XO, bf16_t, WS_XO) WSB(Wxo, bf16_t, WS_WXO)
;             pg8::EpiRes E{XB, SS};
;             for (int blk = bid; blk < 256; blk += G) sample_out_block(lds, XO, Wxo + (size_t)l * 2048 * 512, 512, XB, SS, blk, tid);
.Lprio_4:
.LBB0_1459:
	v_readlane_b32 s6, v254, 0
	s_cmp_ge_i32 s52, s6
	s_cselect_b64 s[10:11], -1, 0
	s_and_b64 s[4:5], s[10:11], s[4:5]
	s_andn2_b64 vcc, exec, s[4:5]
	v_readlane_b32 s7, v254, 1
	s_cbranch_vccnz .LBB0_1514
	v_readlane_b32 s4, v254, 40
	v_readlane_b32 s5, v254, 41
	v_readlane_b32 s6, v254, 42
	v_readlane_b32 s7, v254, 43
	v_mov_b32_e32 v6, v139
	s_mov_b32 s25, s90
	s_mov_b64 s[4:5], s[6:7]
	s_mov_b64 s[4:5], s[6:7]
	s_add_u32 s12, s4, 0x11c00000
	s_addc_u32 s13, s5, 0
	s_mov_b64 s[4:5], s[6:7]
	s_add_u32 s14, s4, 0x13d00000
	s_addc_u32 s15, s5, 0
	s_mov_b64 s[4:5], s[6:7]
	s_add_u32 s16, s4, 0x29a68000
	s_addc_u32 s17, s5, 0
	s_mov_b64 s[4:5], s[6:7]
	s_add_u32 s22, s4, 0xc200000
	s_addc_u32 s23, s5, 0
	v_readlane_b32 s4, v254, 38
	s_lshl_b32 s24, s4, 20
	s_cmpk_gt_i32 s25, 0xff
	v_readlane_b32 s5, v254, 39
	s_cbranch_scc1 .LBB0_1472
	s_lshl_b32 s4, s24, 1
	v_and_b32_e32 v2, 0xffffffc0, v6
	s_add_u32 s4, s22, s4
	s_waitcnt lgkmcnt(0)
	v_ashrrev_i32_e32 v3, 31, v2
	s_addc_u32 s5, s23, 0
	v_lshlrev_b64 v[4:5], 1, v[2:3]
	v_lshl_add_u64 v[2:3], s[16:17], 0, v[4:5]
	v_and_b32_e32 v0, 48, v6
	v_lshl_add_u64 v[4:5], s[4:5], 0, v[4:5]
	v_lshl_add_u64 v[2:3], v[2:3], 0, v[0:1]
	v_lshl_add_u64 v[4:5], v[4:5], 0, v[0:1]
	v_lshrrev_b32_e32 v0, 2, v6
	v_and_b32_e32 v7, 63, v6
	v_ashrrev_i32_e32 v8, 6, v6
	v_and_b32_e32 v30, 15, v6
	v_and_b32_e32 v0, 12, v0
	v_lshlrev_b32_e32 v9, 13, v8
	v_lshl_add_u32 v10, v7, 4, 0
	v_lshlrev_b32_e32 v11, 12, v8
	v_lshl_or_b32 v31, v8, 4, v0
	v_lshlrev_b32_e32 v0, 1, v30
	v_cmp_gt_i32_e64 s[4:5], 2, v8
	v_lshl_add_u64 v[6:7], s[12:13], 0, v[0:1]
	v_cmp_eq_u32_e64 s[6:7], 0, v30
	v_add_u32_e32 v32, v10, v9
	v_add_u32_e32 v33, v10, v11
	s_mov_b32 s26, s25
	s_branch .LBB0_1463

; #define PG8_STAGE(bufoff, gbase, voff) do { _Pragma("unroll") for (int _i = 0; _i < 2; ++_i) \
;         __builtin_amdgcn_global_load_lds((const unsigned*)((const char*)(gbase) + (voff)[_i]), (PG8_LAS unsigned*)(lds + (bufoff) + ldsw + _i * 8192), 16, 0, 0); } while (0)
; #define PG8_LDA(dst, b, h) do { _Pragma("unroll") for (int m = 0; m < 4; ++m) _Pragma("unroll") for (int k = 0; k < 2; ++k) dst[m][k] = *(const PG8_LAS bf16x8*)(lds + PG8_SA(b, h) + aoff + m * 2048 + k * 1024); } while (0)
; #define PG8_LDB(dst, b, h) do { _Pragma("unroll") for (int n = 0; n < 2; ++n) _Pragma("unroll") for (int k = 0; k < 2; ++k) dst[n][k] = *(const PG8_LAS bf16x8*)(lds + PG8_SB(b, h) + boff + n * 2048 + k * 1024); } while (0)
; #define PG8_MMA(ai, bj, At, Bt) do { __builtin_amdgcn_s_setprio(1); _Pragma("unroll") for (int m = 0; m < 4; ++m) _Pragma("unroll") for (int n = 0; n < 2; ++n) _Pragma("unroll") for (int k = 0; k < 2; ++k) \
;         acc[ai][bj][m][n] = __builtin_amdgcn_mfma_f32_16x16x32_bf16(Bt[n][k], At[m][k], acc[ai][bj][m][n], 0, 0, 0); __builtin_amdgcn_s_setprio(0); } while (0)
; #define PG8_WAIT_V(n) asm volatile("s_waitcnt vmcnt(" #n ")" ::: "memory")
; #define PG8_WAIT_L(n) asm volatile("s_waitcnt lgkmcnt(" #n ")" ::: "memory")
; #define PG8_BAR __builtin_amdgcn_s_barrier()
; #define PG8_SCHED __builtin_amdgcn_sched_barrier(0)
; template <class Epi, class Sched, bool ALIGN_EPI = false, bool SP2 = false>
; __device__ __forceinline__ void gemm_phase(PG8_LAS unsigned char* lds, const Gemm g, const Sched& S, const Epi& E) {
;     ...
;             PG8_LDB(B0, 0, 0); PG8_LDB(B1, 0, 1); PG8_SCHED; PG8_LDA(At, 0, 0); PG8_STAGE(PG8_SA(1, 1), a1 + hstep, voffA);
;             PG8_WAIT_V(8); PG8_WAIT_L(0); PG8_BAR; PG8_MMA(0, 0, At, B0); PG8_MMA(0, 1, At, B1); PG8_BAR; PG8_SCHED;
;             PG8_LDA(At, 0, 1); PG8_STAGE(PG8_SB(0, 0), b2, voffB); PG8_STAGE(PG8_SB(0, 1), b2 + hstep, voffB); PG8_STAGE(PG8_SA(0, 0), a2, voffA);
.LBB0_1491:
	s_add_u32 s36, s34, 0x100
	s_addc_u32 s37, s35, 0
	s_add_i32 s63, 0, 0x10000
	s_cmp_eq_u32 s57, 4
	s_cselect_b32 s41, s23, s37
	s_cselect_b32 s40, s29, s36
	v_add_u32_e32 v136, s63, v192
	s_cselect_b32 s39, s21, s56
	s_cselect_b32 s38, s31, s55
	s_add_i32 s68, 0, 0x14000
	ds_read_b128 v[146:149], v136
	ds_read_b128 v[150:153], v136 offset:1024
	ds_read_b128 v[154:157], v136 offset:2048
	ds_read_b128 v[158:161], v136 offset:3072
	v_add_u32_e32 v136, s68, v192
	ds_read_b128 v[162:165], v136
	ds_read_b128 v[166:169], v136 offset:1024
	ds_read_b128 v[170:173], v136 offset:2048
	ds_read_b128 v[174:177], v136 offset:3072
	v_lshl_add_u64 v[136:137], s[34:35], 0, v[132:133]
	s_add_i32 m0, s46, 0xc000
	ds_read_b128 v[178:181], v194
	ds_read_b128 v[182:185], v194 offset:1024
	ds_read_b128 v[186:189], v194 offset:2048
	ds_read_b128 v[196:199], v194 offset:3072
	ds_read_b128 v[200:203], v194 offset:4096
	ds_read_b128 v[204:207], v194 offset:5120
	ds_read_b128 v[226:229], v194 offset:6144
	ds_read_b128 v[230:233], v194 offset:7168
	global_load_lds_dwordx4 v[136:137], off
	v_lshl_add_u64 v[136:137], s[34:35], 0, v[134:135]
	s_add_i32 m0, s46, 0xe000
	s_nop 0
	global_load_lds_dwordx4 v[136:137], off
	s_waitcnt vmcnt(8)
	s_waitcnt lgkmcnt(0)
	s_barrier
	s_waitcnt lgkmcnt(0)
	v_mfma_f32_16x16x32_bf16 v[126:129], v[146:149], v[178:181], v[126:129]
	v_mfma_f32_16x16x32_bf16 v[122:125], v[154:157], v[178:181], v[122:125]
	v_mfma_f32_16x16x32_bf16 v[110:113], v[146:149], v[186:189], v[110:113]
	v_mfma_f32_16x16x32_bf16 v[106:109], v[154:157], v[186:189], v[106:109]
	v_mfma_f32_16x16x32_bf16 v[94:97], v[146:149], v[200:203], v[94:97]
	v_mfma_f32_16x16x32_bf16 v[90:93], v[154:157], v[200:203], v[90:93]
	v_mfma_f32_16x16x32_bf16 v[78:81], v[146:149], v[226:229], v[78:81]
	v_mfma_f32_16x16x32_bf16 v[74:77], v[154:157], v[226:229], v[74:77]
	v_mfma_f32_16x16x32_bf16 v[126:129], v[150:153], v[182:185], v[126:129]
	v_mfma_f32_16x16x32_bf16 v[122:125], v[158:161], v[182:185], v[122:125]
	v_mfma_f32_16x16x32_bf16 v[110:113], v[150:153], v[196:199], v[110:113]
	v_mfma_f32_16x16x32_bf16 v[106:109], v[158:161], v[196:199], v[106:109]
	v_mfma_f32_16x16x32_bf16 v[94:97], v[150:153], v[204:207], v[94:97]
	v_mfma_f32_16x16x32_bf16 v[90:93], v[158:161], v[204:207], v[90:93]
	v_mfma_f32_16x16x32_bf16 v[78:81], v[150:153], v[230:233], v[78:81]
	v_mfma_f32_16x16x32_bf16 v[74:77], v[158:161], v[230:233], v[74:77]
	v_mfma_f32_16x16x32_bf16 v[118:121], v[162:165], v[178:181], v[118:121]
	v_mfma_f32_16x16x32_bf16 v[114:117], v[170:173], v[178:181], v[114:117]
	v_mfma_f32_16x16x32_bf16 v[102:105], v[162:165], v[186:189], v[102:105]
	v_mfma_f32_16x16x32_bf16 v[98:101], v[170:173], v[186:189], v[98:101]
	v_mfma_f32_16x16x32_bf16 v[86:89], v[162:165], v[200:203], v[86:89]
	v_mfma_f32_16x16x32_bf16 v[82:85], v[170:173], v[200:203], v[82:85]
	v_mfma_f32_16x16x32_bf16 v[70:73], v[162:165], v[226:229], v[70:73]
	v_mfma_f32_16x16x32_bf16 v[66:69], v[170:173], v[226:229], v[66:69]
	v_mfma_f32_16x16x32_bf16 v[118:121], v[166:169], v[182:185], v[118:121]
	v_mfma_f32_16x16x32_bf16 v[114:117], v[174:177], v[182:185], v[114:117]
	v_mfma_f32_16x16x32_bf16 v[102:105], v[166:169], v[196:199], v[102:105]
	v_mfma_f32_16x16x32_bf16 v[98:101], v[174:177], v[196:199], v[98:101]
	v_mfma_f32_16x16x32_bf16 v[86:89], v[166:169], v[204:207], v[86:89]
	v_mfma_f32_16x16x32_bf16 v[82:85], v[174:177], v[204:207], v[82:85]
	v_mfma_f32_16x16x32_bf16 v[70:73], v[166:169], v[230:233], v[70:73]
	v_mfma_f32_16x16x32_bf16 v[66:69], v[174:177], v[230:233], v[66:69]
	s_barrier
	s_add_i32 s34, s63, s45
	v_lshl_add_u64 v[136:137], s[38:39], 0, v[0:1]
	s_mov_b32 m0, s34
	ds_read_b128 v[178:181], v194 offset:16384
	ds_read_b128 v[182:185], v194 offset:17408
	ds_read_b128 v[186:189], v194 offset:18432
	ds_read_b128 v[196:199], v194 offset:19456
	ds_read_b128 v[200:203], v194 offset:20480
	ds_read_b128 v[204:207], v194 offset:21504
	ds_read_b128 v[226:229], v194 offset:22528
	ds_read_b128 v[230:233], v194 offset:23552
	global_load_lds_dwordx4 v[136:137], off
	s_add_i32 m0, s34, 0x2000
	s_add_u32 s34, s38, 0x20000
	v_lshl_add_u64 v[190:191], s[38:39], 0, v[130:131]
	s_addc_u32 s35, s39, 0
	s_add_i32 s63, s68, s45
	global_load_lds_dwordx4 v[190:191], off
	v_lshl_add_u64 v[208:209], s[34:35], 0, v[0:1]
	s_mov_b32 m0, s63
	v_lshl_add_u64 v[234:235], s[40:41], 0, v[130:131]
	global_load_lds_dwordx4 v[208:209], off
	v_lshl_add_u64 v[208:209], s[34:35], 0, v[130:131]
	s_add_i32 m0, s63, 0x2000
	s_nop 0
	global_load_lds_dwordx4 v[208:209], off
	v_lshl_add_u64 v[208:209], s[40:41], 0, v[0:1]
	s_mov_b32 m0, s46
	s_nop 0
	global_load_lds_dwordx4 v[208:209], off
	s_mov_b32 m0, s47
	s_nop 0
	global_load_lds_dwordx4 v[234:235], off
	s_waitcnt vmcnt(8)
	s_waitcnt lgkmcnt(0)
	s_barrier
; #define PG8_STAGE(bufoff, gbase, voff) do { _Pragma("unroll") for (int _i = 0; _i < 2; ++_i) \
;         __builtin_amdgcn_global_load_lds((const unsigned*)((const char*)(gbase) + (voff)[_i]), (PG8_LAS unsigned*)(lds + (bufoff) + ldsw + _i * 8192), 16, 0, 0); } while (0)
; #define PG8_LDA(dst, b, h) do { _Pragma("unroll") for (int m = 0; m < 4; ++m) _Pragma("unroll") for (int k = 0; k < 2; ++k) dst[m][k] = *(const PG8_LAS bf16x8*)(lds + PG8_SA(b, h) + aoff + m * 2048 + k * 1024); } while (0)
; #define PG8_LDB(dst, b, h) do { _Pragma("unroll") for (int n = 0; n < 2; ++n) _Pragma("unroll") for (int k = 0; k < 2; ++k) dst[n][k] = *(const PG8_LAS bf16x8*)(lds + PG8_SB(b, h) + boff + n * 2048 + k * 1024); } while (0)
; #define PG8_MMA(ai, bj, At, Bt) do { __builtin_amdgcn_s_setprio(1); _Pragma("unroll") for (int m = 0; m < 4; ++m) _Pragma("unroll") for (int n = 0; n < 2; ++n) _Pragma("unroll") for (int k = 0; k < 2; ++k) \
;         acc[ai][bj][m][n] = __builtin_amdgcn_mfma_f32_16x16x32_bf16(Bt[n][k], At[m][k], acc[ai][bj][m][n], 0, 0, 0); __builtin_amdgcn_s_setprio(0); } while (0)
; #define PG8_WAIT_V(n) asm volatile("s_waitcnt vmcnt(" #n ")" ::: "memory")
; #define PG8_WAIT_L(n) asm volatile("s_waitcnt lgkmcnt(" #n ")" ::: "memory")
; #define PG8_BAR __builtin_amdgcn_s_barrier()
; #define PG8_SCHED __builtin_amdgcn_sched_barrier(0)
; template <class Epi, class Sched, bool ALIGN_EPI = false, bool SP2 = false>
; __device__ __forceinline__ void gemm_phase(PG8_LAS unsigned char* lds, const Gemm g, const Sched& S, const Epi& E) {
;     ...
;             PG8_WAIT_V(8); PG8_WAIT_L(0); PG8_BAR; PG8_MMA(1, 0, At, B0); PG8_MMA(1, 1, At, B1); PG8_BAR; PG8_SCHED;
;             PG8_LDB(B0, 1, 0); PG8_LDB(B1, 1, 1); PG8_SCHED; PG8_LDA(At, 1, 0); PG8_STAGE(PG8_SA(0, 1), a2 + hstep, voffA);
;             PG8_WAIT_V(8); PG8_WAIT_L(0); PG8_BAR; PG8_MMA(0, 0, At, B0); PG8_MMA(0, 1, At, B1); PG8_BAR; PG8_SCHED;
	s_waitcnt lgkmcnt(0)
	v_mfma_f32_16x16x32_bf16 v[62:65], v[146:149], v[178:181], v[62:65]
	v_mfma_f32_16x16x32_bf16 v[58:61], v[154:157], v[178:181], v[58:61]
	v_mfma_f32_16x16x32_bf16 v[46:49], v[146:149], v[186:189], v[46:49]
	v_mfma_f32_16x16x32_bf16 v[42:45], v[154:157], v[186:189], v[42:45]
	v_mfma_f32_16x16x32_bf16 v[30:33], v[146:149], v[200:203], v[30:33]
	v_mfma_f32_16x16x32_bf16 v[26:29], v[154:157], v[200:203], v[26:29]
	v_mfma_f32_16x16x32_bf16 v[14:17], v[146:149], v[226:229], v[14:17]
	v_mfma_f32_16x16x32_bf16 v[10:13], v[154:157], v[226:229], v[10:13]
	v_mfma_f32_16x16x32_bf16 v[62:65], v[150:153], v[182:185], v[62:65]
	v_mfma_f32_16x16x32_bf16 v[58:61], v[158:161], v[182:185], v[58:61]
	v_mfma_f32_16x16x32_bf16 v[46:49], v[150:153], v[196:199], v[46:49]
	v_mfma_f32_16x16x32_bf16 v[42:45], v[158:161], v[196:199], v[42:45]
	v_mfma_f32_16x16x32_bf16 v[30:33], v[150:153], v[204:207], v[30:33]
	v_mfma_f32_16x16x32_bf16 v[26:29], v[158:161], v[204:207], v[26:29]
	v_mfma_f32_16x16x32_bf16 v[14:17], v[150:153], v[230:233], v[14:17]
	v_mfma_f32_16x16x32_bf16 v[10:13], v[158:161], v[230:233], v[10:13]
	v_mfma_f32_16x16x32_bf16 v[54:57], v[162:165], v[178:181], v[54:57]
	v_mfma_f32_16x16x32_bf16 v[50:53], v[170:173], v[178:181], v[50:53]
	v_mfma_f32_16x16x32_bf16 v[38:41], v[162:165], v[186:189], v[38:41]
	v_mfma_f32_16x16x32_bf16 v[34:37], v[170:173], v[186:189], v[34:37]
	v_mfma_f32_16x16x32_bf16 v[22:25], v[162:165], v[200:203], v[22:25]
	v_mfma_f32_16x16x32_bf16 v[18:21], v[170:173], v[200:203], v[18:21]
	v_mfma_f32_16x16x32_bf16 v[6:9], v[162:165], v[226:229], v[6:9]
	v_mfma_f32_16x16x32_bf16 v[2:5], v[170:173], v[226:229], v[2:5]
	v_mfma_f32_16x16x32_bf16 v[54:57], v[166:169], v[182:185], v[54:57]
	v_mfma_f32_16x16x32_bf16 v[50:53], v[174:177], v[182:185], v[50:53]
	v_mfma_f32_16x16x32_bf16 v[38:41], v[166:169], v[196:199], v[38:41]
	v_mfma_f32_16x16x32_bf16 v[34:37], v[174:177], v[196:199], v[34:37]
	v_mfma_f32_16x16x32_bf16 v[22:25], v[166:169], v[204:207], v[22:25]
	v_mfma_f32_16x16x32_bf16 v[18:21], v[174:177], v[204:207], v[18:21]
	v_mfma_f32_16x16x32_bf16 v[6:9], v[166:169], v[230:233], v[6:9]
	v_mfma_f32_16x16x32_bf16 v[2:5], v[174:177], v[230:233], v[2:5]
	s_barrier
	s_add_i32 s63, 0, 0x18000
	s_add_i32 s68, 0, 0x1c000
	v_add_u32_e32 v158, s63, v192
	v_add_u32_e32 v174, s68, v192
	ds_read_b128 v[146:149], v158
	ds_read_b128 v[150:153], v158 offset:1024
	ds_read_b128 v[154:157], v158 offset:2048
	ds_read_b128 v[158:161], v158 offset:3072
	ds_read_b128 v[162:165], v174
	ds_read_b128 v[166:169], v174 offset:1024
	ds_read_b128 v[170:173], v174 offset:2048
	ds_read_b128 v[174:177], v174 offset:3072
	s_add_u32 s34, s40, 0x20000
	s_addc_u32 s35, s41, 0
	s_mov_b32 m0, s48
	v_lshl_add_u64 v[236:237], s[34:35], 0, v[0:1]
	ds_read_b128 v[178:181], v194 offset:32768
	ds_read_b128 v[182:185], v194 offset:33792
	ds_read_b128 v[186:189], v194 offset:34816
	ds_read_b128 v[196:199], v194 offset:35840
	ds_read_b128 v[200:203], v194 offset:36864
	ds_read_b128 v[204:207], v194 offset:37888
	ds_read_b128 v[226:229], v194 offset:38912
	ds_read_b128 v[230:233], v194 offset:39936
	global_load_lds_dwordx4 v[236:237], off
	v_lshl_add_u64 v[236:237], s[34:35], 0, v[130:131]
	s_mov_b32 m0, s49
	s_nop 0
	global_load_lds_dwordx4 v[236:237], off
	s_waitcnt vmcnt(8)
	s_waitcnt lgkmcnt(0)
	s_barrier
	s_waitcnt lgkmcnt(0)
	v_mfma_f32_16x16x32_bf16 v[126:129], v[146:149], v[178:181], v[126:129]
	v_mfma_f32_16x16x32_bf16 v[122:125], v[154:157], v[178:181], v[122:125]
	v_mfma_f32_16x16x32_bf16 v[110:113], v[146:149], v[186:189], v[110:113]
	v_mfma_f32_16x16x32_bf16 v[106:109], v[154:157], v[186:189], v[106:109]
	v_mfma_f32_16x16x32_bf16 v[94:97], v[146:149], v[200:203], v[94:97]
	v_mfma_f32_16x16x32_bf16 v[90:93], v[154:157], v[200:203], v[90:93]
	v_mfma_f32_16x16x32_bf16 v[78:81], v[146:149], v[226:229], v[78:81]
	v_mfma_f32_16x16x32_bf16 v[74:77], v[154:157], v[226:229], v[74:77]
	v_mfma_f32_16x16x32_bf16 v[126:129], v[150:153], v[182:185], v[126:129]
	v_mfma_f32_16x16x32_bf16 v[122:125], v[158:161], v[182:185], v[122:125]
	v_mfma_f32_16x16x32_bf16 v[110:113], v[150:153], v[196:199], v[110:113]
	v_mfma_f32_16x16x32_bf16 v[106:109], v[158:161], v[196:199], v[106:109]
	v_mfma_f32_16x16x32_bf16 v[94:97], v[150:153], v[204:207], v[94:97]
	v_mfma_f32_16x16x32_bf16 v[90:93], v[158:161], v[204:207], v[90:93]
	v_mfma_f32_16x16x32_bf16 v[78:81], v[150:153], v[230:233], v[78:81]
	v_mfma_f32_16x16x32_bf16 v[74:77], v[158:161], v[230:233], v[74:77]
	v_mfma_f32_16x16x32_bf16 v[118:121], v[162:165], v[178:181], v[118:121]
	v_mfma_f32_16x16x32_bf16 v[114:117], v[170:173], v[178:181], v[114:117]
	v_mfma_f32_16x16x32_bf16 v[102:105], v[162:165], v[186:189], v[102:105]
	v_mfma_f32_16x16x32_bf16 v[98:101], v[170:173], v[186:189], v[98:101]
	v_mfma_f32_16x16x32_bf16 v[86:89], v[162:165], v[200:203], v[86:89]
	v_mfma_f32_16x16x32_bf16 v[82:85], v[170:173], v[200:203], v[82:85]
	v_mfma_f32_16x16x32_bf16 v[70:73], v[162:165], v[226:229], v[70:73]
	v_mfma_f32_16x16x32_bf16 v[66:69], v[170:173], v[226:229], v[66:69]
	v_mfma_f32_16x16x32_bf16 v[118:121], v[166:169], v[182:185], v[118:121]
	v_mfma_f32_16x16x32_bf16 v[114:117], v[174:177], v[182:185], v[114:117]
	v_mfma_f32_16x16x32_bf16 v[102:105], v[166:169], v[196:199], v[102:105]
	v_mfma_f32_16x16x32_bf16 v[98:101], v[174:177], v[196:199], v[98:101]
	v_mfma_f32_16x16x32_bf16 v[86:89], v[166:169], v[204:207], v[86:89]
	v_mfma_f32_16x16x32_bf16 v[82:85], v[174:177], v[204:207], v[82:85]
	v_mfma_f32_16x16x32_bf16 v[70:73], v[166:169], v[230:233], v[70:73]
	v_mfma_f32_16x16x32_bf16 v[66:69], v[174:177], v[230:233], v[66:69]
	s_barrier
; #define PG8_STAGE(bufoff, gbase, voff) do { _Pragma("unroll") for (int _i = 0; _i < 2; ++_i) \
;         __builtin_amdgcn_global_load_lds((const unsigned*)((const char*)(gbase) + (voff)[_i]), (PG8_LAS unsigned*)(lds + (bufoff) + ldsw + _i * 8192), 16, 0, 0); } while (0)
; #define PG8_LDA(dst, b, h) do { _Pragma("unroll") for (int m = 0; m < 4; ++m) _Pragma("unroll") for (int k = 0; k < 2; ++k) dst[m][k] = *(const PG8_LAS bf16x8*)(lds + PG8_SA(b, h) + aoff + m * 2048 + k * 1024); } while (0)
; #define PG8_MMA(ai, bj, At, Bt) do { __builtin_amdgcn_s_setprio(1); _Pragma("unroll") for (int m = 0; m < 4; ++m) _Pragma("unroll") for (int n = 0; n < 2; ++n) _Pragma("unroll") for (int k = 0; k < 2; ++k) \
;         acc[ai][bj][m][n] = __builtin_amdgcn_mfma_f32_16x16x32_bf16(Bt[n][k], At[m][k], acc[ai][bj][m][n], 0, 0, 0); __builtin_amdgcn_s_setprio(0); } while (0)
; #define PG8_WAIT_V(n) asm volatile("s_waitcnt vmcnt(" #n ")" ::: "memory")
; #define PG8_WAIT_L(n) asm volatile("s_waitcnt lgkmcnt(" #n ")" ::: "memory")
; #define PG8_BAR __builtin_amdgcn_s_barrier()
; #define PG8_SCHED __builtin_amdgcn_sched_barrier(0)
; template <class Epi, class Sched, bool ALIGN_EPI = false, bool SP2 = false>
; __device__ __forceinline__ void gemm_phase(PG8_LAS unsigned char* lds, const Gemm g, const Sched& S, const Epi& E) {
;     ...
;             PG8_LDA(At, 1, 1); PG8_STAGE(PG8_SB(1, 0), b3, voffB); PG8_STAGE(PG8_SB(1, 1), b3 + hstep, voffB); PG8_STAGE(PG8_SA(1, 0), a3, voffA);
;             PG8_WAIT_V(8); PG8_WAIT_L(0); PG8_BAR; PG8_MMA(1, 0, At, B0); PG8_MMA(1, 1, At, B1); PG8_BAR; PG8_SCHED;
	s_add_i32 s34, s63, s45
	v_lshl_add_u64 v[136:137], v[136:137], 0, s[0:1]
	s_mov_b32 m0, s34
	ds_read_b128 v[178:181], v194 offset:49152
	ds_read_b128 v[182:185], v194 offset:50176
	ds_read_b128 v[186:189], v194 offset:51200
	ds_read_b128 v[196:199], v194 offset:52224
	ds_read_b128 v[200:203], v194 offset:53248
	ds_read_b128 v[204:207], v194 offset:54272
	ds_read_b128 v[226:229], v194 offset:55296
	ds_read_b128 v[230:233], v194 offset:56320
	global_load_lds_dwordx4 v[136:137], off
	s_add_i32 m0, s34, 0x2000
	s_add_u32 s34, s38, 0x20080
	v_lshl_add_u64 v[136:137], v[190:191], 0, s[0:1]
	s_addc_u32 s35, s39, 0
	s_add_i32 s38, s68, s45
	global_load_lds_dwordx4 v[136:137], off
	v_lshl_add_u64 v[136:137], s[34:35], 0, v[0:1]
	s_mov_b32 m0, s38
	s_nop 0
	global_load_lds_dwordx4 v[136:137], off
	v_lshl_add_u64 v[136:137], s[34:35], 0, v[130:131]
	s_add_i32 m0, s38, 0x2000
	s_nop 0
	global_load_lds_dwordx4 v[136:137], off
	v_lshl_add_u64 v[136:137], v[208:209], 0, s[0:1]
	s_mov_b32 m0, s51
	s_nop 0
	global_load_lds_dwordx4 v[136:137], off
	v_lshl_add_u64 v[136:137], v[234:235], 0, s[0:1]
	s_mov_b32 m0, s52
	s_nop 0
	global_load_lds_dwordx4 v[136:137], off
	s_waitcnt vmcnt(8)
	s_waitcnt lgkmcnt(0)
	s_barrier
	s_waitcnt lgkmcnt(0)
	v_mfma_f32_16x16x32_bf16 v[62:65], v[146:149], v[178:181], v[62:65]
	v_mfma_f32_16x16x32_bf16 v[58:61], v[154:157], v[178:181], v[58:61]
	v_mfma_f32_16x16x32_bf16 v[46:49], v[146:149], v[186:189], v[46:49]
	v_mfma_f32_16x16x32_bf16 v[42:45], v[154:157], v[186:189], v[42:45]
	v_mfma_f32_16x16x32_bf16 v[30:33], v[146:149], v[200:203], v[30:33]
	v_mfma_f32_16x16x32_bf16 v[26:29], v[154:157], v[200:203], v[26:29]
	v_mfma_f32_16x16x32_bf16 v[14:17], v[146:149], v[226:229], v[14:17]
	v_mfma_f32_16x16x32_bf16 v[10:13], v[154:157], v[226:229], v[10:13]
	v_mfma_f32_16x16x32_bf16 v[62:65], v[150:153], v[182:185], v[62:65]
	v_mfma_f32_16x16x32_bf16 v[58:61], v[158:161], v[182:185], v[58:61]
	v_mfma_f32_16x16x32_bf16 v[46:49], v[150:153], v[196:199], v[46:49]
	v_mfma_f32_16x16x32_bf16 v[42:45], v[158:161], v[196:199], v[42:45]
	v_mfma_f32_16x16x32_bf16 v[30:33], v[150:153], v[204:207], v[30:33]
	v_mfma_f32_16x16x32_bf16 v[26:29], v[158:161], v[204:207], v[26:29]
	v_mfma_f32_16x16x32_bf16 v[14:17], v[150:153], v[230:233], v[14:17]
	v_mfma_f32_16x16x32_bf16 v[10:13], v[158:161], v[230:233], v[10:13]
	v_mfma_f32_16x16x32_bf16 v[54:57], v[162:165], v[178:181], v[54:57]
	v_mfma_f32_16x16x32_bf16 v[50:53], v[170:173], v[178:181], v[50:53]
	v_mfma_f32_16x16x32_bf16 v[38:41], v[162:165], v[186:189], v[38:41]
	v_mfma_f32_16x16x32_bf16 v[34:37], v[170:173], v[186:189], v[34:37]
	v_mfma_f32_16x16x32_bf16 v[22:25], v[162:165], v[200:203], v[22:25]
	v_mfma_f32_16x16x32_bf16 v[18:21], v[170:173], v[200:203], v[18:21]
	v_mfma_f32_16x16x32_bf16 v[6:9], v[162:165], v[226:229], v[6:9]
	v_mfma_f32_16x16x32_bf16 v[2:5], v[170:173], v[226:229], v[2:5]
	v_mfma_f32_16x16x32_bf16 v[54:57], v[166:169], v[182:185], v[54:57]
	v_mfma_f32_16x16x32_bf16 v[50:53], v[174:177], v[182:185], v[50:53]
	v_mfma_f32_16x16x32_bf16 v[38:41], v[166:169], v[196:199], v[38:41]
	v_mfma_f32_16x16x32_bf16 v[34:37], v[174:177], v[196:199], v[34:37]
	v_mfma_f32_16x16x32_bf16 v[22:25], v[166:169], v[204:207], v[22:25]
	v_mfma_f32_16x16x32_bf16 v[18:21], v[174:177], v[204:207], v[18:21]
	v_mfma_f32_16x16x32_bf16 v[6:9], v[166:169], v[230:233], v[6:9]
	v_mfma_f32_16x16x32_bf16 v[2:5], v[174:177], v[230:233], v[2:5]
	s_barrier
	s_add_i32 s57, s57, 2
	s_add_u32 s55, s55, 0x100
	s_addc_u32 s56, s56, 0
	s_cmp_gt_u32 s57, 5
	s_mov_b64 s[34:35], s[36:37]
	s_cbranch_scc0 .LBB0_1491
	s_and_b64 vcc, exec, s[18:19]
	s_cbranch_vccz .LBB0_1494
	s_barrier
